# gl1 (GLA chunk summaries) forget-gate projection: token rows held replicated per 16-lane row and broadcast by DPP row_newbcast inside v_dot2c instead of 8 v_readlane per token
# speedup vs baseline: 1.0073x; 1.0073x over previous
; __device__ __forceinline__ unsigned pk2(float lo, float hi) { unsigned r; asm("v_cvt_pk_bf16_f32 %0, %1, %2" : "=v"(r) : "v"(lo), "v"(hi)); return r; }
; __device__ __forceinline__ void gl1_item(PREF p, int l, int item, bool valid, LAS unsigned char* pl, int sw, int lane) {
;     ...
;     if (valid) {
;         const bf16_t* prl = P + (size_t)(row0 + lane * rstride) * PW + 2560 + d * 16;
;         const u32x4 lra = *(const u32x4*)prl, lrb = *(const u32x4*)(prl + 8);
;         unsigned lrp[8] = {lra.x, lra.y, lra.z, lra.w, lrb.x, lrb.y, lrb.z, lrb.w};
;         float qc[16], kc[16];
; #pragma unroll
;         for (int ss = 0; ss < 16; ++ss) { const int i = d ? 63 - ss : ss; const bf16_t* pr = P + (size_t)(row0 + i * rstride) * PW + h * 64 + lane;
;             qc[ss] = __builtin_bit_cast(float, (unsigned)pr[1024]); kc[ss] = __builtin_bit_cast(float, (unsigned)pr[1280]); }
;         __builtin_amdgcn_sched_barrier(0);
; #pragma unroll
;         for (int ss = 0; ss < 16; ++ss) { qc[ss] = bf2f(__builtin_bit_cast(unsigned, qc[ss])); kc[ss] = bf2f(__builtin_bit_cast(unsigned, kc[ss])); }
;         unsigned wupp[8];
; #pragma unroll
;         for (int r2 = 0; r2 < 8; ++r2) wupp[r2] = pk2(p.gla_wup[(size_t)((l * 2 + d) * 16 + 2 * r2) * 256 + h * 64 + lane], p.gla_wup[(size_t)((l * 2 + d) * 16 + 2 * r2 + 1) * 256 + h * 64 + lane]);
;         const float bup = p.gla_bup[(l * 2 + d) * 256 + h * 64 + lane];
; #pragma unroll 1
;         for (int g2 = 0; g2 < 2; ++g2) {
;             unsigned vr[16];
; #pragma unroll
;             for (int ii = 0; ii < 16; ++ii) { const int i = 32 * sw + g2 * 16 + ii; vr[ii] = *(const unsigned*)(P + (size_t)(row0 + i * rstride) * PW + 1536 + h * 128 + 2 * lane); }
.LBB0_188:
	s_cmpk_lt_i32 s0, 0x820
	s_cselect_b64 s[12:13], -1, 0
	s_and_b64 s[4:5], s[4:5], exec
	s_cselect_b32 s41, s3, s1
	s_cselect_b32 s1, s30, s2
	s_lshl_b32 s42, s1, 3
	s_cmpk_gt_i32 s0, 0x81f
	s_cbranch_scc1 .LBB0_199
	v_readlane_b32 s52, v253, 55
	v_readlane_b32 s53, v253, 56
	s_and_b32 s1, s0, 3
	s_nop 3
	s_load_dwordx2 s[2:3], s[52:53], 0xc0
	s_load_dwordx4 s[4:7], s[52:53], 0x90
	v_readlane_b32 s30, v254, 5
	v_readlane_b32 s45, v254, 11
	s_and_b32 s46, s38, 1
	v_lshlrev_b32_e32 v134, 1, v64
	v_lshlrev_b32_e32 v135, 2, v64
	s_lshr_b32 s47, s45, 7
	s_mul_i32 s47, s47, 0x9200
	s_lshl_b32 s48, s30, 1
	s_add_i32 s48, s48, s46
	s_waitcnt lgkmcnt(0)
	v_and_b32_e32 v87, 15, v64
	s_mul_i32 s50, s46, 63
	s_lshl_b32 s51, s46, 1
	s_sub_i32 s51, 1, s51
	v_mul_lo_u32 v87, v87, s51
	v_add_u32_e32 v87, s50, v87
	s_mul_i32 s51, s51, s44
	s_mul_i32 s51, s51, 0x16000
	v_mul_lo_u32 v86, v87, s44
	v_add_u32_e32 v86, s43, v86
	s_mov_b32 s49, 0x1600
	s_lshl_b32 s50, s46, 5
	s_add_i32 s50, s50, 0x1400
	s_add_u32 s52, s2, 0xbc00000
	s_addc_u32 s53, s3, 0
	v_mul_lo_u32 v88, v86, s49
	v_add_u32_e32 v88, s50, v88
	global_load_dwordx4 v[0:3], v88, s[52:53]
	global_load_dwordx4 v[4:7], v88, s[52:53] offset:16
	v_add_u32_e32 v88, s51, v88
	global_load_dwordx4 v[106:109], v88, s[52:53]
	global_load_dwordx4 v[110:113], v88, s[52:53] offset:16
	v_add_u32_e32 v88, s51, v88
	global_load_dwordx4 v[114:117], v88, s[52:53]
	global_load_dwordx4 v[118:121], v88, s[52:53] offset:16
	v_add_u32_e32 v88, s51, v88
	global_load_dwordx4 v[122:125], v88, s[52:53]
	global_load_dwordx4 v[126:129], v88, s[52:53] offset:16
	s_lshl_b32 s50, s48, 14
	s_lshl_b32 s51, s1, 8
	s_add_i32 s50, s50, s51
	s_add_u32 s4, s4, s50
	s_addc_u32 s5, s5, 0
	global_load_dword v90, v135, s[4:5]
	global_load_dword v91, v135, s[4:5] offset:1024
	global_load_dword v92, v135, s[4:5] offset:2048
	global_load_dword v93, v135, s[4:5] offset:3072
	s_add_u32 s4, s4, 0x1000
	s_addc_u32 s5, s5, 0
	global_load_dword v94, v135, s[4:5]
	global_load_dword v95, v135, s[4:5] offset:1024
	global_load_dword v96, v135, s[4:5] offset:2048
	global_load_dword v97, v135, s[4:5] offset:3072
	s_add_u32 s4, s4, 0x1000
	s_addc_u32 s5, s5, 0
	global_load_dword v98, v135, s[4:5]
	global_load_dword v99, v135, s[4:5] offset:1024
	global_load_dword v100, v135, s[4:5] offset:2048
	global_load_dword v101, v135, s[4:5] offset:3072
	s_add_u32 s4, s4, 0x1000
	s_addc_u32 s5, s5, 0
	global_load_dword v102, v135, s[4:5]
	global_load_dword v103, v135, s[4:5] offset:1024
	global_load_dword v104, v135, s[4:5] offset:2048
	global_load_dword v105, v135, s[4:5] offset:3072
	s_lshl_b32 s50, s48, 10
	s_add_i32 s50, s50, s51
	s_add_u32 s6, s6, s50
	s_addc_u32 s7, s7, 0
	global_load_dword v16, v135, s[6:7]
	s_mul_i32 s54, s44, 0x1600
	s_lshl_b32 s50, s46, 5
	s_mul_i32 s50, s50, s44
	s_add_i32 s50, s50, s43
	s_mul_hi_u32 s7, s50, 0x1600
	s_mul_i32 s6, s50, 0x1600
	s_add_u32 s6, s6, s52
	s_addc_u32 s7, s7, s53
	s_add_i32 s51, s51, 0xc00
	s_add_u32 s6, s6, s51
	s_addc_u32 s7, s7, 0
	global_load_dword v34, v135, s[6:7]
	s_add_u32 s6, s6, s54
	s_addc_u32 s7, s7, 0
	global_load_dword v35, v135, s[6:7]
	s_add_u32 s6, s6, s54
	s_addc_u32 s7, s7, 0
	global_load_dword v36, v135, s[6:7]
	s_add_u32 s6, s6, s54
	s_addc_u32 s7, s7, 0
	global_load_dword v37, v135, s[6:7]
	s_add_u32 s6, s6, s54
	s_addc_u32 s7, s7, 0
	global_load_dword v38, v135, s[6:7]
	s_add_u32 s6, s6, s54
	s_addc_u32 s7, s7, 0
	global_load_dword v39, v135, s[6:7]
	s_add_u32 s6, s6, s54
	s_addc_u32 s7, s7, 0
	global_load_dword v40, v135, s[6:7]
	s_add_u32 s6, s6, s54
	s_addc_u32 s7, s7, 0
	global_load_dword v41, v135, s[6:7]
	s_add_u32 s6, s6, s54
	s_addc_u32 s7, s7, 0
	global_load_dword v42, v135, s[6:7]
	s_add_u32 s6, s6, s54
	s_addc_u32 s7, s7, 0
	global_load_dword v43, v135, s[6:7]
	s_add_u32 s6, s6, s54
	s_addc_u32 s7, s7, 0
	global_load_dword v44, v135, s[6:7]
	s_add_u32 s6, s6, s54
	s_addc_u32 s7, s7, 0
	global_load_dword v45, v135, s[6:7]
	s_add_u32 s6, s6, s54
	s_addc_u32 s7, s7, 0
	global_load_dword v46, v135, s[6:7]
	s_add_u32 s6, s6, s54
	s_addc_u32 s7, s7, 0
	global_load_dword v47, v135, s[6:7]
	s_add_u32 s6, s6, s54
	s_addc_u32 s7, s7, 0
	global_load_dword v212, v135, s[6:7]
	s_add_u32 s6, s6, s54
	s_addc_u32 s7, s7, 0
	global_load_dword v213, v135, s[6:7]
	s_add_u32 s6, s6, s54
	s_addc_u32 s7, s7, 0
	global_load_dword v214, v135, s[6:7]
	s_add_u32 s6, s6, s54
	s_addc_u32 s7, s7, 0
	global_load_dword v215, v135, s[6:7]
	s_add_u32 s6, s6, s54
	s_addc_u32 s7, s7, 0
	global_load_dword v216, v135, s[6:7]
	s_add_u32 s6, s6, s54
	s_addc_u32 s7, s7, 0
	global_load_dword v217, v135, s[6:7]
	s_add_u32 s6, s6, s54
	s_addc_u32 s7, s7, 0
	global_load_dword v218, v135, s[6:7]
	s_add_u32 s6, s6, s54
	s_addc_u32 s7, s7, 0
	global_load_dword v219, v135, s[6:7]
	s_add_u32 s6, s6, s54
	s_addc_u32 s7, s7, 0
	global_load_dword v222, v135, s[6:7]
	s_add_u32 s6, s6, s54
	s_addc_u32 s7, s7, 0
	global_load_dword v223, v135, s[6:7]
	s_add_u32 s6, s6, s54
	s_addc_u32 s7, s7, 0
	global_load_dword v228, v135, s[6:7]
	s_add_u32 s6, s6, s54
	s_addc_u32 s7, s7, 0
	global_load_dword v229, v135, s[6:7]
	s_add_u32 s6, s6, s54
	s_addc_u32 s7, s7, 0
	global_load_dword v230, v135, s[6:7]
	s_add_u32 s6, s6, s54
	s_addc_u32 s7, s7, 0
	global_load_dword v231, v135, s[6:7]
	s_add_u32 s6, s6, s54
	s_addc_u32 s7, s7, 0
	global_load_dword v232, v135, s[6:7]
	s_add_u32 s6, s6, s54
	s_addc_u32 s7, s7, 0
	global_load_dword v233, v135, s[6:7]
	s_add_u32 s6, s6, s54
	s_addc_u32 s7, s7, 0
	global_load_dword v234, v135, s[6:7]
	s_add_u32 s6, s6, s54
	s_addc_u32 s7, s7, 0
	global_load_dword v235, v135, s[6:7]
	s_mul_i32 s50, s46, 63
	s_mov_b32 s30, s50
	s_mul_i32 s50, s50, s44
	s_add_i32 s50, s50, s43
	s_mul_hi_u32 s7, s50, 0x1600
	s_mul_i32 s6, s50, 0x1600
	s_add_u32 s6, s6, s52
	s_addc_u32 s7, s7, s53
	s_lshl_b32 s51, s1, 7
	s_add_i32 s45, s51, 0x800
	s_add_u32 s6, s6, s45
	s_addc_u32 s7, s7, 0
	s_lshl_b32 s45, s50, 11
	s_add_u32 s4, s2, 0x16f00000
	s_addc_u32 s5, s3, 0
	s_add_u32 s4, s4, s45
	s_addc_u32 s5, s5, 0
	s_lshl_b32 s45, s46, 10
	s_add_i32 s45, s45, s51
	s_add_u32 s4, s4, s45
	s_addc_u32 s5, s5, 0
	s_lshl_b32 s56, s44, 11
	s_mov_b32 s55, 0
	s_mov_b32 s3, 0
	s_mov_b32 s2, 1
	s_cmp_eq_u32 s46, 0
	s_cbranch_scc1 .Lgl1v_fwd
	s_sub_u32 s54, 0, s54
	s_subb_u32 s55, 0, 0
	s_sub_u32 s56, 0, s56
	s_subb_u32 s3, 0, 0
	s_mov_b32 s2, -1
; __device__ __forceinline__ void gl1_item(PREF p, int l, int item, bool valid, LAS unsigned char* pl, int sw, int lane) {
;     ...
;         for (int ss = 0; ss < 16; ++ss) { const int i = d ? 63 - ss : ss; const bf16_t* pr = P + (size_t)(row0 + i * rstride) * PW + h * 64 + lane;
;             qc[ss] = __builtin_bit_cast(float, (unsigned)pr[1024]); kc[ss] = __builtin_bit_cast(float, (unsigned)pr[1280]); }
;         __builtin_amdgcn_sched_barrier(0);
; #pragma unroll
;         for (int ss = 0; ss < 16; ++ss) { qc[ss] = bf2f(__builtin_bit_cast(unsigned, qc[ss])); kc[ss] = bf2f(__builtin_bit_cast(unsigned, kc[ss])); }
;         unsigned wupp[8];
; #pragma unroll
;         for (int r2 = 0; r2 < 8; ++r2) wupp[r2] = pk2(p.gla_wup[(size_t)((l * 2 + d) * 16 + 2 * r2) * 256 + h * 64 + lane], p.gla_wup[(size_t)((l * 2 + d) * 16 + 2 * r2 + 1) * 256 + h * 64 + lane]);
;         const float bup = p.gla_bup[(l * 2 + d) * 256 + h * 64 + lane];
; #pragma unroll 1
;         for (int g2 = 0; g2 < 2; ++g2) {
;             unsigned vr[16];
; #pragma unroll
;             for (int ii = 0; ii < 16; ++ii) { const int i = 32 * sw + g2 * 16 + ii; vr[ii] = *(const unsigned*)(P + (size_t)(row0 + i * rstride) * PW + 1536 + h * 128 + 2 * lane); }
; #pragma unroll
;             for (int ii = 0; ii < 16; ++ii) { const int i = 32 * sw + g2 * 16 + ii; sVt[(2 * lane) * 72 + i] = (bf16_t)(vr[ii] & 0xffffu); sVt[(2 * lane + 1) * 72 + i] = (bf16_t)(vr[ii] >> 16); }
;         }
;         float bc = 0.f;
; #pragma unroll 1
;         for (int g4 = 0; g4 < 4; ++g4) {
;             float qn[16], kn[16];
;             if (g4 < 3) {
; #pragma unroll
;                 for (int ss = 0; ss < 16; ++ss) { const int s = (g4 + 1) * 16 + ss; const int i = d ? 63 - s : s; const bf16_t* pr = P + (size_t)(row0 + i * rstride) * PW + h * 64 + lane;
;                     qn[ss] = __builtin_bit_cast(float, (unsigned)pr[1024]); kn[ss] = __builtin_bit_cast(float, (unsigned)pr[1280]); }
;                 __builtin_amdgcn_sched_barrier(0);
;             }
;             float gv[16];
; #pragma unroll
;             for (int ss = 0; ss < 16; ++ss) { const int s = g4 * 16 + ss; const int i = d ? 63 - s : s;
;                 float z = bup;
; #pragma unroll
;                 for (int r2 = 0; r2 < 8; ++r2) { const unsigned w = (unsigned)__builtin_amdgcn_readlane((int)lrp[r2], i);
.Lgl1v_fwd:
	s_mul_i32 s45, s46, 0x2400
	s_add_i32 s45, s45, s47
	s_add_i32 s45, s45, 0x4800
	s_lshl_b32 s50, s30, 1
	s_add_i32 s45, s45, s50
	s_movk_i32 s50, 0x90
	v_mul_u32_u24_e32 v60, 0x90, v64
	v_add_u32_e32 v60, s45, v60
	s_lshl_b32 s50, s2, 1
	v_mov_b32_e32 v61, s50
	s_waitcnt vmcnt(32)
	v_cvt_pk_bf16_f32 v8, v90, v91
	v_cvt_pk_bf16_f32 v9, v92, v93
	v_cvt_pk_bf16_f32 v10, v94, v95
	v_cvt_pk_bf16_f32 v11, v96, v97
	v_cvt_pk_bf16_f32 v12, v98, v99
	v_cvt_pk_bf16_f32 v13, v100, v101
	v_cvt_pk_bf16_f32 v14, v102, v103
	v_cvt_pk_bf16_f32 v15, v104, v105
	s_waitcnt vmcnt(0)
	v_mul_u32_u24_e32 v86, 0x120, v64
	s_lshl_b32 s45, s46, 6
	s_add_i32 s45, s45, s47
	v_add_u32_e32 v86, s45, v86
	ds_write_b16 v86, v34 offset:0
	ds_write_b16_d16_hi v86, v34 offset:144
	ds_write_b16 v86, v35 offset:2
	ds_write_b16_d16_hi v86, v35 offset:146
	ds_write_b16 v86, v36 offset:4
	ds_write_b16_d16_hi v86, v36 offset:148
	ds_write_b16 v86, v37 offset:6
	ds_write_b16_d16_hi v86, v37 offset:150
	ds_write_b16 v86, v38 offset:8
	ds_write_b16_d16_hi v86, v38 offset:152
	ds_write_b16 v86, v39 offset:10
	ds_write_b16_d16_hi v86, v39 offset:154
	ds_write_b16 v86, v40 offset:12
	ds_write_b16_d16_hi v86, v40 offset:156
	ds_write_b16 v86, v41 offset:14
	ds_write_b16_d16_hi v86, v41 offset:158
	ds_write_b16 v86, v42 offset:16
	ds_write_b16_d16_hi v86, v42 offset:160
	ds_write_b16 v86, v43 offset:18
	ds_write_b16_d16_hi v86, v43 offset:162
	ds_write_b16 v86, v44 offset:20
	ds_write_b16_d16_hi v86, v44 offset:164
	ds_write_b16 v86, v45 offset:22
	ds_write_b16_d16_hi v86, v45 offset:166
	ds_write_b16 v86, v46 offset:24
	ds_write_b16_d16_hi v86, v46 offset:168
	ds_write_b16 v86, v47 offset:26
	ds_write_b16_d16_hi v86, v47 offset:170
	ds_write_b16 v86, v212 offset:28
	ds_write_b16_d16_hi v86, v212 offset:172
	ds_write_b16 v86, v213 offset:30
	ds_write_b16_d16_hi v86, v213 offset:174
	ds_write_b16 v86, v214 offset:32
	ds_write_b16_d16_hi v86, v214 offset:176
	ds_write_b16 v86, v215 offset:34
	ds_write_b16_d16_hi v86, v215 offset:178
	ds_write_b16 v86, v216 offset:36
	ds_write_b16_d16_hi v86, v216 offset:180
	ds_write_b16 v86, v217 offset:38
	ds_write_b16_d16_hi v86, v217 offset:182
	ds_write_b16 v86, v218 offset:40
	ds_write_b16_d16_hi v86, v218 offset:184
	ds_write_b16 v86, v219 offset:42
	ds_write_b16_d16_hi v86, v219 offset:186
	ds_write_b16 v86, v222 offset:44
	ds_write_b16_d16_hi v86, v222 offset:188
	ds_write_b16 v86, v223 offset:46
	ds_write_b16_d16_hi v86, v223 offset:190
	ds_write_b16 v86, v228 offset:48
	ds_write_b16_d16_hi v86, v228 offset:192
	ds_write_b16 v86, v229 offset:50
	ds_write_b16_d16_hi v86, v229 offset:194
	ds_write_b16 v86, v230 offset:52
	ds_write_b16_d16_hi v86, v230 offset:196
	ds_write_b16 v86, v231 offset:54
	ds_write_b16_d16_hi v86, v231 offset:198
	ds_write_b16 v86, v232 offset:56
	ds_write_b16_d16_hi v86, v232 offset:200
	ds_write_b16 v86, v233 offset:58
	ds_write_b16_d16_hi v86, v233 offset:202
	ds_write_b16 v86, v234 offset:60
	ds_write_b16_d16_hi v86, v234 offset:204
	ds_write_b16 v86, v235 offset:62
	ds_write_b16_d16_hi v86, v235 offset:206
	global_load_ushort v148, v134, s[6:7]
	global_load_ushort v164, v134, s[6:7] offset:512
	s_add_u32 s6, s6, s54
	s_addc_u32 s7, s7, s55
	global_load_ushort v149, v134, s[6:7]
	global_load_ushort v165, v134, s[6:7] offset:512
	s_add_u32 s6, s6, s54
	s_addc_u32 s7, s7, s55
	global_load_ushort v150, v134, s[6:7]
	global_load_ushort v166, v134, s[6:7] offset:512
	s_add_u32 s6, s6, s54
	s_addc_u32 s7, s7, s55
	global_load_ushort v151, v134, s[6:7]
	global_load_ushort v167, v134, s[6:7] offset:512
	s_add_u32 s6, s6, s54
	s_addc_u32 s7, s7, s55
	global_load_ushort v152, v134, s[6:7]
	global_load_ushort v168, v134, s[6:7] offset:512
	s_add_u32 s6, s6, s54
	s_addc_u32 s7, s7, s55
	global_load_ushort v153, v134, s[6:7]
	global_load_ushort v169, v134, s[6:7] offset:512
	s_add_u32 s6, s6, s54
	s_addc_u32 s7, s7, s55
	global_load_ushort v154, v134, s[6:7]
	global_load_ushort v170, v134, s[6:7] offset:512
	s_add_u32 s6, s6, s54
	s_addc_u32 s7, s7, s55
	global_load_ushort v155, v134, s[6:7]
	global_load_ushort v171, v134, s[6:7] offset:512
	s_add_u32 s6, s6, s54
	s_addc_u32 s7, s7, s55
	global_load_ushort v156, v134, s[6:7]
	global_load_ushort v172, v134, s[6:7] offset:512
	s_add_u32 s6, s6, s54
	s_addc_u32 s7, s7, s55
	global_load_ushort v157, v134, s[6:7]
	global_load_ushort v173, v134, s[6:7] offset:512
	s_add_u32 s6, s6, s54
	s_addc_u32 s7, s7, s55
	global_load_ushort v158, v134, s[6:7]
	global_load_ushort v174, v134, s[6:7] offset:512
	s_add_u32 s6, s6, s54
	s_addc_u32 s7, s7, s55
	global_load_ushort v159, v134, s[6:7]
	global_load_ushort v175, v134, s[6:7] offset:512
	s_add_u32 s6, s6, s54
	s_addc_u32 s7, s7, s55
	global_load_ushort v160, v134, s[6:7]
	global_load_ushort v176, v134, s[6:7] offset:512
	s_add_u32 s6, s6, s54
	s_addc_u32 s7, s7, s55
	global_load_ushort v161, v134, s[6:7]
	global_load_ushort v177, v134, s[6:7] offset:512
	s_add_u32 s6, s6, s54
	s_addc_u32 s7, s7, s55
	global_load_ushort v162, v134, s[6:7]
	global_load_ushort v178, v134, s[6:7] offset:512
	s_add_u32 s6, s6, s54
	s_addc_u32 s7, s7, s55
	global_load_ushort v163, v134, s[6:7]
	global_load_ushort v179, v134, s[6:7] offset:512
	s_add_u32 s6, s6, s54
	s_addc_u32 s7, s7, s55
	v_mov_b32_e32 v17, 0
	s_mov_b32 s1, 0xbfb8aa3b
	v_mov_b32_e32 v236, v16
	v_dot2c_f32_bf16_dpp v236, v0, v8 row_newbcast:0 row_mask:0xf bank_mask:0xf
	v_dot2c_f32_bf16_dpp v236, v1, v9 row_newbcast:0 row_mask:0xf bank_mask:0xf
	v_dot2c_f32_bf16_dpp v236, v2, v10 row_newbcast:0 row_mask:0xf bank_mask:0xf
	v_dot2c_f32_bf16_dpp v236, v3, v11 row_newbcast:0 row_mask:0xf bank_mask:0xf
; __device__ __forceinline__ void gl1_item(PREF p, int l, int item, bool valid, LAS unsigned char* pl, int sw, int lane) {
;     ...
;             for (int ss = 0; ss < 16; ++ss) { const int s = g4 * 16 + ss; const int i = d ? 63 - s : s;
;                 float z = bup;
; #pragma unroll
;                 for (int r2 = 0; r2 < 8; ++r2) { const unsigned w = (unsigned)__builtin_amdgcn_readlane((int)lrp[r2], i);
;                     z = __builtin_amdgcn_fdot2_f32_bf16(__builtin_bit_cast(bf16x2_t, w), __builtin_bit_cast(bf16x2_t, wupp[r2]), z, false); }
;                 gv[ss] = -(fmaxf(-z, 0.f) + __logf(1.f + __expf(-fabsf(z)))) * (1.f / 16.f);
	v_dot2c_f32_bf16_dpp v236, v4, v12 row_newbcast:0 row_mask:0xf bank_mask:0xf
	v_dot2c_f32_bf16_dpp v236, v5, v13 row_newbcast:0 row_mask:0xf bank_mask:0xf
	v_dot2c_f32_bf16_dpp v236, v6, v14 row_newbcast:0 row_mask:0xf bank_mask:0xf
	v_dot2c_f32_bf16_dpp v236, v7, v15 row_newbcast:0 row_mask:0xf bank_mask:0xf
	v_mov_b32_e32 v237, v16
	v_dot2c_f32_bf16_dpp v237, v0, v8 row_newbcast:1 row_mask:0xf bank_mask:0xf
	v_dot2c_f32_bf16_dpp v237, v1, v9 row_newbcast:1 row_mask:0xf bank_mask:0xf
	v_dot2c_f32_bf16_dpp v237, v2, v10 row_newbcast:1 row_mask:0xf bank_mask:0xf
	v_dot2c_f32_bf16_dpp v237, v3, v11 row_newbcast:1 row_mask:0xf bank_mask:0xf
	v_dot2c_f32_bf16_dpp v237, v4, v12 row_newbcast:1 row_mask:0xf bank_mask:0xf
	v_dot2c_f32_bf16_dpp v237, v5, v13 row_newbcast:1 row_mask:0xf bank_mask:0xf
	v_dot2c_f32_bf16_dpp v237, v6, v14 row_newbcast:1 row_mask:0xf bank_mask:0xf
	v_dot2c_f32_bf16_dpp v237, v7, v15 row_newbcast:1 row_mask:0xf bank_mask:0xf
	v_mov_b32_e32 v238, v16
	v_dot2c_f32_bf16_dpp v238, v0, v8 row_newbcast:2 row_mask:0xf bank_mask:0xf
	v_dot2c_f32_bf16_dpp v238, v1, v9 row_newbcast:2 row_mask:0xf bank_mask:0xf
	v_dot2c_f32_bf16_dpp v238, v2, v10 row_newbcast:2 row_mask:0xf bank_mask:0xf
	v_dot2c_f32_bf16_dpp v238, v3, v11 row_newbcast:2 row_mask:0xf bank_mask:0xf
	v_dot2c_f32_bf16_dpp v238, v4, v12 row_newbcast:2 row_mask:0xf bank_mask:0xf
	v_dot2c_f32_bf16_dpp v238, v5, v13 row_newbcast:2 row_mask:0xf bank_mask:0xf
	v_dot2c_f32_bf16_dpp v238, v6, v14 row_newbcast:2 row_mask:0xf bank_mask:0xf
	v_dot2c_f32_bf16_dpp v238, v7, v15 row_newbcast:2 row_mask:0xf bank_mask:0xf
	v_mov_b32_e32 v239, v16
	v_dot2c_f32_bf16_dpp v239, v0, v8 row_newbcast:3 row_mask:0xf bank_mask:0xf
	v_dot2c_f32_bf16_dpp v239, v1, v9 row_newbcast:3 row_mask:0xf bank_mask:0xf
	v_dot2c_f32_bf16_dpp v239, v2, v10 row_newbcast:3 row_mask:0xf bank_mask:0xf
	v_dot2c_f32_bf16_dpp v239, v3, v11 row_newbcast:3 row_mask:0xf bank_mask:0xf
	v_dot2c_f32_bf16_dpp v239, v4, v12 row_newbcast:3 row_mask:0xf bank_mask:0xf
	v_dot2c_f32_bf16_dpp v239, v5, v13 row_newbcast:3 row_mask:0xf bank_mask:0xf
	v_dot2c_f32_bf16_dpp v239, v6, v14 row_newbcast:3 row_mask:0xf bank_mask:0xf
	v_dot2c_f32_bf16_dpp v239, v7, v15 row_newbcast:3 row_mask:0xf bank_mask:0xf
	v_mov_b32_e32 v240, v16
	v_dot2c_f32_bf16_dpp v240, v0, v8 row_newbcast:4 row_mask:0xf bank_mask:0xf
	v_dot2c_f32_bf16_dpp v240, v1, v9 row_newbcast:4 row_mask:0xf bank_mask:0xf
	v_dot2c_f32_bf16_dpp v240, v2, v10 row_newbcast:4 row_mask:0xf bank_mask:0xf
	v_dot2c_f32_bf16_dpp v240, v3, v11 row_newbcast:4 row_mask:0xf bank_mask:0xf
	v_dot2c_f32_bf16_dpp v240, v4, v12 row_newbcast:4 row_mask:0xf bank_mask:0xf
	v_dot2c_f32_bf16_dpp v240, v5, v13 row_newbcast:4 row_mask:0xf bank_mask:0xf
	v_dot2c_f32_bf16_dpp v240, v6, v14 row_newbcast:4 row_mask:0xf bank_mask:0xf
	v_dot2c_f32_bf16_dpp v240, v7, v15 row_newbcast:4 row_mask:0xf bank_mask:0xf
	v_mov_b32_e32 v241, v16
	v_dot2c_f32_bf16_dpp v241, v0, v8 row_newbcast:5 row_mask:0xf bank_mask:0xf
	v_dot2c_f32_bf16_dpp v241, v1, v9 row_newbcast:5 row_mask:0xf bank_mask:0xf
	v_dot2c_f32_bf16_dpp v241, v2, v10 row_newbcast:5 row_mask:0xf bank_mask:0xf
	v_dot2c_f32_bf16_dpp v241, v3, v11 row_newbcast:5 row_mask:0xf bank_mask:0xf
	v_dot2c_f32_bf16_dpp v241, v4, v12 row_newbcast:5 row_mask:0xf bank_mask:0xf
	v_dot2c_f32_bf16_dpp v241, v5, v13 row_newbcast:5 row_mask:0xf bank_mask:0xf
	v_dot2c_f32_bf16_dpp v241, v6, v14 row_newbcast:5 row_mask:0xf bank_mask:0xf
	v_dot2c_f32_bf16_dpp v241, v7, v15 row_newbcast:5 row_mask:0xf bank_mask:0xf
	v_mov_b32_e32 v242, v16
	v_dot2c_f32_bf16_dpp v242, v0, v8 row_newbcast:6 row_mask:0xf bank_mask:0xf
	v_dot2c_f32_bf16_dpp v242, v1, v9 row_newbcast:6 row_mask:0xf bank_mask:0xf
	v_dot2c_f32_bf16_dpp v242, v2, v10 row_newbcast:6 row_mask:0xf bank_mask:0xf
	v_dot2c_f32_bf16_dpp v242, v3, v11 row_newbcast:6 row_mask:0xf bank_mask:0xf
	v_dot2c_f32_bf16_dpp v242, v4, v12 row_newbcast:6 row_mask:0xf bank_mask:0xf
	v_dot2c_f32_bf16_dpp v242, v5, v13 row_newbcast:6 row_mask:0xf bank_mask:0xf
	v_dot2c_f32_bf16_dpp v242, v6, v14 row_newbcast:6 row_mask:0xf bank_mask:0xf
	v_dot2c_f32_bf16_dpp v242, v7, v15 row_newbcast:6 row_mask:0xf bank_mask:0xf
	v_mov_b32_e32 v243, v16
	v_dot2c_f32_bf16_dpp v243, v0, v8 row_newbcast:7 row_mask:0xf bank_mask:0xf
	v_dot2c_f32_bf16_dpp v243, v1, v9 row_newbcast:7 row_mask:0xf bank_mask:0xf
	v_dot2c_f32_bf16_dpp v243, v2, v10 row_newbcast:7 row_mask:0xf bank_mask:0xf
	v_dot2c_f32_bf16_dpp v243, v3, v11 row_newbcast:7 row_mask:0xf bank_mask:0xf
	v_dot2c_f32_bf16_dpp v243, v4, v12 row_newbcast:7 row_mask:0xf bank_mask:0xf
	v_dot2c_f32_bf16_dpp v243, v5, v13 row_newbcast:7 row_mask:0xf bank_mask:0xf
	v_dot2c_f32_bf16_dpp v243, v6, v14 row_newbcast:7 row_mask:0xf bank_mask:0xf
	v_dot2c_f32_bf16_dpp v243, v7, v15 row_newbcast:7 row_mask:0xf bank_mask:0xf
	v_mov_b32_e32 v244, v16
	v_dot2c_f32_bf16_dpp v244, v0, v8 row_newbcast:8 row_mask:0xf bank_mask:0xf
	v_dot2c_f32_bf16_dpp v244, v1, v9 row_newbcast:8 row_mask:0xf bank_mask:0xf
	v_dot2c_f32_bf16_dpp v244, v2, v10 row_newbcast:8 row_mask:0xf bank_mask:0xf
	v_dot2c_f32_bf16_dpp v244, v3, v11 row_newbcast:8 row_mask:0xf bank_mask:0xf
	v_dot2c_f32_bf16_dpp v244, v4, v12 row_newbcast:8 row_mask:0xf bank_mask:0xf
	v_dot2c_f32_bf16_dpp v244, v5, v13 row_newbcast:8 row_mask:0xf bank_mask:0xf
	v_dot2c_f32_bf16_dpp v244, v6, v14 row_newbcast:8 row_mask:0xf bank_mask:0xf
	v_dot2c_f32_bf16_dpp v244, v7, v15 row_newbcast:8 row_mask:0xf bank_mask:0xf
	v_mov_b32_e32 v245, v16
	v_dot2c_f32_bf16_dpp v245, v0, v8 row_newbcast:9 row_mask:0xf bank_mask:0xf
	v_dot2c_f32_bf16_dpp v245, v1, v9 row_newbcast:9 row_mask:0xf bank_mask:0xf
; __device__ __forceinline__ void gl1_item(PREF p, int l, int item, bool valid, LAS unsigned char* pl, int sw, int lane) {
;     ...
;             for (int ss = 0; ss < 16; ++ss) { const int s = g4 * 16 + ss; const int i = d ? 63 - s : s;
;                 float z = bup;
; #pragma unroll
;                 for (int r2 = 0; r2 < 8; ++r2) { const unsigned w = (unsigned)__builtin_amdgcn_readlane((int)lrp[r2], i);
;                     z = __builtin_amdgcn_fdot2_f32_bf16(__builtin_bit_cast(bf16x2_t, w), __builtin_bit_cast(bf16x2_t, wupp[r2]), z, false); }
;                 gv[ss] = -(fmaxf(-z, 0.f) + __logf(1.f + __expf(-fabsf(z)))) * (1.f / 16.f);
	v_dot2c_f32_bf16_dpp v245, v2, v10 row_newbcast:9 row_mask:0xf bank_mask:0xf
	v_dot2c_f32_bf16_dpp v245, v3, v11 row_newbcast:9 row_mask:0xf bank_mask:0xf
	v_dot2c_f32_bf16_dpp v245, v4, v12 row_newbcast:9 row_mask:0xf bank_mask:0xf
	v_dot2c_f32_bf16_dpp v245, v5, v13 row_newbcast:9 row_mask:0xf bank_mask:0xf
	v_dot2c_f32_bf16_dpp v245, v6, v14 row_newbcast:9 row_mask:0xf bank_mask:0xf
	v_dot2c_f32_bf16_dpp v245, v7, v15 row_newbcast:9 row_mask:0xf bank_mask:0xf
	v_mov_b32_e32 v246, v16
	v_dot2c_f32_bf16_dpp v246, v0, v8 row_newbcast:10 row_mask:0xf bank_mask:0xf
	v_dot2c_f32_bf16_dpp v246, v1, v9 row_newbcast:10 row_mask:0xf bank_mask:0xf
	v_dot2c_f32_bf16_dpp v246, v2, v10 row_newbcast:10 row_mask:0xf bank_mask:0xf
	v_dot2c_f32_bf16_dpp v246, v3, v11 row_newbcast:10 row_mask:0xf bank_mask:0xf
	v_dot2c_f32_bf16_dpp v246, v4, v12 row_newbcast:10 row_mask:0xf bank_mask:0xf
	v_dot2c_f32_bf16_dpp v246, v5, v13 row_newbcast:10 row_mask:0xf bank_mask:0xf
	v_dot2c_f32_bf16_dpp v246, v6, v14 row_newbcast:10 row_mask:0xf bank_mask:0xf
	v_dot2c_f32_bf16_dpp v246, v7, v15 row_newbcast:10 row_mask:0xf bank_mask:0xf
	v_mov_b32_e32 v247, v16
	v_dot2c_f32_bf16_dpp v247, v0, v8 row_newbcast:11 row_mask:0xf bank_mask:0xf
	v_dot2c_f32_bf16_dpp v247, v1, v9 row_newbcast:11 row_mask:0xf bank_mask:0xf
	v_dot2c_f32_bf16_dpp v247, v2, v10 row_newbcast:11 row_mask:0xf bank_mask:0xf
	v_dot2c_f32_bf16_dpp v247, v3, v11 row_newbcast:11 row_mask:0xf bank_mask:0xf
	v_dot2c_f32_bf16_dpp v247, v4, v12 row_newbcast:11 row_mask:0xf bank_mask:0xf
	v_dot2c_f32_bf16_dpp v247, v5, v13 row_newbcast:11 row_mask:0xf bank_mask:0xf
	v_dot2c_f32_bf16_dpp v247, v6, v14 row_newbcast:11 row_mask:0xf bank_mask:0xf
	v_dot2c_f32_bf16_dpp v247, v7, v15 row_newbcast:11 row_mask:0xf bank_mask:0xf
	v_mov_b32_e32 v248, v16
	v_dot2c_f32_bf16_dpp v248, v0, v8 row_newbcast:12 row_mask:0xf bank_mask:0xf
	v_dot2c_f32_bf16_dpp v248, v1, v9 row_newbcast:12 row_mask:0xf bank_mask:0xf
	v_dot2c_f32_bf16_dpp v248, v2, v10 row_newbcast:12 row_mask:0xf bank_mask:0xf
	v_dot2c_f32_bf16_dpp v248, v3, v11 row_newbcast:12 row_mask:0xf bank_mask:0xf
	v_dot2c_f32_bf16_dpp v248, v4, v12 row_newbcast:12 row_mask:0xf bank_mask:0xf
	v_dot2c_f32_bf16_dpp v248, v5, v13 row_newbcast:12 row_mask:0xf bank_mask:0xf
	v_dot2c_f32_bf16_dpp v248, v6, v14 row_newbcast:12 row_mask:0xf bank_mask:0xf
	v_dot2c_f32_bf16_dpp v248, v7, v15 row_newbcast:12 row_mask:0xf bank_mask:0xf
	v_mov_b32_e32 v249, v16
	v_dot2c_f32_bf16_dpp v249, v0, v8 row_newbcast:13 row_mask:0xf bank_mask:0xf
	v_dot2c_f32_bf16_dpp v249, v1, v9 row_newbcast:13 row_mask:0xf bank_mask:0xf
	v_dot2c_f32_bf16_dpp v249, v2, v10 row_newbcast:13 row_mask:0xf bank_mask:0xf
	v_dot2c_f32_bf16_dpp v249, v3, v11 row_newbcast:13 row_mask:0xf bank_mask:0xf
	v_dot2c_f32_bf16_dpp v249, v4, v12 row_newbcast:13 row_mask:0xf bank_mask:0xf
	v_dot2c_f32_bf16_dpp v249, v5, v13 row_newbcast:13 row_mask:0xf bank_mask:0xf
	v_dot2c_f32_bf16_dpp v249, v6, v14 row_newbcast:13 row_mask:0xf bank_mask:0xf
	v_dot2c_f32_bf16_dpp v249, v7, v15 row_newbcast:13 row_mask:0xf bank_mask:0xf
	v_mov_b32_e32 v250, v16
	v_dot2c_f32_bf16_dpp v250, v0, v8 row_newbcast:14 row_mask:0xf bank_mask:0xf
	v_dot2c_f32_bf16_dpp v250, v1, v9 row_newbcast:14 row_mask:0xf bank_mask:0xf
	v_dot2c_f32_bf16_dpp v250, v2, v10 row_newbcast:14 row_mask:0xf bank_mask:0xf
	v_dot2c_f32_bf16_dpp v250, v3, v11 row_newbcast:14 row_mask:0xf bank_mask:0xf
	v_dot2c_f32_bf16_dpp v250, v4, v12 row_newbcast:14 row_mask:0xf bank_mask:0xf
	v_dot2c_f32_bf16_dpp v250, v5, v13 row_newbcast:14 row_mask:0xf bank_mask:0xf
	v_dot2c_f32_bf16_dpp v250, v6, v14 row_newbcast:14 row_mask:0xf bank_mask:0xf
	v_dot2c_f32_bf16_dpp v250, v7, v15 row_newbcast:14 row_mask:0xf bank_mask:0xf
	v_mov_b32_e32 v251, v16
	v_dot2c_f32_bf16_dpp v251, v0, v8 row_newbcast:15 row_mask:0xf bank_mask:0xf
	v_dot2c_f32_bf16_dpp v251, v1, v9 row_newbcast:15 row_mask:0xf bank_mask:0xf
	v_dot2c_f32_bf16_dpp v251, v2, v10 row_newbcast:15 row_mask:0xf bank_mask:0xf
	v_dot2c_f32_bf16_dpp v251, v3, v11 row_newbcast:15 row_mask:0xf bank_mask:0xf
	v_dot2c_f32_bf16_dpp v251, v4, v12 row_newbcast:15 row_mask:0xf bank_mask:0xf
	v_dot2c_f32_bf16_dpp v251, v5, v13 row_newbcast:15 row_mask:0xf bank_mask:0xf
	v_dot2c_f32_bf16_dpp v251, v6, v14 row_newbcast:15 row_mask:0xf bank_mask:0xf
	v_dot2c_f32_bf16_dpp v251, v7, v15 row_newbcast:15 row_mask:0xf bank_mask:0xf
	s_nop 2
	v_mul_f32_e64 v18, |v236|, s1
	v_mul_f32_e64 v19, |v237|, s1
	v_mul_f32_e64 v20, |v238|, s1
	v_mul_f32_e64 v21, |v239|, s1
	v_mul_f32_e64 v22, |v240|, s1
	v_mul_f32_e64 v23, |v241|, s1
	v_mul_f32_e64 v24, |v242|, s1
	v_mul_f32_e64 v25, |v243|, s1
	v_mul_f32_e64 v26, |v244|, s1
	v_mul_f32_e64 v27, |v245|, s1
	v_mul_f32_e64 v28, |v246|, s1
	v_mul_f32_e64 v29, |v247|, s1
	v_mul_f32_e64 v30, |v248|, s1
	v_mul_f32_e64 v31, |v249|, s1
	v_mul_f32_e64 v32, |v250|, s1
	v_mul_f32_e64 v33, |v251|, s1
	v_exp_f32_e32 v18, v18
	v_exp_f32_e32 v19, v19
	v_exp_f32_e32 v20, v20
	v_exp_f32_e32 v21, v21
	v_exp_f32_e32 v22, v22
	v_exp_f32_e32 v23, v23
	v_exp_f32_e32 v24, v24
	v_exp_f32_e32 v25, v25
	v_exp_f32_e32 v26, v26
	v_exp_f32_e32 v27, v27
	v_exp_f32_e32 v28, v28
	v_exp_f32_e32 v29, v29
	v_exp_f32_e32 v30, v30
	v_exp_f32_e32 v31, v31
	v_exp_f32_e32 v32, v32
	v_exp_f32_e32 v33, v33
	v_max_f32_e64 v236, -v236, -v236
	v_max_f32_e64 v237, -v237, -v237
	v_max_f32_e64 v238, -v238, -v238
	v_max_f32_e64 v239, -v239, -v239
	v_max_f32_e64 v240, -v240, -v240
	v_max_f32_e64 v241, -v241, -v241
	v_max_f32_e64 v242, -v242, -v242
	v_max_f32_e64 v243, -v243, -v243
	v_max_f32_e64 v244, -v244, -v244
	v_max_f32_e64 v245, -v245, -v245
; __device__ __forceinline__ void gl1_item(PREF p, int l, int item, bool valid, LAS unsigned char* pl, int sw, int lane) {
;     ...
;                 for (int r2 = 0; r2 < 8; ++r2) { const unsigned w = (unsigned)__builtin_amdgcn_readlane((int)lrp[r2], i);
;                     z = __builtin_amdgcn_fdot2_f32_bf16(__builtin_bit_cast(bf16x2_t, w), __builtin_bit_cast(bf16x2_t, wupp[r2]), z, false); }
;                 gv[ss] = -(fmaxf(-z, 0.f) + __logf(1.f + __expf(-fabsf(z)))) * (1.f / 16.f);
;                 __builtin_amdgcn_sched_barrier(0);
;             }
; #pragma unroll
;             for (int ss = 0; ss < 16; ++ss) { const int s = g4 * 16 + ss; const int i = d ? 63 - s : s; const size_t rowi = (size_t)(row0 + i * rstride);
;                 bc += gv[ss];
;                 const float en = __expf(-bc), ep = __expf(bc);
;                 const float kt = kc[ss] * en, qt = qc[ss] * 0.125f * ep;
	v_max_f32_e64 v246, -v246, -v246
	v_max_f32_e64 v247, -v247, -v247
	v_max_f32_e64 v248, -v248, -v248
	v_max_f32_e64 v249, -v249, -v249
	v_max_f32_e64 v250, -v250, -v250
	v_max_f32_e64 v251, -v251, -v251
	v_max_f32_e32 v236, 0, v236
	v_max_f32_e32 v237, 0, v237
	v_max_f32_e32 v238, 0, v238
	v_max_f32_e32 v239, 0, v239
	v_max_f32_e32 v240, 0, v240
	v_max_f32_e32 v241, 0, v241
	v_max_f32_e32 v242, 0, v242
	v_max_f32_e32 v243, 0, v243
	v_max_f32_e32 v244, 0, v244
	v_max_f32_e32 v245, 0, v245
	v_max_f32_e32 v246, 0, v246
	v_max_f32_e32 v247, 0, v247
	v_max_f32_e32 v248, 0, v248
	v_max_f32_e32 v249, 0, v249
	v_max_f32_e32 v250, 0, v250
	v_max_f32_e32 v251, 0, v251
	v_add_f32_e32 v18, 1.0, v18
	v_add_f32_e32 v19, 1.0, v19
	v_add_f32_e32 v20, 1.0, v20
	v_add_f32_e32 v21, 1.0, v21
	v_add_f32_e32 v22, 1.0, v22
	v_add_f32_e32 v23, 1.0, v23
	v_add_f32_e32 v24, 1.0, v24
	v_add_f32_e32 v25, 1.0, v25
	v_add_f32_e32 v26, 1.0, v26
	v_add_f32_e32 v27, 1.0, v27
	v_add_f32_e32 v28, 1.0, v28
	v_add_f32_e32 v29, 1.0, v29
	v_add_f32_e32 v30, 1.0, v30
	v_add_f32_e32 v31, 1.0, v31
	v_add_f32_e32 v32, 1.0, v32
	v_add_f32_e32 v33, 1.0, v33
	v_log_f32_e32 v18, v18
	v_log_f32_e32 v19, v19
	v_log_f32_e32 v20, v20
	v_log_f32_e32 v21, v21
	v_log_f32_e32 v22, v22
	v_log_f32_e32 v23, v23
	v_log_f32_e32 v24, v24
	v_log_f32_e32 v25, v25
	v_log_f32_e32 v26, v26
	v_log_f32_e32 v27, v27
	v_log_f32_e32 v28, v28
	v_log_f32_e32 v29, v29
	v_log_f32_e32 v30, v30
	v_log_f32_e32 v31, v31
	v_log_f32_e32 v32, v32
	v_log_f32_e32 v33, v33
	s_mov_b32 s45, 0x3f317217
	v_mul_f32_e32 v70, 0x3f317217, v18
	v_mul_f32_e32 v71, 0x3f317217, v19
	v_mul_f32_e32 v72, 0x3f317217, v20
	v_mul_f32_e32 v73, 0x3f317217, v21
	v_mul_f32_e32 v74, 0x3f317217, v22
	v_mul_f32_e32 v75, 0x3f317217, v23
	v_mul_f32_e32 v76, 0x3f317217, v24
	v_mul_f32_e32 v77, 0x3f317217, v25
	v_mul_f32_e32 v78, 0x3f317217, v26
	v_mul_f32_e32 v79, 0x3f317217, v27
	v_mul_f32_e32 v80, 0x3f317217, v28
	v_mul_f32_e32 v81, 0x3f317217, v29
	v_mul_f32_e32 v82, 0x3f317217, v30
	v_mul_f32_e32 v83, 0x3f317217, v31
	v_mul_f32_e32 v84, 0x3f317217, v32
	v_mul_f32_e32 v85, 0x3f317217, v33
	v_fma_f32 v70, v18, s45, -v70
	v_fma_f32 v71, v19, s45, -v71
	v_fma_f32 v72, v20, s45, -v72
	v_fma_f32 v73, v21, s45, -v73
	v_fma_f32 v74, v22, s45, -v74
	v_fma_f32 v75, v23, s45, -v75
	v_fma_f32 v76, v24, s45, -v76
	v_fma_f32 v77, v25, s45, -v77
	v_fma_f32 v78, v26, s45, -v78
	v_fma_f32 v79, v27, s45, -v79
	v_fma_f32 v80, v28, s45, -v80
	v_fma_f32 v81, v29, s45, -v81
	v_fma_f32 v82, v30, s45, -v82
	v_fma_f32 v83, v31, s45, -v83
	v_fma_f32 v84, v32, s45, -v84
	v_fma_f32 v85, v33, s45, -v85
	v_fmac_f32_e32 v70, 0x3377d1cf, v18
	v_fmac_f32_e32 v71, 0x3377d1cf, v19
	v_fmac_f32_e32 v72, 0x3377d1cf, v20
	v_fmac_f32_e32 v73, 0x3377d1cf, v21
	v_fmac_f32_e32 v74, 0x3377d1cf, v22
	v_fmac_f32_e32 v75, 0x3377d1cf, v23
	v_fmac_f32_e32 v76, 0x3377d1cf, v24
	v_fmac_f32_e32 v77, 0x3377d1cf, v25
	v_fmac_f32_e32 v78, 0x3377d1cf, v26
	v_fmac_f32_e32 v79, 0x3377d1cf, v27
	v_fmac_f32_e32 v80, 0x3377d1cf, v28
	v_fmac_f32_e32 v81, 0x3377d1cf, v29
	v_fmac_f32_e32 v82, 0x3377d1cf, v30
	v_fmac_f32_e32 v83, 0x3377d1cf, v31
	v_fmac_f32_e32 v84, 0x3377d1cf, v32
	v_fmac_f32_e32 v85, 0x3377d1cf, v33
	v_fmac_f32_e32 v70, 0x3f317217, v18
	v_fmac_f32_e32 v71, 0x3f317217, v19
	v_fmac_f32_e32 v72, 0x3f317217, v20
	v_fmac_f32_e32 v73, 0x3f317217, v21
	v_fmac_f32_e32 v74, 0x3f317217, v22
	v_fmac_f32_e32 v75, 0x3f317217, v23
	v_fmac_f32_e32 v76, 0x3f317217, v24
	v_fmac_f32_e32 v77, 0x3f317217, v25
	v_fmac_f32_e32 v78, 0x3f317217, v26
	v_fmac_f32_e32 v79, 0x3f317217, v27
	v_fmac_f32_e32 v80, 0x3f317217, v28
	v_fmac_f32_e32 v81, 0x3f317217, v29
	v_fmac_f32_e32 v82, 0x3f317217, v30
	v_fmac_f32_e32 v83, 0x3f317217, v31
	v_fmac_f32_e32 v84, 0x3f317217, v32
	v_fmac_f32_e32 v85, 0x3f317217, v33
	v_add_f32_e32 v236, v236, v70
	v_add_f32_e32 v237, v237, v71
	v_add_f32_e32 v238, v238, v72
	v_add_f32_e32 v239, v239, v73
	v_add_f32_e32 v240, v240, v74
	v_add_f32_e32 v241, v241, v75
	v_add_f32_e32 v242, v242, v76
	v_add_f32_e32 v243, v243, v77
	v_add_f32_e32 v244, v244, v78
	v_add_f32_e32 v245, v245, v79
	v_add_f32_e32 v246, v246, v80
	v_add_f32_e32 v247, v247, v81
	v_add_f32_e32 v248, v248, v82
	v_add_f32_e32 v249, v249, v83
	v_add_f32_e32 v250, v250, v84
	v_add_f32_e32 v251, v251, v85
	v_mov_b32_e32 v70, v17
	v_fmac_f32_e32 v70, 0xbd800000, v236
	v_mov_b32_e32 v71, v70
	v_fmac_f32_e32 v71, 0xbd800000, v237
	v_mov_b32_e32 v72, v71
	v_fmac_f32_e32 v72, 0xbd800000, v238
	v_mov_b32_e32 v73, v72
	v_fmac_f32_e32 v73, 0xbd800000, v239
	v_mov_b32_e32 v74, v73
	v_fmac_f32_e32 v74, 0xbd800000, v240
	v_mov_b32_e32 v75, v74
	v_fmac_f32_e32 v75, 0xbd800000, v241
	v_mov_b32_e32 v76, v75
	v_fmac_f32_e32 v76, 0xbd800000, v242
	v_mov_b32_e32 v77, v76
	v_fmac_f32_e32 v77, 0xbd800000, v243
	v_mov_b32_e32 v78, v77
	v_fmac_f32_e32 v78, 0xbd800000, v244
	v_mov_b32_e32 v79, v78
	v_fmac_f32_e32 v79, 0xbd800000, v245
	v_mov_b32_e32 v80, v79
	v_fmac_f32_e32 v80, 0xbd800000, v246
	v_mov_b32_e32 v81, v80
	v_fmac_f32_e32 v81, 0xbd800000, v247
	v_mov_b32_e32 v82, v81
	v_fmac_f32_e32 v82, 0xbd800000, v248
	v_mov_b32_e32 v83, v82
	v_fmac_f32_e32 v83, 0xbd800000, v249
	v_mov_b32_e32 v84, v83
	v_fmac_f32_e32 v84, 0xbd800000, v250
	v_mov_b32_e32 v85, v84
	v_fmac_f32_e32 v85, 0xbd800000, v251
	v_mov_b32_e32 v17, v85
	s_waitcnt vmcnt(0)
; __device__ __forceinline__ void gl1_item(PREF p, int l, int item, bool valid, LAS unsigned char* pl, int sw, int lane) {
;     ...
;             float qn[16], kn[16];
;             if (g4 < 3) {
; #pragma unroll
;                 for (int ss = 0; ss < 16; ++ss) { const int s = (g4 + 1) * 16 + ss; const int i = d ? 63 - s : s; const bf16_t* pr = P + (size_t)(row0 + i * rstride) * PW + h * 64 + lane;
;                     qn[ss] = __builtin_bit_cast(float, (unsigned)pr[1024]); kn[ss] = __builtin_bit_cast(float, (unsigned)pr[1280]); }
;                 __builtin_amdgcn_sched_barrier(0);
;             }
;             float gv[16];
; #pragma unroll
;             for (int ss = 0; ss < 16; ++ss) { const int s = g4 * 16 + ss; const int i = d ? 63 - s : s;
;                 float z = bup;
; #pragma unroll
;                 for (int r2 = 0; r2 < 8; ++r2) { const unsigned w = (unsigned)__builtin_amdgcn_readlane((int)lrp[r2], i);
;                     z = __builtin_amdgcn_fdot2_f32_bf16(__builtin_bit_cast(bf16x2_t, w), __builtin_bit_cast(bf16x2_t, wupp[r2]), z, false); }
;                 gv[ss] = -(fmaxf(-z, 0.f) + __logf(1.f + __expf(-fabsf(z)))) * (1.f / 16.f);
;                 __builtin_amdgcn_sched_barrier(0);
;             }
; #pragma unroll
;             for (int ss = 0; ss < 16; ++ss) { const int s = g4 * 16 + ss; const int i = d ? 63 - s : s; const size_t rowi = (size_t)(row0 + i * rstride);
;                 bc += gv[ss];
;                 const float en = __expf(-bc), ep = __expf(bc);
;                 const float kt = kc[ss] * en, qt = qc[ss] * 0.125f * ep;
	global_load_ushort v180, v134, s[6:7]
	global_load_ushort v196, v134, s[6:7] offset:512
	s_add_u32 s6, s6, s54
	s_addc_u32 s7, s7, s55
	global_load_ushort v181, v134, s[6:7]
	global_load_ushort v197, v134, s[6:7] offset:512
	s_add_u32 s6, s6, s54
	s_addc_u32 s7, s7, s55
	global_load_ushort v182, v134, s[6:7]
	global_load_ushort v198, v134, s[6:7] offset:512
	s_add_u32 s6, s6, s54
	s_addc_u32 s7, s7, s55
	global_load_ushort v183, v134, s[6:7]
	global_load_ushort v199, v134, s[6:7] offset:512
	s_add_u32 s6, s6, s54
	s_addc_u32 s7, s7, s55
	global_load_ushort v184, v134, s[6:7]
	global_load_ushort v200, v134, s[6:7] offset:512
	s_add_u32 s6, s6, s54
	s_addc_u32 s7, s7, s55
	global_load_ushort v185, v134, s[6:7]
	global_load_ushort v201, v134, s[6:7] offset:512
	s_add_u32 s6, s6, s54
	s_addc_u32 s7, s7, s55
	global_load_ushort v186, v134, s[6:7]
	global_load_ushort v202, v134, s[6:7] offset:512
	s_add_u32 s6, s6, s54
	s_addc_u32 s7, s7, s55
	global_load_ushort v187, v134, s[6:7]
	global_load_ushort v203, v134, s[6:7] offset:512
	s_add_u32 s6, s6, s54
	s_addc_u32 s7, s7, s55
	global_load_ushort v188, v134, s[6:7]
	global_load_ushort v204, v134, s[6:7] offset:512
	s_add_u32 s6, s6, s54
	s_addc_u32 s7, s7, s55
	global_load_ushort v189, v134, s[6:7]
	global_load_ushort v205, v134, s[6:7] offset:512
	s_add_u32 s6, s6, s54
	s_addc_u32 s7, s7, s55
	global_load_ushort v190, v134, s[6:7]
	global_load_ushort v206, v134, s[6:7] offset:512
	s_add_u32 s6, s6, s54
	s_addc_u32 s7, s7, s55
	global_load_ushort v191, v134, s[6:7]
	global_load_ushort v207, v134, s[6:7] offset:512
	s_add_u32 s6, s6, s54
	s_addc_u32 s7, s7, s55
	global_load_ushort v192, v134, s[6:7]
	global_load_ushort v208, v134, s[6:7] offset:512
	s_add_u32 s6, s6, s54
	s_addc_u32 s7, s7, s55
	global_load_ushort v193, v134, s[6:7]
	global_load_ushort v209, v134, s[6:7] offset:512
	s_add_u32 s6, s6, s54
	s_addc_u32 s7, s7, s55
	global_load_ushort v194, v134, s[6:7]
	global_load_ushort v210, v134, s[6:7] offset:512
	s_add_u32 s6, s6, s54
	s_addc_u32 s7, s7, s55
	global_load_ushort v195, v134, s[6:7]
	global_load_ushort v211, v134, s[6:7] offset:512
	s_add_u32 s6, s6, s54
	s_addc_u32 s7, s7, s55
	v_mul_f32_e32 v18, 0xbfb8aa3b, v70
	v_mul_f32_e32 v19, 0xbfb8aa3b, v71
	v_mul_f32_e32 v20, 0xbfb8aa3b, v72
	v_mul_f32_e32 v21, 0xbfb8aa3b, v73
	v_mul_f32_e32 v22, 0xbfb8aa3b, v74
	v_mul_f32_e32 v23, 0xbfb8aa3b, v75
	v_mul_f32_e32 v24, 0xbfb8aa3b, v76
	v_mul_f32_e32 v25, 0xbfb8aa3b, v77
	v_mul_f32_e32 v26, 0xbfb8aa3b, v78
	v_mul_f32_e32 v27, 0xbfb8aa3b, v79
	v_mul_f32_e32 v28, 0xbfb8aa3b, v80
	v_mul_f32_e32 v29, 0xbfb8aa3b, v81
	v_mul_f32_e32 v30, 0xbfb8aa3b, v82
	v_mul_f32_e32 v31, 0xbfb8aa3b, v83
	v_mul_f32_e32 v32, 0xbfb8aa3b, v84
	v_mul_f32_e32 v33, 0xbfb8aa3b, v85
	v_mul_f32_e32 v236, 0x3fb8aa3b, v70
	v_mul_f32_e32 v237, 0x3fb8aa3b, v71
	v_mul_f32_e32 v238, 0x3fb8aa3b, v72
	v_mul_f32_e32 v239, 0x3fb8aa3b, v73
	v_mul_f32_e32 v240, 0x3fb8aa3b, v74
	v_mul_f32_e32 v241, 0x3fb8aa3b, v75
	v_mul_f32_e32 v242, 0x3fb8aa3b, v76
	v_mul_f32_e32 v243, 0x3fb8aa3b, v77
	v_mul_f32_e32 v244, 0x3fb8aa3b, v78
	v_mul_f32_e32 v245, 0x3fb8aa3b, v79
	v_mul_f32_e32 v246, 0x3fb8aa3b, v80
	v_mul_f32_e32 v247, 0x3fb8aa3b, v81
	v_mul_f32_e32 v248, 0x3fb8aa3b, v82
	v_mul_f32_e32 v249, 0x3fb8aa3b, v83
	v_mul_f32_e32 v250, 0x3fb8aa3b, v84
	v_mul_f32_e32 v251, 0x3fb8aa3b, v85
	v_exp_f32_e32 v18, v18
	v_exp_f32_e32 v19, v19
	v_exp_f32_e32 v20, v20
	v_exp_f32_e32 v21, v21
	v_exp_f32_e32 v22, v22
	v_exp_f32_e32 v23, v23
	v_exp_f32_e32 v24, v24
	v_exp_f32_e32 v25, v25
	v_exp_f32_e32 v26, v26
	v_exp_f32_e32 v27, v27
	v_exp_f32_e32 v28, v28
	v_exp_f32_e32 v29, v29
	v_exp_f32_e32 v30, v30
	v_exp_f32_e32 v31, v31
	v_exp_f32_e32 v32, v32
	v_exp_f32_e32 v33, v33
	v_exp_f32_e32 v236, v236
	v_exp_f32_e32 v237, v237
	v_exp_f32_e32 v238, v238
	v_exp_f32_e32 v239, v239
	v_exp_f32_e32 v240, v240
	v_exp_f32_e32 v241, v241
	v_exp_f32_e32 v242, v242
	v_exp_f32_e32 v243, v243
	v_exp_f32_e32 v244, v244
	v_exp_f32_e32 v245, v245
	v_exp_f32_e32 v246, v246
	v_exp_f32_e32 v247, v247
	v_exp_f32_e32 v248, v248
	v_exp_f32_e32 v249, v249
	v_exp_f32_e32 v250, v250
	v_exp_f32_e32 v251, v251
	v_lshlrev_b32_e32 v164, 16, v164
	v_lshlrev_b32_e32 v165, 16, v165
	v_lshlrev_b32_e32 v166, 16, v166
	v_lshlrev_b32_e32 v167, 16, v167
	v_lshlrev_b32_e32 v168, 16, v168
	v_lshlrev_b32_e32 v169, 16, v169
	v_lshlrev_b32_e32 v170, 16, v170
	v_lshlrev_b32_e32 v171, 16, v171
	v_lshlrev_b32_e32 v172, 16, v172
	v_lshlrev_b32_e32 v173, 16, v173
	v_lshlrev_b32_e32 v174, 16, v174
	v_lshlrev_b32_e32 v175, 16, v175
	v_lshlrev_b32_e32 v176, 16, v176
	v_lshlrev_b32_e32 v177, 16, v177
	v_lshlrev_b32_e32 v178, 16, v178
	v_lshlrev_b32_e32 v179, 16, v179
	v_lshlrev_b32_e32 v148, 16, v148
	v_lshlrev_b32_e32 v149, 16, v149
	v_lshlrev_b32_e32 v150, 16, v150
	v_lshlrev_b32_e32 v151, 16, v151
	v_lshlrev_b32_e32 v152, 16, v152
	v_lshlrev_b32_e32 v153, 16, v153
	v_lshlrev_b32_e32 v154, 16, v154
	v_lshlrev_b32_e32 v155, 16, v155
	v_lshlrev_b32_e32 v156, 16, v156
	v_lshlrev_b32_e32 v157, 16, v157
	v_lshlrev_b32_e32 v158, 16, v158
	v_lshlrev_b32_e32 v159, 16, v159
	v_lshlrev_b32_e32 v160, 16, v160
	v_lshlrev_b32_e32 v161, 16, v161
	v_lshlrev_b32_e32 v162, 16, v162
	v_lshlrev_b32_e32 v163, 16, v163
	v_mul_f32_e32 v164, v18, v164
	v_mul_f32_e32 v165, v19, v165
	v_mul_f32_e32 v166, v20, v166
	v_mul_f32_e32 v167, v21, v167
	v_mul_f32_e32 v168, v22, v168
	v_mul_f32_e32 v169, v23, v169
	v_mul_f32_e32 v170, v24, v170
	v_mul_f32_e32 v171, v25, v171
	v_mul_f32_e32 v172, v26, v172
	v_mul_f32_e32 v173, v27, v173
	v_mul_f32_e32 v174, v28, v174
	v_mul_f32_e32 v175, v29, v175
	v_mul_f32_e32 v176, v30, v176
; __device__ __forceinline__ unsigned f2bf(float f) { unsigned r; asm("v_cvt_pk_bf16_f32 %0, %1, %1" : "=v"(r) : "v"(f)); return r & 0xffffu; }
; __device__ __forceinline__ void gl1_item(PREF p, int l, int item, bool valid, LAS unsigned char* pl, int sw, int lane) {
;     ...
;             for (int ss = 0; ss < 16; ++ss) { const int s = g4 * 16 + ss; const int i = d ? 63 - s : s;
;                 float z = bup;
; #pragma unroll
;                 for (int r2 = 0; r2 < 8; ++r2) { const unsigned w = (unsigned)__builtin_amdgcn_readlane((int)lrp[r2], i);
;                     z = __builtin_amdgcn_fdot2_f32_bf16(__builtin_bit_cast(bf16x2_t, w), __builtin_bit_cast(bf16x2_t, wupp[r2]), z, false); }
;     ...
;                 const float kt = kc[ss] * en, qt = qc[ss] * 0.125f * ep;
;                 const unsigned ktb = f2bf(kt);
;                 sKt[lane * 72 + i] = (bf16_t)ktb;
;                 QK[rowi * 1024 + d * 512 + h * 64 + lane] = (bf16_t)f2bf(qt);
;                 QK[rowi * 1024 + d * 512 + 256 + h * 64 + lane] = (bf16_t)ktb;
;             }
; #pragma unroll
;             for (int ss = 0; ss < 16; ++ss) { qc[ss] = bf2f(__builtin_bit_cast(unsigned, qn[ss])); kc[ss] = bf2f(__builtin_bit_cast(unsigned, kn[ss])); }
	v_mul_f32_e32 v177, v31, v177
	v_mul_f32_e32 v178, v32, v178
	v_mul_f32_e32 v179, v33, v179
	v_mul_f32_e32 v148, 0x3e000000, v148
	v_mul_f32_e32 v149, 0x3e000000, v149
	v_mul_f32_e32 v150, 0x3e000000, v150
	v_mul_f32_e32 v151, 0x3e000000, v151
	v_mul_f32_e32 v152, 0x3e000000, v152
	v_mul_f32_e32 v153, 0x3e000000, v153
	v_mul_f32_e32 v154, 0x3e000000, v154
	v_mul_f32_e32 v155, 0x3e000000, v155
	v_mul_f32_e32 v156, 0x3e000000, v156
	v_mul_f32_e32 v157, 0x3e000000, v157
	v_mul_f32_e32 v158, 0x3e000000, v158
	v_mul_f32_e32 v159, 0x3e000000, v159
	v_mul_f32_e32 v160, 0x3e000000, v160
	v_mul_f32_e32 v161, 0x3e000000, v161
	v_mul_f32_e32 v162, 0x3e000000, v162
	v_mul_f32_e32 v163, 0x3e000000, v163
	v_mul_f32_e32 v148, v148, v236
	v_mul_f32_e32 v149, v149, v237
	v_mul_f32_e32 v150, v150, v238
	v_mul_f32_e32 v151, v151, v239
	v_mul_f32_e32 v152, v152, v240
	v_mul_f32_e32 v153, v153, v241
	v_mul_f32_e32 v154, v154, v242
	v_mul_f32_e32 v155, v155, v243
	v_mul_f32_e32 v156, v156, v244
	v_mul_f32_e32 v157, v157, v245
	v_mul_f32_e32 v158, v158, v246
	v_mul_f32_e32 v159, v159, v247
	v_mul_f32_e32 v160, v160, v248
	v_mul_f32_e32 v161, v161, v249
	v_mul_f32_e32 v162, v162, v250
	v_mul_f32_e32 v163, v163, v251
	v_cvt_pk_bf16_f32 v164, v164, v164
	v_cvt_pk_bf16_f32 v165, v165, v165
	v_cvt_pk_bf16_f32 v166, v166, v166
	v_cvt_pk_bf16_f32 v167, v167, v167
	v_cvt_pk_bf16_f32 v168, v168, v168
	v_cvt_pk_bf16_f32 v169, v169, v169
	v_cvt_pk_bf16_f32 v170, v170, v170
	v_cvt_pk_bf16_f32 v171, v171, v171
	v_cvt_pk_bf16_f32 v172, v172, v172
	v_cvt_pk_bf16_f32 v173, v173, v173
	v_cvt_pk_bf16_f32 v174, v174, v174
	v_cvt_pk_bf16_f32 v175, v175, v175
	v_cvt_pk_bf16_f32 v176, v176, v176
	v_cvt_pk_bf16_f32 v177, v177, v177
	v_cvt_pk_bf16_f32 v178, v178, v178
	v_cvt_pk_bf16_f32 v179, v179, v179
	v_cvt_pk_bf16_f32 v148, v148, v148
	v_cvt_pk_bf16_f32 v149, v149, v149
	v_cvt_pk_bf16_f32 v150, v150, v150
	v_cvt_pk_bf16_f32 v151, v151, v151
	v_cvt_pk_bf16_f32 v152, v152, v152
	v_cvt_pk_bf16_f32 v153, v153, v153
	v_cvt_pk_bf16_f32 v154, v154, v154
	v_cvt_pk_bf16_f32 v155, v155, v155
	v_cvt_pk_bf16_f32 v156, v156, v156
	v_cvt_pk_bf16_f32 v157, v157, v157
	v_cvt_pk_bf16_f32 v158, v158, v158
	v_cvt_pk_bf16_f32 v159, v159, v159
	v_cvt_pk_bf16_f32 v160, v160, v160
	v_cvt_pk_bf16_f32 v161, v161, v161
	v_cvt_pk_bf16_f32 v162, v162, v162
	v_cvt_pk_bf16_f32 v163, v163, v163
	ds_write_b16 v60, v164
	v_add_u32_e32 v60, v61, v60
	global_store_short v134, v148, s[4:5]
	global_store_short v134, v164, s[4:5] offset:512
	s_add_u32 s4, s4, s56
	s_addc_u32 s5, s5, s3
	ds_write_b16 v60, v165
	v_add_u32_e32 v60, v61, v60
	global_store_short v134, v149, s[4:5]
	global_store_short v134, v165, s[4:5] offset:512
	s_add_u32 s4, s4, s56
	s_addc_u32 s5, s5, s3
	ds_write_b16 v60, v166
	v_add_u32_e32 v60, v61, v60
	global_store_short v134, v150, s[4:5]
	global_store_short v134, v166, s[4:5] offset:512
	s_add_u32 s4, s4, s56
	s_addc_u32 s5, s5, s3
	ds_write_b16 v60, v167
	v_add_u32_e32 v60, v61, v60
	global_store_short v134, v151, s[4:5]
	global_store_short v134, v167, s[4:5] offset:512
	s_add_u32 s4, s4, s56
	s_addc_u32 s5, s5, s3
	ds_write_b16 v60, v168
	v_add_u32_e32 v60, v61, v60
	global_store_short v134, v152, s[4:5]
	global_store_short v134, v168, s[4:5] offset:512
	s_add_u32 s4, s4, s56
	s_addc_u32 s5, s5, s3
	ds_write_b16 v60, v169
	v_add_u32_e32 v60, v61, v60
	global_store_short v134, v153, s[4:5]
	global_store_short v134, v169, s[4:5] offset:512
	s_add_u32 s4, s4, s56
	s_addc_u32 s5, s5, s3
	ds_write_b16 v60, v170
	v_add_u32_e32 v60, v61, v60
	global_store_short v134, v154, s[4:5]
	global_store_short v134, v170, s[4:5] offset:512
	s_add_u32 s4, s4, s56
	s_addc_u32 s5, s5, s3
	ds_write_b16 v60, v171
	v_add_u32_e32 v60, v61, v60
	global_store_short v134, v155, s[4:5]
	global_store_short v134, v171, s[4:5] offset:512
	s_add_u32 s4, s4, s56
	s_addc_u32 s5, s5, s3
	ds_write_b16 v60, v172
	v_add_u32_e32 v60, v61, v60
	global_store_short v134, v156, s[4:5]
	global_store_short v134, v172, s[4:5] offset:512
	s_add_u32 s4, s4, s56
	s_addc_u32 s5, s5, s3
	ds_write_b16 v60, v173
	v_add_u32_e32 v60, v61, v60
	global_store_short v134, v157, s[4:5]
	global_store_short v134, v173, s[4:5] offset:512
	s_add_u32 s4, s4, s56
	s_addc_u32 s5, s5, s3
	ds_write_b16 v60, v174
	v_add_u32_e32 v60, v61, v60
	global_store_short v134, v158, s[4:5]
	global_store_short v134, v174, s[4:5] offset:512
	s_add_u32 s4, s4, s56
	s_addc_u32 s5, s5, s3
	ds_write_b16 v60, v175
	v_add_u32_e32 v60, v61, v60
	global_store_short v134, v159, s[4:5]
	global_store_short v134, v175, s[4:5] offset:512
	s_add_u32 s4, s4, s56
	s_addc_u32 s5, s5, s3
	ds_write_b16 v60, v176
	v_add_u32_e32 v60, v61, v60
	global_store_short v134, v160, s[4:5]
	global_store_short v134, v176, s[4:5] offset:512
	s_add_u32 s4, s4, s56
	s_addc_u32 s5, s5, s3
	ds_write_b16 v60, v177
	v_add_u32_e32 v60, v61, v60
	global_store_short v134, v161, s[4:5]
	global_store_short v134, v177, s[4:5] offset:512
	s_add_u32 s4, s4, s56
	s_addc_u32 s5, s5, s3
	ds_write_b16 v60, v178
	v_add_u32_e32 v60, v61, v60
	global_store_short v134, v162, s[4:5]
	global_store_short v134, v178, s[4:5] offset:512
	s_add_u32 s4, s4, s56
	s_addc_u32 s5, s5, s3
	ds_write_b16 v60, v179
	v_add_u32_e32 v60, v61, v60
	global_store_short v134, v163, s[4:5]
	global_store_short v134, v179, s[4:5] offset:512
	s_add_u32 s4, s4, s56
	s_addc_u32 s5, s5, s3
	v_mov_b32_e32 v236, v16
	v_dot2c_f32_bf16_dpp v236, v106, v8 row_newbcast:0 row_mask:0xf bank_mask:0xf
	v_dot2c_f32_bf16_dpp v236, v107, v9 row_newbcast:0 row_mask:0xf bank_mask:0xf
	v_dot2c_f32_bf16_dpp v236, v108, v10 row_newbcast:0 row_mask:0xf bank_mask:0xf
; __device__ __forceinline__ void gl1_item(PREF p, int l, int item, bool valid, LAS unsigned char* pl, int sw, int lane) {
;     ...
;             for (int ss = 0; ss < 16; ++ss) { const int s = g4 * 16 + ss; const int i = d ? 63 - s : s;
;                 float z = bup;
; #pragma unroll
;                 for (int r2 = 0; r2 < 8; ++r2) { const unsigned w = (unsigned)__builtin_amdgcn_readlane((int)lrp[r2], i);
;                     z = __builtin_amdgcn_fdot2_f32_bf16(__builtin_bit_cast(bf16x2_t, w), __builtin_bit_cast(bf16x2_t, wupp[r2]), z, false); }
	v_dot2c_f32_bf16_dpp v236, v109, v11 row_newbcast:0 row_mask:0xf bank_mask:0xf
	v_dot2c_f32_bf16_dpp v236, v110, v12 row_newbcast:0 row_mask:0xf bank_mask:0xf
	v_dot2c_f32_bf16_dpp v236, v111, v13 row_newbcast:0 row_mask:0xf bank_mask:0xf
	v_dot2c_f32_bf16_dpp v236, v112, v14 row_newbcast:0 row_mask:0xf bank_mask:0xf
	v_dot2c_f32_bf16_dpp v236, v113, v15 row_newbcast:0 row_mask:0xf bank_mask:0xf
	v_mov_b32_e32 v237, v16
	v_dot2c_f32_bf16_dpp v237, v106, v8 row_newbcast:1 row_mask:0xf bank_mask:0xf
	v_dot2c_f32_bf16_dpp v237, v107, v9 row_newbcast:1 row_mask:0xf bank_mask:0xf
	v_dot2c_f32_bf16_dpp v237, v108, v10 row_newbcast:1 row_mask:0xf bank_mask:0xf
	v_dot2c_f32_bf16_dpp v237, v109, v11 row_newbcast:1 row_mask:0xf bank_mask:0xf
	v_dot2c_f32_bf16_dpp v237, v110, v12 row_newbcast:1 row_mask:0xf bank_mask:0xf
	v_dot2c_f32_bf16_dpp v237, v111, v13 row_newbcast:1 row_mask:0xf bank_mask:0xf
	v_dot2c_f32_bf16_dpp v237, v112, v14 row_newbcast:1 row_mask:0xf bank_mask:0xf
	v_dot2c_f32_bf16_dpp v237, v113, v15 row_newbcast:1 row_mask:0xf bank_mask:0xf
	v_mov_b32_e32 v238, v16
	v_dot2c_f32_bf16_dpp v238, v106, v8 row_newbcast:2 row_mask:0xf bank_mask:0xf
	v_dot2c_f32_bf16_dpp v238, v107, v9 row_newbcast:2 row_mask:0xf bank_mask:0xf
	v_dot2c_f32_bf16_dpp v238, v108, v10 row_newbcast:2 row_mask:0xf bank_mask:0xf
	v_dot2c_f32_bf16_dpp v238, v109, v11 row_newbcast:2 row_mask:0xf bank_mask:0xf
	v_dot2c_f32_bf16_dpp v238, v110, v12 row_newbcast:2 row_mask:0xf bank_mask:0xf
	v_dot2c_f32_bf16_dpp v238, v111, v13 row_newbcast:2 row_mask:0xf bank_mask:0xf
	v_dot2c_f32_bf16_dpp v238, v112, v14 row_newbcast:2 row_mask:0xf bank_mask:0xf
	v_dot2c_f32_bf16_dpp v238, v113, v15 row_newbcast:2 row_mask:0xf bank_mask:0xf
	v_mov_b32_e32 v239, v16
	v_dot2c_f32_bf16_dpp v239, v106, v8 row_newbcast:3 row_mask:0xf bank_mask:0xf
	v_dot2c_f32_bf16_dpp v239, v107, v9 row_newbcast:3 row_mask:0xf bank_mask:0xf
	v_dot2c_f32_bf16_dpp v239, v108, v10 row_newbcast:3 row_mask:0xf bank_mask:0xf
	v_dot2c_f32_bf16_dpp v239, v109, v11 row_newbcast:3 row_mask:0xf bank_mask:0xf
	v_dot2c_f32_bf16_dpp v239, v110, v12 row_newbcast:3 row_mask:0xf bank_mask:0xf
	v_dot2c_f32_bf16_dpp v239, v111, v13 row_newbcast:3 row_mask:0xf bank_mask:0xf
	v_dot2c_f32_bf16_dpp v239, v112, v14 row_newbcast:3 row_mask:0xf bank_mask:0xf
	v_dot2c_f32_bf16_dpp v239, v113, v15 row_newbcast:3 row_mask:0xf bank_mask:0xf
	v_mov_b32_e32 v240, v16
	v_dot2c_f32_bf16_dpp v240, v106, v8 row_newbcast:4 row_mask:0xf bank_mask:0xf
	v_dot2c_f32_bf16_dpp v240, v107, v9 row_newbcast:4 row_mask:0xf bank_mask:0xf
	v_dot2c_f32_bf16_dpp v240, v108, v10 row_newbcast:4 row_mask:0xf bank_mask:0xf
	v_dot2c_f32_bf16_dpp v240, v109, v11 row_newbcast:4 row_mask:0xf bank_mask:0xf
	v_dot2c_f32_bf16_dpp v240, v110, v12 row_newbcast:4 row_mask:0xf bank_mask:0xf
	v_dot2c_f32_bf16_dpp v240, v111, v13 row_newbcast:4 row_mask:0xf bank_mask:0xf
	v_dot2c_f32_bf16_dpp v240, v112, v14 row_newbcast:4 row_mask:0xf bank_mask:0xf
	v_dot2c_f32_bf16_dpp v240, v113, v15 row_newbcast:4 row_mask:0xf bank_mask:0xf
	v_mov_b32_e32 v241, v16
	v_dot2c_f32_bf16_dpp v241, v106, v8 row_newbcast:5 row_mask:0xf bank_mask:0xf
	v_dot2c_f32_bf16_dpp v241, v107, v9 row_newbcast:5 row_mask:0xf bank_mask:0xf
	v_dot2c_f32_bf16_dpp v241, v108, v10 row_newbcast:5 row_mask:0xf bank_mask:0xf
	v_dot2c_f32_bf16_dpp v241, v109, v11 row_newbcast:5 row_mask:0xf bank_mask:0xf
	v_dot2c_f32_bf16_dpp v241, v110, v12 row_newbcast:5 row_mask:0xf bank_mask:0xf
	v_dot2c_f32_bf16_dpp v241, v111, v13 row_newbcast:5 row_mask:0xf bank_mask:0xf
	v_dot2c_f32_bf16_dpp v241, v112, v14 row_newbcast:5 row_mask:0xf bank_mask:0xf
	v_dot2c_f32_bf16_dpp v241, v113, v15 row_newbcast:5 row_mask:0xf bank_mask:0xf
	v_mov_b32_e32 v242, v16
	v_dot2c_f32_bf16_dpp v242, v106, v8 row_newbcast:6 row_mask:0xf bank_mask:0xf
	v_dot2c_f32_bf16_dpp v242, v107, v9 row_newbcast:6 row_mask:0xf bank_mask:0xf
	v_dot2c_f32_bf16_dpp v242, v108, v10 row_newbcast:6 row_mask:0xf bank_mask:0xf
	v_dot2c_f32_bf16_dpp v242, v109, v11 row_newbcast:6 row_mask:0xf bank_mask:0xf
	v_dot2c_f32_bf16_dpp v242, v110, v12 row_newbcast:6 row_mask:0xf bank_mask:0xf
	v_dot2c_f32_bf16_dpp v242, v111, v13 row_newbcast:6 row_mask:0xf bank_mask:0xf
	v_dot2c_f32_bf16_dpp v242, v112, v14 row_newbcast:6 row_mask:0xf bank_mask:0xf
	v_dot2c_f32_bf16_dpp v242, v113, v15 row_newbcast:6 row_mask:0xf bank_mask:0xf
	v_mov_b32_e32 v243, v16
	v_dot2c_f32_bf16_dpp v243, v106, v8 row_newbcast:7 row_mask:0xf bank_mask:0xf
	v_dot2c_f32_bf16_dpp v243, v107, v9 row_newbcast:7 row_mask:0xf bank_mask:0xf
	v_dot2c_f32_bf16_dpp v243, v108, v10 row_newbcast:7 row_mask:0xf bank_mask:0xf
	v_dot2c_f32_bf16_dpp v243, v109, v11 row_newbcast:7 row_mask:0xf bank_mask:0xf
	v_dot2c_f32_bf16_dpp v243, v110, v12 row_newbcast:7 row_mask:0xf bank_mask:0xf
	v_dot2c_f32_bf16_dpp v243, v111, v13 row_newbcast:7 row_mask:0xf bank_mask:0xf
	v_dot2c_f32_bf16_dpp v243, v112, v14 row_newbcast:7 row_mask:0xf bank_mask:0xf
	v_dot2c_f32_bf16_dpp v243, v113, v15 row_newbcast:7 row_mask:0xf bank_mask:0xf
	v_mov_b32_e32 v244, v16
	v_dot2c_f32_bf16_dpp v244, v106, v8 row_newbcast:8 row_mask:0xf bank_mask:0xf
	v_dot2c_f32_bf16_dpp v244, v107, v9 row_newbcast:8 row_mask:0xf bank_mask:0xf
	v_dot2c_f32_bf16_dpp v244, v108, v10 row_newbcast:8 row_mask:0xf bank_mask:0xf
	v_dot2c_f32_bf16_dpp v244, v109, v11 row_newbcast:8 row_mask:0xf bank_mask:0xf
	v_dot2c_f32_bf16_dpp v244, v110, v12 row_newbcast:8 row_mask:0xf bank_mask:0xf
	v_dot2c_f32_bf16_dpp v244, v111, v13 row_newbcast:8 row_mask:0xf bank_mask:0xf
	v_dot2c_f32_bf16_dpp v244, v112, v14 row_newbcast:8 row_mask:0xf bank_mask:0xf
; __device__ __forceinline__ void gl1_item(PREF p, int l, int item, bool valid, LAS unsigned char* pl, int sw, int lane) {
;     ...
;             for (int ss = 0; ss < 16; ++ss) { const int s = g4 * 16 + ss; const int i = d ? 63 - s : s;
;                 float z = bup;
; #pragma unroll
;                 for (int r2 = 0; r2 < 8; ++r2) { const unsigned w = (unsigned)__builtin_amdgcn_readlane((int)lrp[r2], i);
;                     z = __builtin_amdgcn_fdot2_f32_bf16(__builtin_bit_cast(bf16x2_t, w), __builtin_bit_cast(bf16x2_t, wupp[r2]), z, false); }
	v_dot2c_f32_bf16_dpp v244, v113, v15 row_newbcast:8 row_mask:0xf bank_mask:0xf
	v_mov_b32_e32 v245, v16
	v_dot2c_f32_bf16_dpp v245, v106, v8 row_newbcast:9 row_mask:0xf bank_mask:0xf
	v_dot2c_f32_bf16_dpp v245, v107, v9 row_newbcast:9 row_mask:0xf bank_mask:0xf
	v_dot2c_f32_bf16_dpp v245, v108, v10 row_newbcast:9 row_mask:0xf bank_mask:0xf
	v_dot2c_f32_bf16_dpp v245, v109, v11 row_newbcast:9 row_mask:0xf bank_mask:0xf
	v_dot2c_f32_bf16_dpp v245, v110, v12 row_newbcast:9 row_mask:0xf bank_mask:0xf
	v_dot2c_f32_bf16_dpp v245, v111, v13 row_newbcast:9 row_mask:0xf bank_mask:0xf
	v_dot2c_f32_bf16_dpp v245, v112, v14 row_newbcast:9 row_mask:0xf bank_mask:0xf
	v_dot2c_f32_bf16_dpp v245, v113, v15 row_newbcast:9 row_mask:0xf bank_mask:0xf
	v_mov_b32_e32 v246, v16
	v_dot2c_f32_bf16_dpp v246, v106, v8 row_newbcast:10 row_mask:0xf bank_mask:0xf
	v_dot2c_f32_bf16_dpp v246, v107, v9 row_newbcast:10 row_mask:0xf bank_mask:0xf
	v_dot2c_f32_bf16_dpp v246, v108, v10 row_newbcast:10 row_mask:0xf bank_mask:0xf
	v_dot2c_f32_bf16_dpp v246, v109, v11 row_newbcast:10 row_mask:0xf bank_mask:0xf
	v_dot2c_f32_bf16_dpp v246, v110, v12 row_newbcast:10 row_mask:0xf bank_mask:0xf
	v_dot2c_f32_bf16_dpp v246, v111, v13 row_newbcast:10 row_mask:0xf bank_mask:0xf
	v_dot2c_f32_bf16_dpp v246, v112, v14 row_newbcast:10 row_mask:0xf bank_mask:0xf
	v_dot2c_f32_bf16_dpp v246, v113, v15 row_newbcast:10 row_mask:0xf bank_mask:0xf
	v_mov_b32_e32 v247, v16
	v_dot2c_f32_bf16_dpp v247, v106, v8 row_newbcast:11 row_mask:0xf bank_mask:0xf
	v_dot2c_f32_bf16_dpp v247, v107, v9 row_newbcast:11 row_mask:0xf bank_mask:0xf
	v_dot2c_f32_bf16_dpp v247, v108, v10 row_newbcast:11 row_mask:0xf bank_mask:0xf
	v_dot2c_f32_bf16_dpp v247, v109, v11 row_newbcast:11 row_mask:0xf bank_mask:0xf
	v_dot2c_f32_bf16_dpp v247, v110, v12 row_newbcast:11 row_mask:0xf bank_mask:0xf
	v_dot2c_f32_bf16_dpp v247, v111, v13 row_newbcast:11 row_mask:0xf bank_mask:0xf
	v_dot2c_f32_bf16_dpp v247, v112, v14 row_newbcast:11 row_mask:0xf bank_mask:0xf
	v_dot2c_f32_bf16_dpp v247, v113, v15 row_newbcast:11 row_mask:0xf bank_mask:0xf
	v_mov_b32_e32 v248, v16
	v_dot2c_f32_bf16_dpp v248, v106, v8 row_newbcast:12 row_mask:0xf bank_mask:0xf
	v_dot2c_f32_bf16_dpp v248, v107, v9 row_newbcast:12 row_mask:0xf bank_mask:0xf
	v_dot2c_f32_bf16_dpp v248, v108, v10 row_newbcast:12 row_mask:0xf bank_mask:0xf
	v_dot2c_f32_bf16_dpp v248, v109, v11 row_newbcast:12 row_mask:0xf bank_mask:0xf
	v_dot2c_f32_bf16_dpp v248, v110, v12 row_newbcast:12 row_mask:0xf bank_mask:0xf
	v_dot2c_f32_bf16_dpp v248, v111, v13 row_newbcast:12 row_mask:0xf bank_mask:0xf
	v_dot2c_f32_bf16_dpp v248, v112, v14 row_newbcast:12 row_mask:0xf bank_mask:0xf
	v_dot2c_f32_bf16_dpp v248, v113, v15 row_newbcast:12 row_mask:0xf bank_mask:0xf
	v_mov_b32_e32 v249, v16
	v_dot2c_f32_bf16_dpp v249, v106, v8 row_newbcast:13 row_mask:0xf bank_mask:0xf
	v_dot2c_f32_bf16_dpp v249, v107, v9 row_newbcast:13 row_mask:0xf bank_mask:0xf
	v_dot2c_f32_bf16_dpp v249, v108, v10 row_newbcast:13 row_mask:0xf bank_mask:0xf
	v_dot2c_f32_bf16_dpp v249, v109, v11 row_newbcast:13 row_mask:0xf bank_mask:0xf
	v_dot2c_f32_bf16_dpp v249, v110, v12 row_newbcast:13 row_mask:0xf bank_mask:0xf
	v_dot2c_f32_bf16_dpp v249, v111, v13 row_newbcast:13 row_mask:0xf bank_mask:0xf
	v_dot2c_f32_bf16_dpp v249, v112, v14 row_newbcast:13 row_mask:0xf bank_mask:0xf
	v_dot2c_f32_bf16_dpp v249, v113, v15 row_newbcast:13 row_mask:0xf bank_mask:0xf
	v_mov_b32_e32 v250, v16
	v_dot2c_f32_bf16_dpp v250, v106, v8 row_newbcast:14 row_mask:0xf bank_mask:0xf
	v_dot2c_f32_bf16_dpp v250, v107, v9 row_newbcast:14 row_mask:0xf bank_mask:0xf
	v_dot2c_f32_bf16_dpp v250, v108, v10 row_newbcast:14 row_mask:0xf bank_mask:0xf
	v_dot2c_f32_bf16_dpp v250, v109, v11 row_newbcast:14 row_mask:0xf bank_mask:0xf
	v_dot2c_f32_bf16_dpp v250, v110, v12 row_newbcast:14 row_mask:0xf bank_mask:0xf
	v_dot2c_f32_bf16_dpp v250, v111, v13 row_newbcast:14 row_mask:0xf bank_mask:0xf
	v_dot2c_f32_bf16_dpp v250, v112, v14 row_newbcast:14 row_mask:0xf bank_mask:0xf
	v_dot2c_f32_bf16_dpp v250, v113, v15 row_newbcast:14 row_mask:0xf bank_mask:0xf
	v_mov_b32_e32 v251, v16
	v_dot2c_f32_bf16_dpp v251, v106, v8 row_newbcast:15 row_mask:0xf bank_mask:0xf
	v_dot2c_f32_bf16_dpp v251, v107, v9 row_newbcast:15 row_mask:0xf bank_mask:0xf
	v_dot2c_f32_bf16_dpp v251, v108, v10 row_newbcast:15 row_mask:0xf bank_mask:0xf
	v_dot2c_f32_bf16_dpp v251, v109, v11 row_newbcast:15 row_mask:0xf bank_mask:0xf
	v_dot2c_f32_bf16_dpp v251, v110, v12 row_newbcast:15 row_mask:0xf bank_mask:0xf
	v_dot2c_f32_bf16_dpp v251, v111, v13 row_newbcast:15 row_mask:0xf bank_mask:0xf
	v_dot2c_f32_bf16_dpp v251, v112, v14 row_newbcast:15 row_mask:0xf bank_mask:0xf
	v_dot2c_f32_bf16_dpp v251, v113, v15 row_newbcast:15 row_mask:0xf bank_mask:0xf
	s_nop 2
	v_mul_f32_e64 v18, |v236|, s1
	v_mul_f32_e64 v19, |v237|, s1
	v_mul_f32_e64 v20, |v238|, s1
	v_mul_f32_e64 v21, |v239|, s1
	v_mul_f32_e64 v22, |v240|, s1
	v_mul_f32_e64 v23, |v241|, s1
	v_mul_f32_e64 v24, |v242|, s1
	v_mul_f32_e64 v25, |v243|, s1
	v_mul_f32_e64 v26, |v244|, s1
	v_mul_f32_e64 v27, |v245|, s1
	v_mul_f32_e64 v28, |v246|, s1
	v_mul_f32_e64 v29, |v247|, s1
	v_mul_f32_e64 v30, |v248|, s1
	v_mul_f32_e64 v31, |v249|, s1
	v_mul_f32_e64 v32, |v250|, s1
	v_mul_f32_e64 v33, |v251|, s1
	v_exp_f32_e32 v18, v18
	v_exp_f32_e32 v19, v19
	v_exp_f32_e32 v20, v20
	v_exp_f32_e32 v21, v21
	v_exp_f32_e32 v22, v22
	v_exp_f32_e32 v23, v23
	v_exp_f32_e32 v24, v24
	v_exp_f32_e32 v25, v25
	v_exp_f32_e32 v26, v26
	v_exp_f32_e32 v27, v27
	v_exp_f32_e32 v28, v28
	v_exp_f32_e32 v29, v29
	v_exp_f32_e32 v30, v30
	v_exp_f32_e32 v31, v31
	v_exp_f32_e32 v32, v32
; __device__ __forceinline__ void gl1_item(PREF p, int l, int item, bool valid, LAS unsigned char* pl, int sw, int lane) {
;     ...
;                 for (int r2 = 0; r2 < 8; ++r2) { const unsigned w = (unsigned)__builtin_amdgcn_readlane((int)lrp[r2], i);
;                     z = __builtin_amdgcn_fdot2_f32_bf16(__builtin_bit_cast(bf16x2_t, w), __builtin_bit_cast(bf16x2_t, wupp[r2]), z, false); }
;                 gv[ss] = -(fmaxf(-z, 0.f) + __logf(1.f + __expf(-fabsf(z)))) * (1.f / 16.f);
;                 __builtin_amdgcn_sched_barrier(0);
;             }
; #pragma unroll
;             for (int ss = 0; ss < 16; ++ss) { const int s = g4 * 16 + ss; const int i = d ? 63 - s : s; const size_t rowi = (size_t)(row0 + i * rstride);
;                 bc += gv[ss];
	v_exp_f32_e32 v33, v33
	v_max_f32_e64 v236, -v236, -v236
	v_max_f32_e64 v237, -v237, -v237
	v_max_f32_e64 v238, -v238, -v238
	v_max_f32_e64 v239, -v239, -v239
	v_max_f32_e64 v240, -v240, -v240
	v_max_f32_e64 v241, -v241, -v241
	v_max_f32_e64 v242, -v242, -v242
	v_max_f32_e64 v243, -v243, -v243
	v_max_f32_e64 v244, -v244, -v244
	v_max_f32_e64 v245, -v245, -v245
	v_max_f32_e64 v246, -v246, -v246
	v_max_f32_e64 v247, -v247, -v247
	v_max_f32_e64 v248, -v248, -v248
	v_max_f32_e64 v249, -v249, -v249
	v_max_f32_e64 v250, -v250, -v250
	v_max_f32_e64 v251, -v251, -v251
	v_max_f32_e32 v236, 0, v236
	v_max_f32_e32 v237, 0, v237
	v_max_f32_e32 v238, 0, v238
	v_max_f32_e32 v239, 0, v239
	v_max_f32_e32 v240, 0, v240
	v_max_f32_e32 v241, 0, v241
	v_max_f32_e32 v242, 0, v242
	v_max_f32_e32 v243, 0, v243
	v_max_f32_e32 v244, 0, v244
	v_max_f32_e32 v245, 0, v245
	v_max_f32_e32 v246, 0, v246
	v_max_f32_e32 v247, 0, v247
	v_max_f32_e32 v248, 0, v248
	v_max_f32_e32 v249, 0, v249
	v_max_f32_e32 v250, 0, v250
	v_max_f32_e32 v251, 0, v251
	v_add_f32_e32 v18, 1.0, v18
	v_add_f32_e32 v19, 1.0, v19
	v_add_f32_e32 v20, 1.0, v20
	v_add_f32_e32 v21, 1.0, v21
	v_add_f32_e32 v22, 1.0, v22
	v_add_f32_e32 v23, 1.0, v23
	v_add_f32_e32 v24, 1.0, v24
	v_add_f32_e32 v25, 1.0, v25
	v_add_f32_e32 v26, 1.0, v26
	v_add_f32_e32 v27, 1.0, v27
	v_add_f32_e32 v28, 1.0, v28
	v_add_f32_e32 v29, 1.0, v29
	v_add_f32_e32 v30, 1.0, v30
	v_add_f32_e32 v31, 1.0, v31
	v_add_f32_e32 v32, 1.0, v32
	v_add_f32_e32 v33, 1.0, v33
	v_log_f32_e32 v18, v18
	v_log_f32_e32 v19, v19
	v_log_f32_e32 v20, v20
	v_log_f32_e32 v21, v21
	v_log_f32_e32 v22, v22
	v_log_f32_e32 v23, v23
	v_log_f32_e32 v24, v24
	v_log_f32_e32 v25, v25
	v_log_f32_e32 v26, v26
	v_log_f32_e32 v27, v27
	v_log_f32_e32 v28, v28
	v_log_f32_e32 v29, v29
	v_log_f32_e32 v30, v30
	v_log_f32_e32 v31, v31
	v_log_f32_e32 v32, v32
	v_log_f32_e32 v33, v33
	s_mov_b32 s45, 0x3f317217
	v_mul_f32_e32 v70, 0x3f317217, v18
	v_mul_f32_e32 v71, 0x3f317217, v19
	v_mul_f32_e32 v72, 0x3f317217, v20
	v_mul_f32_e32 v73, 0x3f317217, v21
	v_mul_f32_e32 v74, 0x3f317217, v22
	v_mul_f32_e32 v75, 0x3f317217, v23
	v_mul_f32_e32 v76, 0x3f317217, v24
	v_mul_f32_e32 v77, 0x3f317217, v25
	v_mul_f32_e32 v78, 0x3f317217, v26
	v_mul_f32_e32 v79, 0x3f317217, v27
	v_mul_f32_e32 v80, 0x3f317217, v28
	v_mul_f32_e32 v81, 0x3f317217, v29
	v_mul_f32_e32 v82, 0x3f317217, v30
	v_mul_f32_e32 v83, 0x3f317217, v31
	v_mul_f32_e32 v84, 0x3f317217, v32
	v_mul_f32_e32 v85, 0x3f317217, v33
	v_fma_f32 v70, v18, s45, -v70
	v_fma_f32 v71, v19, s45, -v71
	v_fma_f32 v72, v20, s45, -v72
	v_fma_f32 v73, v21, s45, -v73
	v_fma_f32 v74, v22, s45, -v74
	v_fma_f32 v75, v23, s45, -v75
	v_fma_f32 v76, v24, s45, -v76
	v_fma_f32 v77, v25, s45, -v77
	v_fma_f32 v78, v26, s45, -v78
	v_fma_f32 v79, v27, s45, -v79
	v_fma_f32 v80, v28, s45, -v80
	v_fma_f32 v81, v29, s45, -v81
	v_fma_f32 v82, v30, s45, -v82
	v_fma_f32 v83, v31, s45, -v83
	v_fma_f32 v84, v32, s45, -v84
	v_fma_f32 v85, v33, s45, -v85
	v_fmac_f32_e32 v70, 0x3377d1cf, v18
	v_fmac_f32_e32 v71, 0x3377d1cf, v19
	v_fmac_f32_e32 v72, 0x3377d1cf, v20
	v_fmac_f32_e32 v73, 0x3377d1cf, v21
	v_fmac_f32_e32 v74, 0x3377d1cf, v22
	v_fmac_f32_e32 v75, 0x3377d1cf, v23
	v_fmac_f32_e32 v76, 0x3377d1cf, v24
	v_fmac_f32_e32 v77, 0x3377d1cf, v25
	v_fmac_f32_e32 v78, 0x3377d1cf, v26
	v_fmac_f32_e32 v79, 0x3377d1cf, v27
	v_fmac_f32_e32 v80, 0x3377d1cf, v28
	v_fmac_f32_e32 v81, 0x3377d1cf, v29
	v_fmac_f32_e32 v82, 0x3377d1cf, v30
	v_fmac_f32_e32 v83, 0x3377d1cf, v31
	v_fmac_f32_e32 v84, 0x3377d1cf, v32
	v_fmac_f32_e32 v85, 0x3377d1cf, v33
	v_fmac_f32_e32 v70, 0x3f317217, v18
	v_fmac_f32_e32 v71, 0x3f317217, v19
	v_fmac_f32_e32 v72, 0x3f317217, v20
	v_fmac_f32_e32 v73, 0x3f317217, v21
	v_fmac_f32_e32 v74, 0x3f317217, v22
	v_fmac_f32_e32 v75, 0x3f317217, v23
	v_fmac_f32_e32 v76, 0x3f317217, v24
	v_fmac_f32_e32 v77, 0x3f317217, v25
	v_fmac_f32_e32 v78, 0x3f317217, v26
	v_fmac_f32_e32 v79, 0x3f317217, v27
	v_fmac_f32_e32 v80, 0x3f317217, v28
	v_fmac_f32_e32 v81, 0x3f317217, v29
	v_fmac_f32_e32 v82, 0x3f317217, v30
	v_fmac_f32_e32 v83, 0x3f317217, v31
	v_fmac_f32_e32 v84, 0x3f317217, v32
	v_fmac_f32_e32 v85, 0x3f317217, v33
	v_add_f32_e32 v236, v236, v70
	v_add_f32_e32 v237, v237, v71
	v_add_f32_e32 v238, v238, v72
	v_add_f32_e32 v239, v239, v73
	v_add_f32_e32 v240, v240, v74
	v_add_f32_e32 v241, v241, v75
	v_add_f32_e32 v242, v242, v76
	v_add_f32_e32 v243, v243, v77
	v_add_f32_e32 v244, v244, v78
	v_add_f32_e32 v245, v245, v79
	v_add_f32_e32 v246, v246, v80
	v_add_f32_e32 v247, v247, v81
	v_add_f32_e32 v248, v248, v82
	v_add_f32_e32 v249, v249, v83
	v_add_f32_e32 v250, v250, v84
	v_add_f32_e32 v251, v251, v85
	v_mov_b32_e32 v70, v17
	v_fmac_f32_e32 v70, 0xbd800000, v236
	v_mov_b32_e32 v71, v70
	v_fmac_f32_e32 v71, 0xbd800000, v237
	v_mov_b32_e32 v72, v71
	v_fmac_f32_e32 v72, 0xbd800000, v238
	v_mov_b32_e32 v73, v72
	v_fmac_f32_e32 v73, 0xbd800000, v239
	v_mov_b32_e32 v74, v73
	v_fmac_f32_e32 v74, 0xbd800000, v240
	v_mov_b32_e32 v75, v74
	v_fmac_f32_e32 v75, 0xbd800000, v241
	v_mov_b32_e32 v76, v75
	v_fmac_f32_e32 v76, 0xbd800000, v242
	v_mov_b32_e32 v77, v76
	v_fmac_f32_e32 v77, 0xbd800000, v243
	v_mov_b32_e32 v78, v77
	v_fmac_f32_e32 v78, 0xbd800000, v244
	v_mov_b32_e32 v79, v78
	v_fmac_f32_e32 v79, 0xbd800000, v245
	v_mov_b32_e32 v80, v79
	v_fmac_f32_e32 v80, 0xbd800000, v246
	v_mov_b32_e32 v81, v80
	v_fmac_f32_e32 v81, 0xbd800000, v247
	v_mov_b32_e32 v82, v81
	v_fmac_f32_e32 v82, 0xbd800000, v248
	v_mov_b32_e32 v83, v82
	v_fmac_f32_e32 v83, 0xbd800000, v249
	v_mov_b32_e32 v84, v83
	v_fmac_f32_e32 v84, 0xbd800000, v250
	v_mov_b32_e32 v85, v84
	v_fmac_f32_e32 v85, 0xbd800000, v251
	v_mov_b32_e32 v17, v85
	s_waitcnt vmcnt(32)
; __device__ __forceinline__ void gl1_item(PREF p, int l, int item, bool valid, LAS unsigned char* pl, int sw, int lane) {
;     ...
;             float qn[16], kn[16];
;             if (g4 < 3) {
; #pragma unroll
;                 for (int ss = 0; ss < 16; ++ss) { const int s = (g4 + 1) * 16 + ss; const int i = d ? 63 - s : s; const bf16_t* pr = P + (size_t)(row0 + i * rstride) * PW + h * 64 + lane;
;                     qn[ss] = __builtin_bit_cast(float, (unsigned)pr[1024]); kn[ss] = __builtin_bit_cast(float, (unsigned)pr[1280]); }
;                 __builtin_amdgcn_sched_barrier(0);
;             }
;             float gv[16];
; #pragma unroll
;             for (int ss = 0; ss < 16; ++ss) { const int s = g4 * 16 + ss; const int i = d ? 63 - s : s;
;                 float z = bup;
; #pragma unroll
;                 for (int r2 = 0; r2 < 8; ++r2) { const unsigned w = (unsigned)__builtin_amdgcn_readlane((int)lrp[r2], i);
;                     z = __builtin_amdgcn_fdot2_f32_bf16(__builtin_bit_cast(bf16x2_t, w), __builtin_bit_cast(bf16x2_t, wupp[r2]), z, false); }
;                 gv[ss] = -(fmaxf(-z, 0.f) + __logf(1.f + __expf(-fabsf(z)))) * (1.f / 16.f);
;                 __builtin_amdgcn_sched_barrier(0);
;             }
; #pragma unroll
;             for (int ss = 0; ss < 16; ++ss) { const int s = g4 * 16 + ss; const int i = d ? 63 - s : s; const size_t rowi = (size_t)(row0 + i * rstride);
;                 bc += gv[ss];
;                 const float en = __expf(-bc), ep = __expf(bc);
;                 const float kt = kc[ss] * en, qt = qc[ss] * 0.125f * ep;
	global_load_ushort v148, v134, s[6:7]
	global_load_ushort v164, v134, s[6:7] offset:512
	s_add_u32 s6, s6, s54
	s_addc_u32 s7, s7, s55
	global_load_ushort v149, v134, s[6:7]
	global_load_ushort v165, v134, s[6:7] offset:512
	s_add_u32 s6, s6, s54
	s_addc_u32 s7, s7, s55
	global_load_ushort v150, v134, s[6:7]
	global_load_ushort v166, v134, s[6:7] offset:512
	s_add_u32 s6, s6, s54
	s_addc_u32 s7, s7, s55
	global_load_ushort v151, v134, s[6:7]
	global_load_ushort v167, v134, s[6:7] offset:512
	s_add_u32 s6, s6, s54
	s_addc_u32 s7, s7, s55
	global_load_ushort v152, v134, s[6:7]
	global_load_ushort v168, v134, s[6:7] offset:512
	s_add_u32 s6, s6, s54
	s_addc_u32 s7, s7, s55
	global_load_ushort v153, v134, s[6:7]
	global_load_ushort v169, v134, s[6:7] offset:512
	s_add_u32 s6, s6, s54
	s_addc_u32 s7, s7, s55
	global_load_ushort v154, v134, s[6:7]
	global_load_ushort v170, v134, s[6:7] offset:512
	s_add_u32 s6, s6, s54
	s_addc_u32 s7, s7, s55
	global_load_ushort v155, v134, s[6:7]
	global_load_ushort v171, v134, s[6:7] offset:512
	s_add_u32 s6, s6, s54
	s_addc_u32 s7, s7, s55
	global_load_ushort v156, v134, s[6:7]
	global_load_ushort v172, v134, s[6:7] offset:512
	s_add_u32 s6, s6, s54
	s_addc_u32 s7, s7, s55
	global_load_ushort v157, v134, s[6:7]
	global_load_ushort v173, v134, s[6:7] offset:512
	s_add_u32 s6, s6, s54
	s_addc_u32 s7, s7, s55
	global_load_ushort v158, v134, s[6:7]
	global_load_ushort v174, v134, s[6:7] offset:512
	s_add_u32 s6, s6, s54
	s_addc_u32 s7, s7, s55
	global_load_ushort v159, v134, s[6:7]
	global_load_ushort v175, v134, s[6:7] offset:512
	s_add_u32 s6, s6, s54
	s_addc_u32 s7, s7, s55
	global_load_ushort v160, v134, s[6:7]
	global_load_ushort v176, v134, s[6:7] offset:512
	s_add_u32 s6, s6, s54
	s_addc_u32 s7, s7, s55
	global_load_ushort v161, v134, s[6:7]
	global_load_ushort v177, v134, s[6:7] offset:512
	s_add_u32 s6, s6, s54
	s_addc_u32 s7, s7, s55
	global_load_ushort v162, v134, s[6:7]
	global_load_ushort v178, v134, s[6:7] offset:512
	s_add_u32 s6, s6, s54
	s_addc_u32 s7, s7, s55
	global_load_ushort v163, v134, s[6:7]
	global_load_ushort v179, v134, s[6:7] offset:512
	s_add_u32 s6, s6, s54
	s_addc_u32 s7, s7, s55
	v_mul_f32_e32 v18, 0xbfb8aa3b, v70
	v_mul_f32_e32 v19, 0xbfb8aa3b, v71
	v_mul_f32_e32 v20, 0xbfb8aa3b, v72
	v_mul_f32_e32 v21, 0xbfb8aa3b, v73
	v_mul_f32_e32 v22, 0xbfb8aa3b, v74
	v_mul_f32_e32 v23, 0xbfb8aa3b, v75
	v_mul_f32_e32 v24, 0xbfb8aa3b, v76
	v_mul_f32_e32 v25, 0xbfb8aa3b, v77
	v_mul_f32_e32 v26, 0xbfb8aa3b, v78
	v_mul_f32_e32 v27, 0xbfb8aa3b, v79
	v_mul_f32_e32 v28, 0xbfb8aa3b, v80
	v_mul_f32_e32 v29, 0xbfb8aa3b, v81
	v_mul_f32_e32 v30, 0xbfb8aa3b, v82
	v_mul_f32_e32 v31, 0xbfb8aa3b, v83
	v_mul_f32_e32 v32, 0xbfb8aa3b, v84
	v_mul_f32_e32 v33, 0xbfb8aa3b, v85
	v_mul_f32_e32 v236, 0x3fb8aa3b, v70
	v_mul_f32_e32 v237, 0x3fb8aa3b, v71
	v_mul_f32_e32 v238, 0x3fb8aa3b, v72
	v_mul_f32_e32 v239, 0x3fb8aa3b, v73
	v_mul_f32_e32 v240, 0x3fb8aa3b, v74
	v_mul_f32_e32 v241, 0x3fb8aa3b, v75
	v_mul_f32_e32 v242, 0x3fb8aa3b, v76
	v_mul_f32_e32 v243, 0x3fb8aa3b, v77
	v_mul_f32_e32 v244, 0x3fb8aa3b, v78
	v_mul_f32_e32 v245, 0x3fb8aa3b, v79
	v_mul_f32_e32 v246, 0x3fb8aa3b, v80
	v_mul_f32_e32 v247, 0x3fb8aa3b, v81
	v_mul_f32_e32 v248, 0x3fb8aa3b, v82
	v_mul_f32_e32 v249, 0x3fb8aa3b, v83
	v_mul_f32_e32 v250, 0x3fb8aa3b, v84
	v_mul_f32_e32 v251, 0x3fb8aa3b, v85
	v_exp_f32_e32 v18, v18
	v_exp_f32_e32 v19, v19
	v_exp_f32_e32 v20, v20
	v_exp_f32_e32 v21, v21
	v_exp_f32_e32 v22, v22
	v_exp_f32_e32 v23, v23
	v_exp_f32_e32 v24, v24
	v_exp_f32_e32 v25, v25
	v_exp_f32_e32 v26, v26
	v_exp_f32_e32 v27, v27
	v_exp_f32_e32 v28, v28
	v_exp_f32_e32 v29, v29
	v_exp_f32_e32 v30, v30
	v_exp_f32_e32 v31, v31
	v_exp_f32_e32 v32, v32
	v_exp_f32_e32 v33, v33
	v_exp_f32_e32 v236, v236
	v_exp_f32_e32 v237, v237
	v_exp_f32_e32 v238, v238
	v_exp_f32_e32 v239, v239
	v_exp_f32_e32 v240, v240
	v_exp_f32_e32 v241, v241
	v_exp_f32_e32 v242, v242
	v_exp_f32_e32 v243, v243
	v_exp_f32_e32 v244, v244
	v_exp_f32_e32 v245, v245
	v_exp_f32_e32 v246, v246
	v_exp_f32_e32 v247, v247
	v_exp_f32_e32 v248, v248
	v_exp_f32_e32 v249, v249
	v_exp_f32_e32 v250, v250
	v_exp_f32_e32 v251, v251
	v_lshlrev_b32_e32 v196, 16, v196
	v_lshlrev_b32_e32 v197, 16, v197
	v_lshlrev_b32_e32 v198, 16, v198
	v_lshlrev_b32_e32 v199, 16, v199
	v_lshlrev_b32_e32 v200, 16, v200
	v_lshlrev_b32_e32 v201, 16, v201
	v_lshlrev_b32_e32 v202, 16, v202
	v_lshlrev_b32_e32 v203, 16, v203
	v_lshlrev_b32_e32 v204, 16, v204
	v_lshlrev_b32_e32 v205, 16, v205
	v_lshlrev_b32_e32 v206, 16, v206
	v_lshlrev_b32_e32 v207, 16, v207
	v_lshlrev_b32_e32 v208, 16, v208
	v_lshlrev_b32_e32 v209, 16, v209
	v_lshlrev_b32_e32 v210, 16, v210
	v_lshlrev_b32_e32 v211, 16, v211
	v_lshlrev_b32_e32 v180, 16, v180
	v_lshlrev_b32_e32 v181, 16, v181
	v_lshlrev_b32_e32 v182, 16, v182
	v_lshlrev_b32_e32 v183, 16, v183
	v_lshlrev_b32_e32 v184, 16, v184
	v_lshlrev_b32_e32 v185, 16, v185
	v_lshlrev_b32_e32 v186, 16, v186
	v_lshlrev_b32_e32 v187, 16, v187
	v_lshlrev_b32_e32 v188, 16, v188
	v_lshlrev_b32_e32 v189, 16, v189
	v_lshlrev_b32_e32 v190, 16, v190
	v_lshlrev_b32_e32 v191, 16, v191
	v_lshlrev_b32_e32 v192, 16, v192
	v_lshlrev_b32_e32 v193, 16, v193
	v_lshlrev_b32_e32 v194, 16, v194
	v_lshlrev_b32_e32 v195, 16, v195
	v_mul_f32_e32 v196, v18, v196
	v_mul_f32_e32 v197, v19, v197
	v_mul_f32_e32 v198, v20, v198
	v_mul_f32_e32 v199, v21, v199
	v_mul_f32_e32 v200, v22, v200
	v_mul_f32_e32 v201, v23, v201
	v_mul_f32_e32 v202, v24, v202
	v_mul_f32_e32 v203, v25, v203
	v_mul_f32_e32 v204, v26, v204
	v_mul_f32_e32 v205, v27, v205
	v_mul_f32_e32 v206, v28, v206
	v_mul_f32_e32 v207, v29, v207
	v_mul_f32_e32 v208, v30, v208
; __device__ __forceinline__ unsigned f2bf(float f) { unsigned r; asm("v_cvt_pk_bf16_f32 %0, %1, %1" : "=v"(r) : "v"(f)); return r & 0xffffu; }
; __device__ __forceinline__ void gl1_item(PREF p, int l, int item, bool valid, LAS unsigned char* pl, int sw, int lane) {
;     ...
;             for (int ss = 0; ss < 16; ++ss) { const int s = g4 * 16 + ss; const int i = d ? 63 - s : s;
;                 float z = bup;
; #pragma unroll
;                 for (int r2 = 0; r2 < 8; ++r2) { const unsigned w = (unsigned)__builtin_amdgcn_readlane((int)lrp[r2], i);
;                     z = __builtin_amdgcn_fdot2_f32_bf16(__builtin_bit_cast(bf16x2_t, w), __builtin_bit_cast(bf16x2_t, wupp[r2]), z, false); }
;     ...
;             for (int ss = 0; ss < 16; ++ss) { const int s = g4 * 16 + ss; const int i = d ? 63 - s : s; const size_t rowi = (size_t)(row0 + i * rstride);
;                 bc += gv[ss];
;                 const float en = __expf(-bc), ep = __expf(bc);
;                 const float kt = kc[ss] * en, qt = qc[ss] * 0.125f * ep;
;                 const unsigned ktb = f2bf(kt);
;                 sKt[lane * 72 + i] = (bf16_t)ktb;
;                 QK[rowi * 1024 + d * 512 + h * 64 + lane] = (bf16_t)f2bf(qt);
;                 QK[rowi * 1024 + d * 512 + 256 + h * 64 + lane] = (bf16_t)ktb;
;             }
	v_mul_f32_e32 v209, v31, v209
	v_mul_f32_e32 v210, v32, v210
	v_mul_f32_e32 v211, v33, v211
	v_mul_f32_e32 v180, 0x3e000000, v180
	v_mul_f32_e32 v181, 0x3e000000, v181
	v_mul_f32_e32 v182, 0x3e000000, v182
	v_mul_f32_e32 v183, 0x3e000000, v183
	v_mul_f32_e32 v184, 0x3e000000, v184
	v_mul_f32_e32 v185, 0x3e000000, v185
	v_mul_f32_e32 v186, 0x3e000000, v186
	v_mul_f32_e32 v187, 0x3e000000, v187
	v_mul_f32_e32 v188, 0x3e000000, v188
	v_mul_f32_e32 v189, 0x3e000000, v189
	v_mul_f32_e32 v190, 0x3e000000, v190
	v_mul_f32_e32 v191, 0x3e000000, v191
	v_mul_f32_e32 v192, 0x3e000000, v192
	v_mul_f32_e32 v193, 0x3e000000, v193
	v_mul_f32_e32 v194, 0x3e000000, v194
	v_mul_f32_e32 v195, 0x3e000000, v195
	v_mul_f32_e32 v180, v180, v236
	v_mul_f32_e32 v181, v181, v237
	v_mul_f32_e32 v182, v182, v238
	v_mul_f32_e32 v183, v183, v239
	v_mul_f32_e32 v184, v184, v240
	v_mul_f32_e32 v185, v185, v241
	v_mul_f32_e32 v186, v186, v242
	v_mul_f32_e32 v187, v187, v243
	v_mul_f32_e32 v188, v188, v244
	v_mul_f32_e32 v189, v189, v245
	v_mul_f32_e32 v190, v190, v246
	v_mul_f32_e32 v191, v191, v247
	v_mul_f32_e32 v192, v192, v248
	v_mul_f32_e32 v193, v193, v249
	v_mul_f32_e32 v194, v194, v250
	v_mul_f32_e32 v195, v195, v251
	v_cvt_pk_bf16_f32 v196, v196, v196
	v_cvt_pk_bf16_f32 v197, v197, v197
	v_cvt_pk_bf16_f32 v198, v198, v198
	v_cvt_pk_bf16_f32 v199, v199, v199
	v_cvt_pk_bf16_f32 v200, v200, v200
	v_cvt_pk_bf16_f32 v201, v201, v201
	v_cvt_pk_bf16_f32 v202, v202, v202
	v_cvt_pk_bf16_f32 v203, v203, v203
	v_cvt_pk_bf16_f32 v204, v204, v204
	v_cvt_pk_bf16_f32 v205, v205, v205
	v_cvt_pk_bf16_f32 v206, v206, v206
	v_cvt_pk_bf16_f32 v207, v207, v207
	v_cvt_pk_bf16_f32 v208, v208, v208
	v_cvt_pk_bf16_f32 v209, v209, v209
	v_cvt_pk_bf16_f32 v210, v210, v210
	v_cvt_pk_bf16_f32 v211, v211, v211
	v_cvt_pk_bf16_f32 v180, v180, v180
	v_cvt_pk_bf16_f32 v181, v181, v181
	v_cvt_pk_bf16_f32 v182, v182, v182
	v_cvt_pk_bf16_f32 v183, v183, v183
	v_cvt_pk_bf16_f32 v184, v184, v184
	v_cvt_pk_bf16_f32 v185, v185, v185
	v_cvt_pk_bf16_f32 v186, v186, v186
	v_cvt_pk_bf16_f32 v187, v187, v187
	v_cvt_pk_bf16_f32 v188, v188, v188
	v_cvt_pk_bf16_f32 v189, v189, v189
	v_cvt_pk_bf16_f32 v190, v190, v190
	v_cvt_pk_bf16_f32 v191, v191, v191
	v_cvt_pk_bf16_f32 v192, v192, v192
	v_cvt_pk_bf16_f32 v193, v193, v193
	v_cvt_pk_bf16_f32 v194, v194, v194
	v_cvt_pk_bf16_f32 v195, v195, v195
	ds_write_b16 v60, v196
	v_add_u32_e32 v60, v61, v60
	global_store_short v134, v180, s[4:5]
	global_store_short v134, v196, s[4:5] offset:512
	s_add_u32 s4, s4, s56
	s_addc_u32 s5, s5, s3
	ds_write_b16 v60, v197
	v_add_u32_e32 v60, v61, v60
	global_store_short v134, v181, s[4:5]
	global_store_short v134, v197, s[4:5] offset:512
	s_add_u32 s4, s4, s56
	s_addc_u32 s5, s5, s3
	ds_write_b16 v60, v198
	v_add_u32_e32 v60, v61, v60
	global_store_short v134, v182, s[4:5]
	global_store_short v134, v198, s[4:5] offset:512
	s_add_u32 s4, s4, s56
	s_addc_u32 s5, s5, s3
	ds_write_b16 v60, v199
	v_add_u32_e32 v60, v61, v60
	global_store_short v134, v183, s[4:5]
	global_store_short v134, v199, s[4:5] offset:512
	s_add_u32 s4, s4, s56
	s_addc_u32 s5, s5, s3
	ds_write_b16 v60, v200
	v_add_u32_e32 v60, v61, v60
	global_store_short v134, v184, s[4:5]
	global_store_short v134, v200, s[4:5] offset:512
	s_add_u32 s4, s4, s56
	s_addc_u32 s5, s5, s3
	ds_write_b16 v60, v201
	v_add_u32_e32 v60, v61, v60
	global_store_short v134, v185, s[4:5]
	global_store_short v134, v201, s[4:5] offset:512
	s_add_u32 s4, s4, s56
	s_addc_u32 s5, s5, s3
	ds_write_b16 v60, v202
	v_add_u32_e32 v60, v61, v60
	global_store_short v134, v186, s[4:5]
	global_store_short v134, v202, s[4:5] offset:512
	s_add_u32 s4, s4, s56
	s_addc_u32 s5, s5, s3
	ds_write_b16 v60, v203
	v_add_u32_e32 v60, v61, v60
	global_store_short v134, v187, s[4:5]
	global_store_short v134, v203, s[4:5] offset:512
	s_add_u32 s4, s4, s56
	s_addc_u32 s5, s5, s3
	ds_write_b16 v60, v204
	v_add_u32_e32 v60, v61, v60
	global_store_short v134, v188, s[4:5]
	global_store_short v134, v204, s[4:5] offset:512
	s_add_u32 s4, s4, s56
	s_addc_u32 s5, s5, s3
	ds_write_b16 v60, v205
	v_add_u32_e32 v60, v61, v60
	global_store_short v134, v189, s[4:5]
	global_store_short v134, v205, s[4:5] offset:512
	s_add_u32 s4, s4, s56
	s_addc_u32 s5, s5, s3
	ds_write_b16 v60, v206
	v_add_u32_e32 v60, v61, v60
	global_store_short v134, v190, s[4:5]
	global_store_short v134, v206, s[4:5] offset:512
	s_add_u32 s4, s4, s56
	s_addc_u32 s5, s5, s3
	ds_write_b16 v60, v207
	v_add_u32_e32 v60, v61, v60
	global_store_short v134, v191, s[4:5]
	global_store_short v134, v207, s[4:5] offset:512
	s_add_u32 s4, s4, s56
	s_addc_u32 s5, s5, s3
	ds_write_b16 v60, v208
	v_add_u32_e32 v60, v61, v60
	global_store_short v134, v192, s[4:5]
	global_store_short v134, v208, s[4:5] offset:512
	s_add_u32 s4, s4, s56
	s_addc_u32 s5, s5, s3
	ds_write_b16 v60, v209
	v_add_u32_e32 v60, v61, v60
	global_store_short v134, v193, s[4:5]
	global_store_short v134, v209, s[4:5] offset:512
	s_add_u32 s4, s4, s56
	s_addc_u32 s5, s5, s3
	ds_write_b16 v60, v210
	v_add_u32_e32 v60, v61, v60
	global_store_short v134, v194, s[4:5]
	global_store_short v134, v210, s[4:5] offset:512
	s_add_u32 s4, s4, s56
	s_addc_u32 s5, s5, s3
	ds_write_b16 v60, v211
	v_add_u32_e32 v60, v61, v60
	global_store_short v134, v195, s[4:5]
	global_store_short v134, v211, s[4:5] offset:512
	s_add_u32 s4, s4, s56
	s_addc_u32 s5, s5, s3
	v_mov_b32_e32 v236, v16
	v_dot2c_f32_bf16_dpp v236, v114, v8 row_newbcast:0 row_mask:0xf bank_mask:0xf
	v_dot2c_f32_bf16_dpp v236, v115, v9 row_newbcast:0 row_mask:0xf bank_mask:0xf
	v_dot2c_f32_bf16_dpp v236, v116, v10 row_newbcast:0 row_mask:0xf bank_mask:0xf
; __device__ __forceinline__ void gl1_item(PREF p, int l, int item, bool valid, LAS unsigned char* pl, int sw, int lane) {
;     ...
;             for (int ss = 0; ss < 16; ++ss) { const int s = g4 * 16 + ss; const int i = d ? 63 - s : s;
;                 float z = bup;
; #pragma unroll
;                 for (int r2 = 0; r2 < 8; ++r2) { const unsigned w = (unsigned)__builtin_amdgcn_readlane((int)lrp[r2], i);
;                     z = __builtin_amdgcn_fdot2_f32_bf16(__builtin_bit_cast(bf16x2_t, w), __builtin_bit_cast(bf16x2_t, wupp[r2]), z, false); }
	v_dot2c_f32_bf16_dpp v236, v117, v11 row_newbcast:0 row_mask:0xf bank_mask:0xf
	v_dot2c_f32_bf16_dpp v236, v118, v12 row_newbcast:0 row_mask:0xf bank_mask:0xf
	v_dot2c_f32_bf16_dpp v236, v119, v13 row_newbcast:0 row_mask:0xf bank_mask:0xf
	v_dot2c_f32_bf16_dpp v236, v120, v14 row_newbcast:0 row_mask:0xf bank_mask:0xf
	v_dot2c_f32_bf16_dpp v236, v121, v15 row_newbcast:0 row_mask:0xf bank_mask:0xf
	v_mov_b32_e32 v237, v16
	v_dot2c_f32_bf16_dpp v237, v114, v8 row_newbcast:1 row_mask:0xf bank_mask:0xf
	v_dot2c_f32_bf16_dpp v237, v115, v9 row_newbcast:1 row_mask:0xf bank_mask:0xf
	v_dot2c_f32_bf16_dpp v237, v116, v10 row_newbcast:1 row_mask:0xf bank_mask:0xf
	v_dot2c_f32_bf16_dpp v237, v117, v11 row_newbcast:1 row_mask:0xf bank_mask:0xf
	v_dot2c_f32_bf16_dpp v237, v118, v12 row_newbcast:1 row_mask:0xf bank_mask:0xf
	v_dot2c_f32_bf16_dpp v237, v119, v13 row_newbcast:1 row_mask:0xf bank_mask:0xf
	v_dot2c_f32_bf16_dpp v237, v120, v14 row_newbcast:1 row_mask:0xf bank_mask:0xf
	v_dot2c_f32_bf16_dpp v237, v121, v15 row_newbcast:1 row_mask:0xf bank_mask:0xf
	v_mov_b32_e32 v238, v16
	v_dot2c_f32_bf16_dpp v238, v114, v8 row_newbcast:2 row_mask:0xf bank_mask:0xf
	v_dot2c_f32_bf16_dpp v238, v115, v9 row_newbcast:2 row_mask:0xf bank_mask:0xf
	v_dot2c_f32_bf16_dpp v238, v116, v10 row_newbcast:2 row_mask:0xf bank_mask:0xf
	v_dot2c_f32_bf16_dpp v238, v117, v11 row_newbcast:2 row_mask:0xf bank_mask:0xf
	v_dot2c_f32_bf16_dpp v238, v118, v12 row_newbcast:2 row_mask:0xf bank_mask:0xf
	v_dot2c_f32_bf16_dpp v238, v119, v13 row_newbcast:2 row_mask:0xf bank_mask:0xf
	v_dot2c_f32_bf16_dpp v238, v120, v14 row_newbcast:2 row_mask:0xf bank_mask:0xf
	v_dot2c_f32_bf16_dpp v238, v121, v15 row_newbcast:2 row_mask:0xf bank_mask:0xf
	v_mov_b32_e32 v239, v16
	v_dot2c_f32_bf16_dpp v239, v114, v8 row_newbcast:3 row_mask:0xf bank_mask:0xf
	v_dot2c_f32_bf16_dpp v239, v115, v9 row_newbcast:3 row_mask:0xf bank_mask:0xf
	v_dot2c_f32_bf16_dpp v239, v116, v10 row_newbcast:3 row_mask:0xf bank_mask:0xf
	v_dot2c_f32_bf16_dpp v239, v117, v11 row_newbcast:3 row_mask:0xf bank_mask:0xf
	v_dot2c_f32_bf16_dpp v239, v118, v12 row_newbcast:3 row_mask:0xf bank_mask:0xf
	v_dot2c_f32_bf16_dpp v239, v119, v13 row_newbcast:3 row_mask:0xf bank_mask:0xf
	v_dot2c_f32_bf16_dpp v239, v120, v14 row_newbcast:3 row_mask:0xf bank_mask:0xf
	v_dot2c_f32_bf16_dpp v239, v121, v15 row_newbcast:3 row_mask:0xf bank_mask:0xf
	v_mov_b32_e32 v240, v16
	v_dot2c_f32_bf16_dpp v240, v114, v8 row_newbcast:4 row_mask:0xf bank_mask:0xf
	v_dot2c_f32_bf16_dpp v240, v115, v9 row_newbcast:4 row_mask:0xf bank_mask:0xf
	v_dot2c_f32_bf16_dpp v240, v116, v10 row_newbcast:4 row_mask:0xf bank_mask:0xf
	v_dot2c_f32_bf16_dpp v240, v117, v11 row_newbcast:4 row_mask:0xf bank_mask:0xf
	v_dot2c_f32_bf16_dpp v240, v118, v12 row_newbcast:4 row_mask:0xf bank_mask:0xf
	v_dot2c_f32_bf16_dpp v240, v119, v13 row_newbcast:4 row_mask:0xf bank_mask:0xf
	v_dot2c_f32_bf16_dpp v240, v120, v14 row_newbcast:4 row_mask:0xf bank_mask:0xf
	v_dot2c_f32_bf16_dpp v240, v121, v15 row_newbcast:4 row_mask:0xf bank_mask:0xf
	v_mov_b32_e32 v241, v16
	v_dot2c_f32_bf16_dpp v241, v114, v8 row_newbcast:5 row_mask:0xf bank_mask:0xf
	v_dot2c_f32_bf16_dpp v241, v115, v9 row_newbcast:5 row_mask:0xf bank_mask:0xf
	v_dot2c_f32_bf16_dpp v241, v116, v10 row_newbcast:5 row_mask:0xf bank_mask:0xf
	v_dot2c_f32_bf16_dpp v241, v117, v11 row_newbcast:5 row_mask:0xf bank_mask:0xf
	v_dot2c_f32_bf16_dpp v241, v118, v12 row_newbcast:5 row_mask:0xf bank_mask:0xf
	v_dot2c_f32_bf16_dpp v241, v119, v13 row_newbcast:5 row_mask:0xf bank_mask:0xf
	v_dot2c_f32_bf16_dpp v241, v120, v14 row_newbcast:5 row_mask:0xf bank_mask:0xf
	v_dot2c_f32_bf16_dpp v241, v121, v15 row_newbcast:5 row_mask:0xf bank_mask:0xf
	v_mov_b32_e32 v242, v16
	v_dot2c_f32_bf16_dpp v242, v114, v8 row_newbcast:6 row_mask:0xf bank_mask:0xf
	v_dot2c_f32_bf16_dpp v242, v115, v9 row_newbcast:6 row_mask:0xf bank_mask:0xf
	v_dot2c_f32_bf16_dpp v242, v116, v10 row_newbcast:6 row_mask:0xf bank_mask:0xf
	v_dot2c_f32_bf16_dpp v242, v117, v11 row_newbcast:6 row_mask:0xf bank_mask:0xf
	v_dot2c_f32_bf16_dpp v242, v118, v12 row_newbcast:6 row_mask:0xf bank_mask:0xf
	v_dot2c_f32_bf16_dpp v242, v119, v13 row_newbcast:6 row_mask:0xf bank_mask:0xf
	v_dot2c_f32_bf16_dpp v242, v120, v14 row_newbcast:6 row_mask:0xf bank_mask:0xf
	v_dot2c_f32_bf16_dpp v242, v121, v15 row_newbcast:6 row_mask:0xf bank_mask:0xf
	v_mov_b32_e32 v243, v16
	v_dot2c_f32_bf16_dpp v243, v114, v8 row_newbcast:7 row_mask:0xf bank_mask:0xf
	v_dot2c_f32_bf16_dpp v243, v115, v9 row_newbcast:7 row_mask:0xf bank_mask:0xf
	v_dot2c_f32_bf16_dpp v243, v116, v10 row_newbcast:7 row_mask:0xf bank_mask:0xf
	v_dot2c_f32_bf16_dpp v243, v117, v11 row_newbcast:7 row_mask:0xf bank_mask:0xf
	v_dot2c_f32_bf16_dpp v243, v118, v12 row_newbcast:7 row_mask:0xf bank_mask:0xf
	v_dot2c_f32_bf16_dpp v243, v119, v13 row_newbcast:7 row_mask:0xf bank_mask:0xf
	v_dot2c_f32_bf16_dpp v243, v120, v14 row_newbcast:7 row_mask:0xf bank_mask:0xf
	v_dot2c_f32_bf16_dpp v243, v121, v15 row_newbcast:7 row_mask:0xf bank_mask:0xf
	v_mov_b32_e32 v244, v16
	v_dot2c_f32_bf16_dpp v244, v114, v8 row_newbcast:8 row_mask:0xf bank_mask:0xf
	v_dot2c_f32_bf16_dpp v244, v115, v9 row_newbcast:8 row_mask:0xf bank_mask:0xf
	v_dot2c_f32_bf16_dpp v244, v116, v10 row_newbcast:8 row_mask:0xf bank_mask:0xf
	v_dot2c_f32_bf16_dpp v244, v117, v11 row_newbcast:8 row_mask:0xf bank_mask:0xf
	v_dot2c_f32_bf16_dpp v244, v118, v12 row_newbcast:8 row_mask:0xf bank_mask:0xf
	v_dot2c_f32_bf16_dpp v244, v119, v13 row_newbcast:8 row_mask:0xf bank_mask:0xf
	v_dot2c_f32_bf16_dpp v244, v120, v14 row_newbcast:8 row_mask:0xf bank_mask:0xf
; __device__ __forceinline__ void gl1_item(PREF p, int l, int item, bool valid, LAS unsigned char* pl, int sw, int lane) {
;     ...
;             for (int ss = 0; ss < 16; ++ss) { const int s = g4 * 16 + ss; const int i = d ? 63 - s : s;
;                 float z = bup;
; #pragma unroll
;                 for (int r2 = 0; r2 < 8; ++r2) { const unsigned w = (unsigned)__builtin_amdgcn_readlane((int)lrp[r2], i);
;                     z = __builtin_amdgcn_fdot2_f32_bf16(__builtin_bit_cast(bf16x2_t, w), __builtin_bit_cast(bf16x2_t, wupp[r2]), z, false); }
;                 gv[ss] = -(fmaxf(-z, 0.f) + __logf(1.f + __expf(-fabsf(z)))) * (1.f / 16.f);
	v_dot2c_f32_bf16_dpp v244, v121, v15 row_newbcast:8 row_mask:0xf bank_mask:0xf
	v_mov_b32_e32 v245, v16
	v_dot2c_f32_bf16_dpp v245, v114, v8 row_newbcast:9 row_mask:0xf bank_mask:0xf
	v_dot2c_f32_bf16_dpp v245, v115, v9 row_newbcast:9 row_mask:0xf bank_mask:0xf
	v_dot2c_f32_bf16_dpp v245, v116, v10 row_newbcast:9 row_mask:0xf bank_mask:0xf
	v_dot2c_f32_bf16_dpp v245, v117, v11 row_newbcast:9 row_mask:0xf bank_mask:0xf
	v_dot2c_f32_bf16_dpp v245, v118, v12 row_newbcast:9 row_mask:0xf bank_mask:0xf
	v_dot2c_f32_bf16_dpp v245, v119, v13 row_newbcast:9 row_mask:0xf bank_mask:0xf
	v_dot2c_f32_bf16_dpp v245, v120, v14 row_newbcast:9 row_mask:0xf bank_mask:0xf
	v_dot2c_f32_bf16_dpp v245, v121, v15 row_newbcast:9 row_mask:0xf bank_mask:0xf
	v_mov_b32_e32 v246, v16
	v_dot2c_f32_bf16_dpp v246, v114, v8 row_newbcast:10 row_mask:0xf bank_mask:0xf
	v_dot2c_f32_bf16_dpp v246, v115, v9 row_newbcast:10 row_mask:0xf bank_mask:0xf
	v_dot2c_f32_bf16_dpp v246, v116, v10 row_newbcast:10 row_mask:0xf bank_mask:0xf
	v_dot2c_f32_bf16_dpp v246, v117, v11 row_newbcast:10 row_mask:0xf bank_mask:0xf
	v_dot2c_f32_bf16_dpp v246, v118, v12 row_newbcast:10 row_mask:0xf bank_mask:0xf
	v_dot2c_f32_bf16_dpp v246, v119, v13 row_newbcast:10 row_mask:0xf bank_mask:0xf
	v_dot2c_f32_bf16_dpp v246, v120, v14 row_newbcast:10 row_mask:0xf bank_mask:0xf
	v_dot2c_f32_bf16_dpp v246, v121, v15 row_newbcast:10 row_mask:0xf bank_mask:0xf
	v_mov_b32_e32 v247, v16
	v_dot2c_f32_bf16_dpp v247, v114, v8 row_newbcast:11 row_mask:0xf bank_mask:0xf
	v_dot2c_f32_bf16_dpp v247, v115, v9 row_newbcast:11 row_mask:0xf bank_mask:0xf
	v_dot2c_f32_bf16_dpp v247, v116, v10 row_newbcast:11 row_mask:0xf bank_mask:0xf
	v_dot2c_f32_bf16_dpp v247, v117, v11 row_newbcast:11 row_mask:0xf bank_mask:0xf
	v_dot2c_f32_bf16_dpp v247, v118, v12 row_newbcast:11 row_mask:0xf bank_mask:0xf
	v_dot2c_f32_bf16_dpp v247, v119, v13 row_newbcast:11 row_mask:0xf bank_mask:0xf
	v_dot2c_f32_bf16_dpp v247, v120, v14 row_newbcast:11 row_mask:0xf bank_mask:0xf
	v_dot2c_f32_bf16_dpp v247, v121, v15 row_newbcast:11 row_mask:0xf bank_mask:0xf
	v_mov_b32_e32 v248, v16
	v_dot2c_f32_bf16_dpp v248, v114, v8 row_newbcast:12 row_mask:0xf bank_mask:0xf
	v_dot2c_f32_bf16_dpp v248, v115, v9 row_newbcast:12 row_mask:0xf bank_mask:0xf
	v_dot2c_f32_bf16_dpp v248, v116, v10 row_newbcast:12 row_mask:0xf bank_mask:0xf
	v_dot2c_f32_bf16_dpp v248, v117, v11 row_newbcast:12 row_mask:0xf bank_mask:0xf
	v_dot2c_f32_bf16_dpp v248, v118, v12 row_newbcast:12 row_mask:0xf bank_mask:0xf
	v_dot2c_f32_bf16_dpp v248, v119, v13 row_newbcast:12 row_mask:0xf bank_mask:0xf
	v_dot2c_f32_bf16_dpp v248, v120, v14 row_newbcast:12 row_mask:0xf bank_mask:0xf
	v_dot2c_f32_bf16_dpp v248, v121, v15 row_newbcast:12 row_mask:0xf bank_mask:0xf
	v_mov_b32_e32 v249, v16
	v_dot2c_f32_bf16_dpp v249, v114, v8 row_newbcast:13 row_mask:0xf bank_mask:0xf
	v_dot2c_f32_bf16_dpp v249, v115, v9 row_newbcast:13 row_mask:0xf bank_mask:0xf
	v_dot2c_f32_bf16_dpp v249, v116, v10 row_newbcast:13 row_mask:0xf bank_mask:0xf
	v_dot2c_f32_bf16_dpp v249, v117, v11 row_newbcast:13 row_mask:0xf bank_mask:0xf
	v_dot2c_f32_bf16_dpp v249, v118, v12 row_newbcast:13 row_mask:0xf bank_mask:0xf
	v_dot2c_f32_bf16_dpp v249, v119, v13 row_newbcast:13 row_mask:0xf bank_mask:0xf
	v_dot2c_f32_bf16_dpp v249, v120, v14 row_newbcast:13 row_mask:0xf bank_mask:0xf
	v_dot2c_f32_bf16_dpp v249, v121, v15 row_newbcast:13 row_mask:0xf bank_mask:0xf
	v_mov_b32_e32 v250, v16
	v_dot2c_f32_bf16_dpp v250, v114, v8 row_newbcast:14 row_mask:0xf bank_mask:0xf
	v_dot2c_f32_bf16_dpp v250, v115, v9 row_newbcast:14 row_mask:0xf bank_mask:0xf
	v_dot2c_f32_bf16_dpp v250, v116, v10 row_newbcast:14 row_mask:0xf bank_mask:0xf
	v_dot2c_f32_bf16_dpp v250, v117, v11 row_newbcast:14 row_mask:0xf bank_mask:0xf
	v_dot2c_f32_bf16_dpp v250, v118, v12 row_newbcast:14 row_mask:0xf bank_mask:0xf
	v_dot2c_f32_bf16_dpp v250, v119, v13 row_newbcast:14 row_mask:0xf bank_mask:0xf
	v_dot2c_f32_bf16_dpp v250, v120, v14 row_newbcast:14 row_mask:0xf bank_mask:0xf
	v_dot2c_f32_bf16_dpp v250, v121, v15 row_newbcast:14 row_mask:0xf bank_mask:0xf
	v_mov_b32_e32 v251, v16
	v_dot2c_f32_bf16_dpp v251, v114, v8 row_newbcast:15 row_mask:0xf bank_mask:0xf
	v_dot2c_f32_bf16_dpp v251, v115, v9 row_newbcast:15 row_mask:0xf bank_mask:0xf
	v_dot2c_f32_bf16_dpp v251, v116, v10 row_newbcast:15 row_mask:0xf bank_mask:0xf
	v_dot2c_f32_bf16_dpp v251, v117, v11 row_newbcast:15 row_mask:0xf bank_mask:0xf
	v_dot2c_f32_bf16_dpp v251, v118, v12 row_newbcast:15 row_mask:0xf bank_mask:0xf
	v_dot2c_f32_bf16_dpp v251, v119, v13 row_newbcast:15 row_mask:0xf bank_mask:0xf
	v_dot2c_f32_bf16_dpp v251, v120, v14 row_newbcast:15 row_mask:0xf bank_mask:0xf
	v_dot2c_f32_bf16_dpp v251, v121, v15 row_newbcast:15 row_mask:0xf bank_mask:0xf
	s_nop 2
	v_mul_f32_e64 v18, |v236|, s1
	v_mul_f32_e64 v19, |v237|, s1
	v_mul_f32_e64 v20, |v238|, s1
	v_mul_f32_e64 v21, |v239|, s1
	v_mul_f32_e64 v22, |v240|, s1
	v_mul_f32_e64 v23, |v241|, s1
	v_mul_f32_e64 v24, |v242|, s1
	v_mul_f32_e64 v25, |v243|, s1
	v_mul_f32_e64 v26, |v244|, s1
	v_mul_f32_e64 v27, |v245|, s1
	v_mul_f32_e64 v28, |v246|, s1
	v_mul_f32_e64 v29, |v247|, s1
	v_mul_f32_e64 v30, |v248|, s1
	v_mul_f32_e64 v31, |v249|, s1
	v_mul_f32_e64 v32, |v250|, s1
	v_mul_f32_e64 v33, |v251|, s1
	v_exp_f32_e32 v18, v18
	v_exp_f32_e32 v19, v19
	v_exp_f32_e32 v20, v20
	v_exp_f32_e32 v21, v21
	v_exp_f32_e32 v22, v22
	v_exp_f32_e32 v23, v23
	v_exp_f32_e32 v24, v24
	v_exp_f32_e32 v25, v25
	v_exp_f32_e32 v26, v26
	v_exp_f32_e32 v27, v27
	v_exp_f32_e32 v28, v28
	v_exp_f32_e32 v29, v29
	v_exp_f32_e32 v30, v30
	v_exp_f32_e32 v31, v31
	v_exp_f32_e32 v32, v32
; __device__ __forceinline__ void gl1_item(PREF p, int l, int item, bool valid, LAS unsigned char* pl, int sw, int lane) {
;     ...
;                 gv[ss] = -(fmaxf(-z, 0.f) + __logf(1.f + __expf(-fabsf(z)))) * (1.f / 16.f);
;     ...
;                 bc += gv[ss];
	v_exp_f32_e32 v33, v33
	v_max_f32_e64 v236, -v236, -v236
	v_max_f32_e64 v237, -v237, -v237
	v_max_f32_e64 v238, -v238, -v238
	v_max_f32_e64 v239, -v239, -v239
	v_max_f32_e64 v240, -v240, -v240
	v_max_f32_e64 v241, -v241, -v241
	v_max_f32_e64 v242, -v242, -v242
	v_max_f32_e64 v243, -v243, -v243
	v_max_f32_e64 v244, -v244, -v244
	v_max_f32_e64 v245, -v245, -v245
	v_max_f32_e64 v246, -v246, -v246
	v_max_f32_e64 v247, -v247, -v247
	v_max_f32_e64 v248, -v248, -v248
	v_max_f32_e64 v249, -v249, -v249
	v_max_f32_e64 v250, -v250, -v250
	v_max_f32_e64 v251, -v251, -v251
	v_max_f32_e32 v236, 0, v236
	v_max_f32_e32 v237, 0, v237
	v_max_f32_e32 v238, 0, v238
	v_max_f32_e32 v239, 0, v239
	v_max_f32_e32 v240, 0, v240
	v_max_f32_e32 v241, 0, v241
	v_max_f32_e32 v242, 0, v242
	v_max_f32_e32 v243, 0, v243
	v_max_f32_e32 v244, 0, v244
	v_max_f32_e32 v245, 0, v245
	v_max_f32_e32 v246, 0, v246
	v_max_f32_e32 v247, 0, v247
	v_max_f32_e32 v248, 0, v248
	v_max_f32_e32 v249, 0, v249
	v_max_f32_e32 v250, 0, v250
	v_max_f32_e32 v251, 0, v251
	v_add_f32_e32 v18, 1.0, v18
	v_add_f32_e32 v19, 1.0, v19
	v_add_f32_e32 v20, 1.0, v20
	v_add_f32_e32 v21, 1.0, v21
	v_add_f32_e32 v22, 1.0, v22
	v_add_f32_e32 v23, 1.0, v23
	v_add_f32_e32 v24, 1.0, v24
	v_add_f32_e32 v25, 1.0, v25
	v_add_f32_e32 v26, 1.0, v26
	v_add_f32_e32 v27, 1.0, v27
	v_add_f32_e32 v28, 1.0, v28
	v_add_f32_e32 v29, 1.0, v29
	v_add_f32_e32 v30, 1.0, v30
	v_add_f32_e32 v31, 1.0, v31
	v_add_f32_e32 v32, 1.0, v32
	v_add_f32_e32 v33, 1.0, v33
	v_log_f32_e32 v18, v18
	v_log_f32_e32 v19, v19
	v_log_f32_e32 v20, v20
	v_log_f32_e32 v21, v21
	v_log_f32_e32 v22, v22
	v_log_f32_e32 v23, v23
	v_log_f32_e32 v24, v24
	v_log_f32_e32 v25, v25
	v_log_f32_e32 v26, v26
	v_log_f32_e32 v27, v27
	v_log_f32_e32 v28, v28
	v_log_f32_e32 v29, v29
	v_log_f32_e32 v30, v30
	v_log_f32_e32 v31, v31
	v_log_f32_e32 v32, v32
	v_log_f32_e32 v33, v33
	s_mov_b32 s45, 0x3f317217
	v_mul_f32_e32 v70, 0x3f317217, v18
	v_mul_f32_e32 v71, 0x3f317217, v19
	v_mul_f32_e32 v72, 0x3f317217, v20
	v_mul_f32_e32 v73, 0x3f317217, v21
	v_mul_f32_e32 v74, 0x3f317217, v22
	v_mul_f32_e32 v75, 0x3f317217, v23
	v_mul_f32_e32 v76, 0x3f317217, v24
	v_mul_f32_e32 v77, 0x3f317217, v25
	v_mul_f32_e32 v78, 0x3f317217, v26
	v_mul_f32_e32 v79, 0x3f317217, v27
	v_mul_f32_e32 v80, 0x3f317217, v28
	v_mul_f32_e32 v81, 0x3f317217, v29
	v_mul_f32_e32 v82, 0x3f317217, v30
	v_mul_f32_e32 v83, 0x3f317217, v31
	v_mul_f32_e32 v84, 0x3f317217, v32
	v_mul_f32_e32 v85, 0x3f317217, v33
	v_fma_f32 v70, v18, s45, -v70
	v_fma_f32 v71, v19, s45, -v71
	v_fma_f32 v72, v20, s45, -v72
	v_fma_f32 v73, v21, s45, -v73
	v_fma_f32 v74, v22, s45, -v74
	v_fma_f32 v75, v23, s45, -v75
	v_fma_f32 v76, v24, s45, -v76
	v_fma_f32 v77, v25, s45, -v77
	v_fma_f32 v78, v26, s45, -v78
	v_fma_f32 v79, v27, s45, -v79
	v_fma_f32 v80, v28, s45, -v80
	v_fma_f32 v81, v29, s45, -v81
	v_fma_f32 v82, v30, s45, -v82
	v_fma_f32 v83, v31, s45, -v83
	v_fma_f32 v84, v32, s45, -v84
	v_fma_f32 v85, v33, s45, -v85
	v_fmac_f32_e32 v70, 0x3377d1cf, v18
	v_fmac_f32_e32 v71, 0x3377d1cf, v19
	v_fmac_f32_e32 v72, 0x3377d1cf, v20
	v_fmac_f32_e32 v73, 0x3377d1cf, v21
	v_fmac_f32_e32 v74, 0x3377d1cf, v22
	v_fmac_f32_e32 v75, 0x3377d1cf, v23
	v_fmac_f32_e32 v76, 0x3377d1cf, v24
	v_fmac_f32_e32 v77, 0x3377d1cf, v25
	v_fmac_f32_e32 v78, 0x3377d1cf, v26
	v_fmac_f32_e32 v79, 0x3377d1cf, v27
	v_fmac_f32_e32 v80, 0x3377d1cf, v28
	v_fmac_f32_e32 v81, 0x3377d1cf, v29
	v_fmac_f32_e32 v82, 0x3377d1cf, v30
	v_fmac_f32_e32 v83, 0x3377d1cf, v31
	v_fmac_f32_e32 v84, 0x3377d1cf, v32
	v_fmac_f32_e32 v85, 0x3377d1cf, v33
	v_fmac_f32_e32 v70, 0x3f317217, v18
	v_fmac_f32_e32 v71, 0x3f317217, v19
	v_fmac_f32_e32 v72, 0x3f317217, v20
	v_fmac_f32_e32 v73, 0x3f317217, v21
	v_fmac_f32_e32 v74, 0x3f317217, v22
	v_fmac_f32_e32 v75, 0x3f317217, v23
	v_fmac_f32_e32 v76, 0x3f317217, v24
	v_fmac_f32_e32 v77, 0x3f317217, v25
	v_fmac_f32_e32 v78, 0x3f317217, v26
	v_fmac_f32_e32 v79, 0x3f317217, v27
	v_fmac_f32_e32 v80, 0x3f317217, v28
	v_fmac_f32_e32 v81, 0x3f317217, v29
	v_fmac_f32_e32 v82, 0x3f317217, v30
	v_fmac_f32_e32 v83, 0x3f317217, v31
	v_fmac_f32_e32 v84, 0x3f317217, v32
	v_fmac_f32_e32 v85, 0x3f317217, v33
	v_add_f32_e32 v236, v236, v70
	v_add_f32_e32 v237, v237, v71
	v_add_f32_e32 v238, v238, v72
	v_add_f32_e32 v239, v239, v73
	v_add_f32_e32 v240, v240, v74
	v_add_f32_e32 v241, v241, v75
	v_add_f32_e32 v242, v242, v76
	v_add_f32_e32 v243, v243, v77
	v_add_f32_e32 v244, v244, v78
	v_add_f32_e32 v245, v245, v79
	v_add_f32_e32 v246, v246, v80
	v_add_f32_e32 v247, v247, v81
	v_add_f32_e32 v248, v248, v82
	v_add_f32_e32 v249, v249, v83
	v_add_f32_e32 v250, v250, v84
	v_add_f32_e32 v251, v251, v85
	v_mov_b32_e32 v70, v17
	v_fmac_f32_e32 v70, 0xbd800000, v236
	v_mov_b32_e32 v71, v70
	v_fmac_f32_e32 v71, 0xbd800000, v237
	v_mov_b32_e32 v72, v71
	v_fmac_f32_e32 v72, 0xbd800000, v238
	v_mov_b32_e32 v73, v72
	v_fmac_f32_e32 v73, 0xbd800000, v239
	v_mov_b32_e32 v74, v73
	v_fmac_f32_e32 v74, 0xbd800000, v240
	v_mov_b32_e32 v75, v74
	v_fmac_f32_e32 v75, 0xbd800000, v241
	v_mov_b32_e32 v76, v75
	v_fmac_f32_e32 v76, 0xbd800000, v242
	v_mov_b32_e32 v77, v76
	v_fmac_f32_e32 v77, 0xbd800000, v243
	v_mov_b32_e32 v78, v77
	v_fmac_f32_e32 v78, 0xbd800000, v244
	v_mov_b32_e32 v79, v78
	v_fmac_f32_e32 v79, 0xbd800000, v245
	v_mov_b32_e32 v80, v79
	v_fmac_f32_e32 v80, 0xbd800000, v246
	v_mov_b32_e32 v81, v80
	v_fmac_f32_e32 v81, 0xbd800000, v247
	v_mov_b32_e32 v82, v81
	v_fmac_f32_e32 v82, 0xbd800000, v248
	v_mov_b32_e32 v83, v82
	v_fmac_f32_e32 v83, 0xbd800000, v249
	v_mov_b32_e32 v84, v83
	v_fmac_f32_e32 v84, 0xbd800000, v250
	v_mov_b32_e32 v85, v84
	v_fmac_f32_e32 v85, 0xbd800000, v251
	v_mov_b32_e32 v17, v85
	s_waitcnt vmcnt(32)
; __device__ __forceinline__ void gl1_item(PREF p, int l, int item, bool valid, LAS unsigned char* pl, int sw, int lane) {
;     ...
;             if (g4 < 3) {
; #pragma unroll
;                 for (int ss = 0; ss < 16; ++ss) { const int s = (g4 + 1) * 16 + ss; const int i = d ? 63 - s : s; const bf16_t* pr = P + (size_t)(row0 + i * rstride) * PW + h * 64 + lane;
;                     qn[ss] = __builtin_bit_cast(float, (unsigned)pr[1024]); kn[ss] = __builtin_bit_cast(float, (unsigned)pr[1280]); }
;                 __builtin_amdgcn_sched_barrier(0);
;             }
;     ...
;                 const float en = __expf(-bc), ep = __expf(bc);
;                 const float kt = kc[ss] * en, qt = qc[ss] * 0.125f * ep;
	global_load_ushort v180, v134, s[6:7]
	global_load_ushort v196, v134, s[6:7] offset:512
	s_add_u32 s6, s6, s54
	s_addc_u32 s7, s7, s55
	global_load_ushort v181, v134, s[6:7]
	global_load_ushort v197, v134, s[6:7] offset:512
	s_add_u32 s6, s6, s54
	s_addc_u32 s7, s7, s55
	global_load_ushort v182, v134, s[6:7]
	global_load_ushort v198, v134, s[6:7] offset:512
	s_add_u32 s6, s6, s54
	s_addc_u32 s7, s7, s55
	global_load_ushort v183, v134, s[6:7]
	global_load_ushort v199, v134, s[6:7] offset:512
	s_add_u32 s6, s6, s54
	s_addc_u32 s7, s7, s55
	global_load_ushort v184, v134, s[6:7]
	global_load_ushort v200, v134, s[6:7] offset:512
	s_add_u32 s6, s6, s54
	s_addc_u32 s7, s7, s55
	global_load_ushort v185, v134, s[6:7]
	global_load_ushort v201, v134, s[6:7] offset:512
	s_add_u32 s6, s6, s54
	s_addc_u32 s7, s7, s55
	global_load_ushort v186, v134, s[6:7]
	global_load_ushort v202, v134, s[6:7] offset:512
	s_add_u32 s6, s6, s54
	s_addc_u32 s7, s7, s55
	global_load_ushort v187, v134, s[6:7]
	global_load_ushort v203, v134, s[6:7] offset:512
	s_add_u32 s6, s6, s54
	s_addc_u32 s7, s7, s55
	global_load_ushort v188, v134, s[6:7]
	global_load_ushort v204, v134, s[6:7] offset:512
	s_add_u32 s6, s6, s54
	s_addc_u32 s7, s7, s55
	global_load_ushort v189, v134, s[6:7]
	global_load_ushort v205, v134, s[6:7] offset:512
	s_add_u32 s6, s6, s54
	s_addc_u32 s7, s7, s55
	global_load_ushort v190, v134, s[6:7]
	global_load_ushort v206, v134, s[6:7] offset:512
	s_add_u32 s6, s6, s54
	s_addc_u32 s7, s7, s55
	global_load_ushort v191, v134, s[6:7]
	global_load_ushort v207, v134, s[6:7] offset:512
	s_add_u32 s6, s6, s54
	s_addc_u32 s7, s7, s55
	global_load_ushort v192, v134, s[6:7]
	global_load_ushort v208, v134, s[6:7] offset:512
	s_add_u32 s6, s6, s54
	s_addc_u32 s7, s7, s55
	global_load_ushort v193, v134, s[6:7]
	global_load_ushort v209, v134, s[6:7] offset:512
	s_add_u32 s6, s6, s54
	s_addc_u32 s7, s7, s55
	global_load_ushort v194, v134, s[6:7]
	global_load_ushort v210, v134, s[6:7] offset:512
	s_add_u32 s6, s6, s54
	s_addc_u32 s7, s7, s55
	global_load_ushort v195, v134, s[6:7]
	global_load_ushort v211, v134, s[6:7] offset:512
	s_add_u32 s6, s6, s54
	s_addc_u32 s7, s7, s55
	v_mul_f32_e32 v18, 0xbfb8aa3b, v70
	v_mul_f32_e32 v19, 0xbfb8aa3b, v71
	v_mul_f32_e32 v20, 0xbfb8aa3b, v72
	v_mul_f32_e32 v21, 0xbfb8aa3b, v73
	v_mul_f32_e32 v22, 0xbfb8aa3b, v74
	v_mul_f32_e32 v23, 0xbfb8aa3b, v75
	v_mul_f32_e32 v24, 0xbfb8aa3b, v76
	v_mul_f32_e32 v25, 0xbfb8aa3b, v77
	v_mul_f32_e32 v26, 0xbfb8aa3b, v78
	v_mul_f32_e32 v27, 0xbfb8aa3b, v79
	v_mul_f32_e32 v28, 0xbfb8aa3b, v80
	v_mul_f32_e32 v29, 0xbfb8aa3b, v81
	v_mul_f32_e32 v30, 0xbfb8aa3b, v82
	v_mul_f32_e32 v31, 0xbfb8aa3b, v83
	v_mul_f32_e32 v32, 0xbfb8aa3b, v84
	v_mul_f32_e32 v33, 0xbfb8aa3b, v85
	v_mul_f32_e32 v236, 0x3fb8aa3b, v70
	v_mul_f32_e32 v237, 0x3fb8aa3b, v71
	v_mul_f32_e32 v238, 0x3fb8aa3b, v72
	v_mul_f32_e32 v239, 0x3fb8aa3b, v73
	v_mul_f32_e32 v240, 0x3fb8aa3b, v74
	v_mul_f32_e32 v241, 0x3fb8aa3b, v75
	v_mul_f32_e32 v242, 0x3fb8aa3b, v76
	v_mul_f32_e32 v243, 0x3fb8aa3b, v77
	v_mul_f32_e32 v244, 0x3fb8aa3b, v78
	v_mul_f32_e32 v245, 0x3fb8aa3b, v79
	v_mul_f32_e32 v246, 0x3fb8aa3b, v80
	v_mul_f32_e32 v247, 0x3fb8aa3b, v81
	v_mul_f32_e32 v248, 0x3fb8aa3b, v82
	v_mul_f32_e32 v249, 0x3fb8aa3b, v83
	v_mul_f32_e32 v250, 0x3fb8aa3b, v84
	v_mul_f32_e32 v251, 0x3fb8aa3b, v85
	v_exp_f32_e32 v18, v18
	v_exp_f32_e32 v19, v19
	v_exp_f32_e32 v20, v20
	v_exp_f32_e32 v21, v21
	v_exp_f32_e32 v22, v22
	v_exp_f32_e32 v23, v23
	v_exp_f32_e32 v24, v24
	v_exp_f32_e32 v25, v25
	v_exp_f32_e32 v26, v26
	v_exp_f32_e32 v27, v27
	v_exp_f32_e32 v28, v28
	v_exp_f32_e32 v29, v29
	v_exp_f32_e32 v30, v30
	v_exp_f32_e32 v31, v31
	v_exp_f32_e32 v32, v32
	v_exp_f32_e32 v33, v33
	v_exp_f32_e32 v236, v236
	v_exp_f32_e32 v237, v237
	v_exp_f32_e32 v238, v238
	v_exp_f32_e32 v239, v239
	v_exp_f32_e32 v240, v240
	v_exp_f32_e32 v241, v241
	v_exp_f32_e32 v242, v242
	v_exp_f32_e32 v243, v243
	v_exp_f32_e32 v244, v244
	v_exp_f32_e32 v245, v245
	v_exp_f32_e32 v246, v246
	v_exp_f32_e32 v247, v247
	v_exp_f32_e32 v248, v248
	v_exp_f32_e32 v249, v249
	v_exp_f32_e32 v250, v250
	v_exp_f32_e32 v251, v251
	v_lshlrev_b32_e32 v164, 16, v164
	v_lshlrev_b32_e32 v165, 16, v165
	v_lshlrev_b32_e32 v166, 16, v166
	v_lshlrev_b32_e32 v167, 16, v167
	v_lshlrev_b32_e32 v168, 16, v168
	v_lshlrev_b32_e32 v169, 16, v169
	v_lshlrev_b32_e32 v170, 16, v170
	v_lshlrev_b32_e32 v171, 16, v171
	v_lshlrev_b32_e32 v172, 16, v172
	v_lshlrev_b32_e32 v173, 16, v173
	v_lshlrev_b32_e32 v174, 16, v174
	v_lshlrev_b32_e32 v175, 16, v175
	v_lshlrev_b32_e32 v176, 16, v176
	v_lshlrev_b32_e32 v177, 16, v177
	v_lshlrev_b32_e32 v178, 16, v178
	v_lshlrev_b32_e32 v179, 16, v179
	v_lshlrev_b32_e32 v148, 16, v148
	v_lshlrev_b32_e32 v149, 16, v149
	v_lshlrev_b32_e32 v150, 16, v150
	v_lshlrev_b32_e32 v151, 16, v151
	v_lshlrev_b32_e32 v152, 16, v152
	v_lshlrev_b32_e32 v153, 16, v153
	v_lshlrev_b32_e32 v154, 16, v154
	v_lshlrev_b32_e32 v155, 16, v155
	v_lshlrev_b32_e32 v156, 16, v156
	v_lshlrev_b32_e32 v157, 16, v157
	v_lshlrev_b32_e32 v158, 16, v158
	v_lshlrev_b32_e32 v159, 16, v159
	v_lshlrev_b32_e32 v160, 16, v160
	v_lshlrev_b32_e32 v161, 16, v161
	v_lshlrev_b32_e32 v162, 16, v162
	v_lshlrev_b32_e32 v163, 16, v163
	v_mul_f32_e32 v164, v18, v164
	v_mul_f32_e32 v165, v19, v165
	v_mul_f32_e32 v166, v20, v166
	v_mul_f32_e32 v167, v21, v167
	v_mul_f32_e32 v168, v22, v168
	v_mul_f32_e32 v169, v23, v169
	v_mul_f32_e32 v170, v24, v170
	v_mul_f32_e32 v171, v25, v171
	v_mul_f32_e32 v172, v26, v172
	v_mul_f32_e32 v173, v27, v173
	v_mul_f32_e32 v174, v28, v174
	v_mul_f32_e32 v175, v29, v175
	v_mul_f32_e32 v176, v30, v176
; __device__ __forceinline__ unsigned f2bf(float f) { unsigned r; asm("v_cvt_pk_bf16_f32 %0, %1, %1" : "=v"(r) : "v"(f)); return r & 0xffffu; }
; __device__ __forceinline__ void gl1_item(PREF p, int l, int item, bool valid, LAS unsigned char* pl, int sw, int lane) {
;     ...
;             for (int ss = 0; ss < 16; ++ss) { const int s = g4 * 16 + ss; const int i = d ? 63 - s : s;
;                 float z = bup;
; #pragma unroll
;                 for (int r2 = 0; r2 < 8; ++r2) { const unsigned w = (unsigned)__builtin_amdgcn_readlane((int)lrp[r2], i);
;                     z = __builtin_amdgcn_fdot2_f32_bf16(__builtin_bit_cast(bf16x2_t, w), __builtin_bit_cast(bf16x2_t, wupp[r2]), z, false); }
;     ...
;                 const float kt = kc[ss] * en, qt = qc[ss] * 0.125f * ep;
;                 const unsigned ktb = f2bf(kt);
;                 sKt[lane * 72 + i] = (bf16_t)ktb;
;                 QK[rowi * 1024 + d * 512 + h * 64 + lane] = (bf16_t)f2bf(qt);
;                 QK[rowi * 1024 + d * 512 + 256 + h * 64 + lane] = (bf16_t)ktb;
;             }
	v_mul_f32_e32 v177, v31, v177
	v_mul_f32_e32 v178, v32, v178
	v_mul_f32_e32 v179, v33, v179
	v_mul_f32_e32 v148, 0x3e000000, v148
	v_mul_f32_e32 v149, 0x3e000000, v149
	v_mul_f32_e32 v150, 0x3e000000, v150
	v_mul_f32_e32 v151, 0x3e000000, v151
	v_mul_f32_e32 v152, 0x3e000000, v152
	v_mul_f32_e32 v153, 0x3e000000, v153
	v_mul_f32_e32 v154, 0x3e000000, v154
	v_mul_f32_e32 v155, 0x3e000000, v155
	v_mul_f32_e32 v156, 0x3e000000, v156
	v_mul_f32_e32 v157, 0x3e000000, v157
	v_mul_f32_e32 v158, 0x3e000000, v158
	v_mul_f32_e32 v159, 0x3e000000, v159
	v_mul_f32_e32 v160, 0x3e000000, v160
	v_mul_f32_e32 v161, 0x3e000000, v161
	v_mul_f32_e32 v162, 0x3e000000, v162
	v_mul_f32_e32 v163, 0x3e000000, v163
	v_mul_f32_e32 v148, v148, v236
	v_mul_f32_e32 v149, v149, v237
	v_mul_f32_e32 v150, v150, v238
	v_mul_f32_e32 v151, v151, v239
	v_mul_f32_e32 v152, v152, v240
	v_mul_f32_e32 v153, v153, v241
	v_mul_f32_e32 v154, v154, v242
	v_mul_f32_e32 v155, v155, v243
	v_mul_f32_e32 v156, v156, v244
	v_mul_f32_e32 v157, v157, v245
	v_mul_f32_e32 v158, v158, v246
	v_mul_f32_e32 v159, v159, v247
	v_mul_f32_e32 v160, v160, v248
	v_mul_f32_e32 v161, v161, v249
	v_mul_f32_e32 v162, v162, v250
	v_mul_f32_e32 v163, v163, v251
	v_cvt_pk_bf16_f32 v164, v164, v164
	v_cvt_pk_bf16_f32 v165, v165, v165
	v_cvt_pk_bf16_f32 v166, v166, v166
	v_cvt_pk_bf16_f32 v167, v167, v167
	v_cvt_pk_bf16_f32 v168, v168, v168
	v_cvt_pk_bf16_f32 v169, v169, v169
	v_cvt_pk_bf16_f32 v170, v170, v170
	v_cvt_pk_bf16_f32 v171, v171, v171
	v_cvt_pk_bf16_f32 v172, v172, v172
	v_cvt_pk_bf16_f32 v173, v173, v173
	v_cvt_pk_bf16_f32 v174, v174, v174
	v_cvt_pk_bf16_f32 v175, v175, v175
	v_cvt_pk_bf16_f32 v176, v176, v176
	v_cvt_pk_bf16_f32 v177, v177, v177
	v_cvt_pk_bf16_f32 v178, v178, v178
	v_cvt_pk_bf16_f32 v179, v179, v179
	v_cvt_pk_bf16_f32 v148, v148, v148
	v_cvt_pk_bf16_f32 v149, v149, v149
	v_cvt_pk_bf16_f32 v150, v150, v150
	v_cvt_pk_bf16_f32 v151, v151, v151
	v_cvt_pk_bf16_f32 v152, v152, v152
	v_cvt_pk_bf16_f32 v153, v153, v153
	v_cvt_pk_bf16_f32 v154, v154, v154
	v_cvt_pk_bf16_f32 v155, v155, v155
	v_cvt_pk_bf16_f32 v156, v156, v156
	v_cvt_pk_bf16_f32 v157, v157, v157
	v_cvt_pk_bf16_f32 v158, v158, v158
	v_cvt_pk_bf16_f32 v159, v159, v159
	v_cvt_pk_bf16_f32 v160, v160, v160
	v_cvt_pk_bf16_f32 v161, v161, v161
	v_cvt_pk_bf16_f32 v162, v162, v162
	v_cvt_pk_bf16_f32 v163, v163, v163
	ds_write_b16 v60, v164
	v_add_u32_e32 v60, v61, v60
	global_store_short v134, v148, s[4:5]
	global_store_short v134, v164, s[4:5] offset:512
	s_add_u32 s4, s4, s56
	s_addc_u32 s5, s5, s3
	ds_write_b16 v60, v165
	v_add_u32_e32 v60, v61, v60
	global_store_short v134, v149, s[4:5]
	global_store_short v134, v165, s[4:5] offset:512
	s_add_u32 s4, s4, s56
	s_addc_u32 s5, s5, s3
	ds_write_b16 v60, v166
	v_add_u32_e32 v60, v61, v60
	global_store_short v134, v150, s[4:5]
	global_store_short v134, v166, s[4:5] offset:512
	s_add_u32 s4, s4, s56
	s_addc_u32 s5, s5, s3
	ds_write_b16 v60, v167
	v_add_u32_e32 v60, v61, v60
	global_store_short v134, v151, s[4:5]
	global_store_short v134, v167, s[4:5] offset:512
	s_add_u32 s4, s4, s56
	s_addc_u32 s5, s5, s3
	ds_write_b16 v60, v168
	v_add_u32_e32 v60, v61, v60
	global_store_short v134, v152, s[4:5]
	global_store_short v134, v168, s[4:5] offset:512
	s_add_u32 s4, s4, s56
	s_addc_u32 s5, s5, s3
	ds_write_b16 v60, v169
	v_add_u32_e32 v60, v61, v60
	global_store_short v134, v153, s[4:5]
	global_store_short v134, v169, s[4:5] offset:512
	s_add_u32 s4, s4, s56
	s_addc_u32 s5, s5, s3
	ds_write_b16 v60, v170
	v_add_u32_e32 v60, v61, v60
	global_store_short v134, v154, s[4:5]
	global_store_short v134, v170, s[4:5] offset:512
	s_add_u32 s4, s4, s56
	s_addc_u32 s5, s5, s3
	ds_write_b16 v60, v171
	v_add_u32_e32 v60, v61, v60
	global_store_short v134, v155, s[4:5]
	global_store_short v134, v171, s[4:5] offset:512
	s_add_u32 s4, s4, s56
	s_addc_u32 s5, s5, s3
	ds_write_b16 v60, v172
	v_add_u32_e32 v60, v61, v60
	global_store_short v134, v156, s[4:5]
	global_store_short v134, v172, s[4:5] offset:512
	s_add_u32 s4, s4, s56
	s_addc_u32 s5, s5, s3
	ds_write_b16 v60, v173
	v_add_u32_e32 v60, v61, v60
	global_store_short v134, v157, s[4:5]
	global_store_short v134, v173, s[4:5] offset:512
	s_add_u32 s4, s4, s56
	s_addc_u32 s5, s5, s3
	ds_write_b16 v60, v174
	v_add_u32_e32 v60, v61, v60
	global_store_short v134, v158, s[4:5]
	global_store_short v134, v174, s[4:5] offset:512
	s_add_u32 s4, s4, s56
	s_addc_u32 s5, s5, s3
	ds_write_b16 v60, v175
	v_add_u32_e32 v60, v61, v60
	global_store_short v134, v159, s[4:5]
	global_store_short v134, v175, s[4:5] offset:512
	s_add_u32 s4, s4, s56
	s_addc_u32 s5, s5, s3
	ds_write_b16 v60, v176
	v_add_u32_e32 v60, v61, v60
	global_store_short v134, v160, s[4:5]
	global_store_short v134, v176, s[4:5] offset:512
	s_add_u32 s4, s4, s56
	s_addc_u32 s5, s5, s3
	ds_write_b16 v60, v177
	v_add_u32_e32 v60, v61, v60
	global_store_short v134, v161, s[4:5]
	global_store_short v134, v177, s[4:5] offset:512
	s_add_u32 s4, s4, s56
	s_addc_u32 s5, s5, s3
	ds_write_b16 v60, v178
	v_add_u32_e32 v60, v61, v60
	global_store_short v134, v162, s[4:5]
	global_store_short v134, v178, s[4:5] offset:512
	s_add_u32 s4, s4, s56
	s_addc_u32 s5, s5, s3
	ds_write_b16 v60, v179
	v_add_u32_e32 v60, v61, v60
	global_store_short v134, v163, s[4:5]
	global_store_short v134, v179, s[4:5] offset:512
	s_add_u32 s4, s4, s56
	s_addc_u32 s5, s5, s3
	v_mov_b32_e32 v236, v16
	v_dot2c_f32_bf16_dpp v236, v122, v8 row_newbcast:0 row_mask:0xf bank_mask:0xf
	v_dot2c_f32_bf16_dpp v236, v123, v9 row_newbcast:0 row_mask:0xf bank_mask:0xf
	v_dot2c_f32_bf16_dpp v236, v124, v10 row_newbcast:0 row_mask:0xf bank_mask:0xf
; __device__ __forceinline__ void gl1_item(PREF p, int l, int item, bool valid, LAS unsigned char* pl, int sw, int lane) {
;     ...
;             for (int ss = 0; ss < 16; ++ss) { const int s = g4 * 16 + ss; const int i = d ? 63 - s : s;
;                 float z = bup;
; #pragma unroll
;                 for (int r2 = 0; r2 < 8; ++r2) { const unsigned w = (unsigned)__builtin_amdgcn_readlane((int)lrp[r2], i);
;                     z = __builtin_amdgcn_fdot2_f32_bf16(__builtin_bit_cast(bf16x2_t, w), __builtin_bit_cast(bf16x2_t, wupp[r2]), z, false); }
	v_dot2c_f32_bf16_dpp v236, v125, v11 row_newbcast:0 row_mask:0xf bank_mask:0xf
	v_dot2c_f32_bf16_dpp v236, v126, v12 row_newbcast:0 row_mask:0xf bank_mask:0xf
	v_dot2c_f32_bf16_dpp v236, v127, v13 row_newbcast:0 row_mask:0xf bank_mask:0xf
	v_dot2c_f32_bf16_dpp v236, v128, v14 row_newbcast:0 row_mask:0xf bank_mask:0xf
	v_dot2c_f32_bf16_dpp v236, v129, v15 row_newbcast:0 row_mask:0xf bank_mask:0xf
	v_mov_b32_e32 v237, v16
	v_dot2c_f32_bf16_dpp v237, v122, v8 row_newbcast:1 row_mask:0xf bank_mask:0xf
	v_dot2c_f32_bf16_dpp v237, v123, v9 row_newbcast:1 row_mask:0xf bank_mask:0xf
	v_dot2c_f32_bf16_dpp v237, v124, v10 row_newbcast:1 row_mask:0xf bank_mask:0xf
	v_dot2c_f32_bf16_dpp v237, v125, v11 row_newbcast:1 row_mask:0xf bank_mask:0xf
	v_dot2c_f32_bf16_dpp v237, v126, v12 row_newbcast:1 row_mask:0xf bank_mask:0xf
	v_dot2c_f32_bf16_dpp v237, v127, v13 row_newbcast:1 row_mask:0xf bank_mask:0xf
	v_dot2c_f32_bf16_dpp v237, v128, v14 row_newbcast:1 row_mask:0xf bank_mask:0xf
	v_dot2c_f32_bf16_dpp v237, v129, v15 row_newbcast:1 row_mask:0xf bank_mask:0xf
	v_mov_b32_e32 v238, v16
	v_dot2c_f32_bf16_dpp v238, v122, v8 row_newbcast:2 row_mask:0xf bank_mask:0xf
	v_dot2c_f32_bf16_dpp v238, v123, v9 row_newbcast:2 row_mask:0xf bank_mask:0xf
	v_dot2c_f32_bf16_dpp v238, v124, v10 row_newbcast:2 row_mask:0xf bank_mask:0xf
	v_dot2c_f32_bf16_dpp v238, v125, v11 row_newbcast:2 row_mask:0xf bank_mask:0xf
	v_dot2c_f32_bf16_dpp v238, v126, v12 row_newbcast:2 row_mask:0xf bank_mask:0xf
	v_dot2c_f32_bf16_dpp v238, v127, v13 row_newbcast:2 row_mask:0xf bank_mask:0xf
	v_dot2c_f32_bf16_dpp v238, v128, v14 row_newbcast:2 row_mask:0xf bank_mask:0xf
	v_dot2c_f32_bf16_dpp v238, v129, v15 row_newbcast:2 row_mask:0xf bank_mask:0xf
	v_mov_b32_e32 v239, v16
	v_dot2c_f32_bf16_dpp v239, v122, v8 row_newbcast:3 row_mask:0xf bank_mask:0xf
	v_dot2c_f32_bf16_dpp v239, v123, v9 row_newbcast:3 row_mask:0xf bank_mask:0xf
	v_dot2c_f32_bf16_dpp v239, v124, v10 row_newbcast:3 row_mask:0xf bank_mask:0xf
	v_dot2c_f32_bf16_dpp v239, v125, v11 row_newbcast:3 row_mask:0xf bank_mask:0xf
	v_dot2c_f32_bf16_dpp v239, v126, v12 row_newbcast:3 row_mask:0xf bank_mask:0xf
	v_dot2c_f32_bf16_dpp v239, v127, v13 row_newbcast:3 row_mask:0xf bank_mask:0xf
	v_dot2c_f32_bf16_dpp v239, v128, v14 row_newbcast:3 row_mask:0xf bank_mask:0xf
	v_dot2c_f32_bf16_dpp v239, v129, v15 row_newbcast:3 row_mask:0xf bank_mask:0xf
	v_mov_b32_e32 v240, v16
	v_dot2c_f32_bf16_dpp v240, v122, v8 row_newbcast:4 row_mask:0xf bank_mask:0xf
	v_dot2c_f32_bf16_dpp v240, v123, v9 row_newbcast:4 row_mask:0xf bank_mask:0xf
	v_dot2c_f32_bf16_dpp v240, v124, v10 row_newbcast:4 row_mask:0xf bank_mask:0xf
	v_dot2c_f32_bf16_dpp v240, v125, v11 row_newbcast:4 row_mask:0xf bank_mask:0xf
	v_dot2c_f32_bf16_dpp v240, v126, v12 row_newbcast:4 row_mask:0xf bank_mask:0xf
	v_dot2c_f32_bf16_dpp v240, v127, v13 row_newbcast:4 row_mask:0xf bank_mask:0xf
	v_dot2c_f32_bf16_dpp v240, v128, v14 row_newbcast:4 row_mask:0xf bank_mask:0xf
	v_dot2c_f32_bf16_dpp v240, v129, v15 row_newbcast:4 row_mask:0xf bank_mask:0xf
	v_mov_b32_e32 v241, v16
	v_dot2c_f32_bf16_dpp v241, v122, v8 row_newbcast:5 row_mask:0xf bank_mask:0xf
	v_dot2c_f32_bf16_dpp v241, v123, v9 row_newbcast:5 row_mask:0xf bank_mask:0xf
	v_dot2c_f32_bf16_dpp v241, v124, v10 row_newbcast:5 row_mask:0xf bank_mask:0xf
	v_dot2c_f32_bf16_dpp v241, v125, v11 row_newbcast:5 row_mask:0xf bank_mask:0xf
	v_dot2c_f32_bf16_dpp v241, v126, v12 row_newbcast:5 row_mask:0xf bank_mask:0xf
	v_dot2c_f32_bf16_dpp v241, v127, v13 row_newbcast:5 row_mask:0xf bank_mask:0xf
	v_dot2c_f32_bf16_dpp v241, v128, v14 row_newbcast:5 row_mask:0xf bank_mask:0xf
	v_dot2c_f32_bf16_dpp v241, v129, v15 row_newbcast:5 row_mask:0xf bank_mask:0xf
	v_mov_b32_e32 v242, v16
	v_dot2c_f32_bf16_dpp v242, v122, v8 row_newbcast:6 row_mask:0xf bank_mask:0xf
	v_dot2c_f32_bf16_dpp v242, v123, v9 row_newbcast:6 row_mask:0xf bank_mask:0xf
	v_dot2c_f32_bf16_dpp v242, v124, v10 row_newbcast:6 row_mask:0xf bank_mask:0xf
	v_dot2c_f32_bf16_dpp v242, v125, v11 row_newbcast:6 row_mask:0xf bank_mask:0xf
	v_dot2c_f32_bf16_dpp v242, v126, v12 row_newbcast:6 row_mask:0xf bank_mask:0xf
	v_dot2c_f32_bf16_dpp v242, v127, v13 row_newbcast:6 row_mask:0xf bank_mask:0xf
	v_dot2c_f32_bf16_dpp v242, v128, v14 row_newbcast:6 row_mask:0xf bank_mask:0xf
	v_dot2c_f32_bf16_dpp v242, v129, v15 row_newbcast:6 row_mask:0xf bank_mask:0xf
	v_mov_b32_e32 v243, v16
	v_dot2c_f32_bf16_dpp v243, v122, v8 row_newbcast:7 row_mask:0xf bank_mask:0xf
	v_dot2c_f32_bf16_dpp v243, v123, v9 row_newbcast:7 row_mask:0xf bank_mask:0xf
	v_dot2c_f32_bf16_dpp v243, v124, v10 row_newbcast:7 row_mask:0xf bank_mask:0xf
	v_dot2c_f32_bf16_dpp v243, v125, v11 row_newbcast:7 row_mask:0xf bank_mask:0xf
	v_dot2c_f32_bf16_dpp v243, v126, v12 row_newbcast:7 row_mask:0xf bank_mask:0xf
	v_dot2c_f32_bf16_dpp v243, v127, v13 row_newbcast:7 row_mask:0xf bank_mask:0xf
	v_dot2c_f32_bf16_dpp v243, v128, v14 row_newbcast:7 row_mask:0xf bank_mask:0xf
	v_dot2c_f32_bf16_dpp v243, v129, v15 row_newbcast:7 row_mask:0xf bank_mask:0xf
	v_mov_b32_e32 v244, v16
	v_dot2c_f32_bf16_dpp v244, v122, v8 row_newbcast:8 row_mask:0xf bank_mask:0xf
	v_dot2c_f32_bf16_dpp v244, v123, v9 row_newbcast:8 row_mask:0xf bank_mask:0xf
	v_dot2c_f32_bf16_dpp v244, v124, v10 row_newbcast:8 row_mask:0xf bank_mask:0xf
	v_dot2c_f32_bf16_dpp v244, v125, v11 row_newbcast:8 row_mask:0xf bank_mask:0xf
	v_dot2c_f32_bf16_dpp v244, v126, v12 row_newbcast:8 row_mask:0xf bank_mask:0xf
	v_dot2c_f32_bf16_dpp v244, v127, v13 row_newbcast:8 row_mask:0xf bank_mask:0xf
	v_dot2c_f32_bf16_dpp v244, v128, v14 row_newbcast:8 row_mask:0xf bank_mask:0xf
; __device__ __forceinline__ void gl1_item(PREF p, int l, int item, bool valid, LAS unsigned char* pl, int sw, int lane) {
;     ...
;             for (int ss = 0; ss < 16; ++ss) { const int s = g4 * 16 + ss; const int i = d ? 63 - s : s;
;                 float z = bup;
; #pragma unroll
;                 for (int r2 = 0; r2 < 8; ++r2) { const unsigned w = (unsigned)__builtin_amdgcn_readlane((int)lrp[r2], i);
;                     z = __builtin_amdgcn_fdot2_f32_bf16(__builtin_bit_cast(bf16x2_t, w), __builtin_bit_cast(bf16x2_t, wupp[r2]), z, false); }
;                 gv[ss] = -(fmaxf(-z, 0.f) + __logf(1.f + __expf(-fabsf(z)))) * (1.f / 16.f);
	v_dot2c_f32_bf16_dpp v244, v129, v15 row_newbcast:8 row_mask:0xf bank_mask:0xf
	v_mov_b32_e32 v245, v16
	v_dot2c_f32_bf16_dpp v245, v122, v8 row_newbcast:9 row_mask:0xf bank_mask:0xf
	v_dot2c_f32_bf16_dpp v245, v123, v9 row_newbcast:9 row_mask:0xf bank_mask:0xf
	v_dot2c_f32_bf16_dpp v245, v124, v10 row_newbcast:9 row_mask:0xf bank_mask:0xf
	v_dot2c_f32_bf16_dpp v245, v125, v11 row_newbcast:9 row_mask:0xf bank_mask:0xf
	v_dot2c_f32_bf16_dpp v245, v126, v12 row_newbcast:9 row_mask:0xf bank_mask:0xf
	v_dot2c_f32_bf16_dpp v245, v127, v13 row_newbcast:9 row_mask:0xf bank_mask:0xf
	v_dot2c_f32_bf16_dpp v245, v128, v14 row_newbcast:9 row_mask:0xf bank_mask:0xf
	v_dot2c_f32_bf16_dpp v245, v129, v15 row_newbcast:9 row_mask:0xf bank_mask:0xf
	v_mov_b32_e32 v246, v16
	v_dot2c_f32_bf16_dpp v246, v122, v8 row_newbcast:10 row_mask:0xf bank_mask:0xf
	v_dot2c_f32_bf16_dpp v246, v123, v9 row_newbcast:10 row_mask:0xf bank_mask:0xf
	v_dot2c_f32_bf16_dpp v246, v124, v10 row_newbcast:10 row_mask:0xf bank_mask:0xf
	v_dot2c_f32_bf16_dpp v246, v125, v11 row_newbcast:10 row_mask:0xf bank_mask:0xf
	v_dot2c_f32_bf16_dpp v246, v126, v12 row_newbcast:10 row_mask:0xf bank_mask:0xf
	v_dot2c_f32_bf16_dpp v246, v127, v13 row_newbcast:10 row_mask:0xf bank_mask:0xf
	v_dot2c_f32_bf16_dpp v246, v128, v14 row_newbcast:10 row_mask:0xf bank_mask:0xf
	v_dot2c_f32_bf16_dpp v246, v129, v15 row_newbcast:10 row_mask:0xf bank_mask:0xf
	v_mov_b32_e32 v247, v16
	v_dot2c_f32_bf16_dpp v247, v122, v8 row_newbcast:11 row_mask:0xf bank_mask:0xf
	v_dot2c_f32_bf16_dpp v247, v123, v9 row_newbcast:11 row_mask:0xf bank_mask:0xf
	v_dot2c_f32_bf16_dpp v247, v124, v10 row_newbcast:11 row_mask:0xf bank_mask:0xf
	v_dot2c_f32_bf16_dpp v247, v125, v11 row_newbcast:11 row_mask:0xf bank_mask:0xf
	v_dot2c_f32_bf16_dpp v247, v126, v12 row_newbcast:11 row_mask:0xf bank_mask:0xf
	v_dot2c_f32_bf16_dpp v247, v127, v13 row_newbcast:11 row_mask:0xf bank_mask:0xf
	v_dot2c_f32_bf16_dpp v247, v128, v14 row_newbcast:11 row_mask:0xf bank_mask:0xf
	v_dot2c_f32_bf16_dpp v247, v129, v15 row_newbcast:11 row_mask:0xf bank_mask:0xf
	v_mov_b32_e32 v248, v16
	v_dot2c_f32_bf16_dpp v248, v122, v8 row_newbcast:12 row_mask:0xf bank_mask:0xf
	v_dot2c_f32_bf16_dpp v248, v123, v9 row_newbcast:12 row_mask:0xf bank_mask:0xf
	v_dot2c_f32_bf16_dpp v248, v124, v10 row_newbcast:12 row_mask:0xf bank_mask:0xf
	v_dot2c_f32_bf16_dpp v248, v125, v11 row_newbcast:12 row_mask:0xf bank_mask:0xf
	v_dot2c_f32_bf16_dpp v248, v126, v12 row_newbcast:12 row_mask:0xf bank_mask:0xf
	v_dot2c_f32_bf16_dpp v248, v127, v13 row_newbcast:12 row_mask:0xf bank_mask:0xf
	v_dot2c_f32_bf16_dpp v248, v128, v14 row_newbcast:12 row_mask:0xf bank_mask:0xf
	v_dot2c_f32_bf16_dpp v248, v129, v15 row_newbcast:12 row_mask:0xf bank_mask:0xf
	v_mov_b32_e32 v249, v16
	v_dot2c_f32_bf16_dpp v249, v122, v8 row_newbcast:13 row_mask:0xf bank_mask:0xf
	v_dot2c_f32_bf16_dpp v249, v123, v9 row_newbcast:13 row_mask:0xf bank_mask:0xf
	v_dot2c_f32_bf16_dpp v249, v124, v10 row_newbcast:13 row_mask:0xf bank_mask:0xf
	v_dot2c_f32_bf16_dpp v249, v125, v11 row_newbcast:13 row_mask:0xf bank_mask:0xf
	v_dot2c_f32_bf16_dpp v249, v126, v12 row_newbcast:13 row_mask:0xf bank_mask:0xf
	v_dot2c_f32_bf16_dpp v249, v127, v13 row_newbcast:13 row_mask:0xf bank_mask:0xf
	v_dot2c_f32_bf16_dpp v249, v128, v14 row_newbcast:13 row_mask:0xf bank_mask:0xf
	v_dot2c_f32_bf16_dpp v249, v129, v15 row_newbcast:13 row_mask:0xf bank_mask:0xf
	v_mov_b32_e32 v250, v16
	v_dot2c_f32_bf16_dpp v250, v122, v8 row_newbcast:14 row_mask:0xf bank_mask:0xf
	v_dot2c_f32_bf16_dpp v250, v123, v9 row_newbcast:14 row_mask:0xf bank_mask:0xf
	v_dot2c_f32_bf16_dpp v250, v124, v10 row_newbcast:14 row_mask:0xf bank_mask:0xf
	v_dot2c_f32_bf16_dpp v250, v125, v11 row_newbcast:14 row_mask:0xf bank_mask:0xf
	v_dot2c_f32_bf16_dpp v250, v126, v12 row_newbcast:14 row_mask:0xf bank_mask:0xf
	v_dot2c_f32_bf16_dpp v250, v127, v13 row_newbcast:14 row_mask:0xf bank_mask:0xf
	v_dot2c_f32_bf16_dpp v250, v128, v14 row_newbcast:14 row_mask:0xf bank_mask:0xf
	v_dot2c_f32_bf16_dpp v250, v129, v15 row_newbcast:14 row_mask:0xf bank_mask:0xf
	v_mov_b32_e32 v251, v16
	v_dot2c_f32_bf16_dpp v251, v122, v8 row_newbcast:15 row_mask:0xf bank_mask:0xf
	v_dot2c_f32_bf16_dpp v251, v123, v9 row_newbcast:15 row_mask:0xf bank_mask:0xf
	v_dot2c_f32_bf16_dpp v251, v124, v10 row_newbcast:15 row_mask:0xf bank_mask:0xf
	v_dot2c_f32_bf16_dpp v251, v125, v11 row_newbcast:15 row_mask:0xf bank_mask:0xf
	v_dot2c_f32_bf16_dpp v251, v126, v12 row_newbcast:15 row_mask:0xf bank_mask:0xf
	v_dot2c_f32_bf16_dpp v251, v127, v13 row_newbcast:15 row_mask:0xf bank_mask:0xf
	v_dot2c_f32_bf16_dpp v251, v128, v14 row_newbcast:15 row_mask:0xf bank_mask:0xf
	v_dot2c_f32_bf16_dpp v251, v129, v15 row_newbcast:15 row_mask:0xf bank_mask:0xf
	s_nop 2
	v_mul_f32_e64 v18, |v236|, s1
	v_mul_f32_e64 v19, |v237|, s1
	v_mul_f32_e64 v20, |v238|, s1
	v_mul_f32_e64 v21, |v239|, s1
	v_mul_f32_e64 v22, |v240|, s1
	v_mul_f32_e64 v23, |v241|, s1
	v_mul_f32_e64 v24, |v242|, s1
	v_mul_f32_e64 v25, |v243|, s1
	v_mul_f32_e64 v26, |v244|, s1
	v_mul_f32_e64 v27, |v245|, s1
	v_mul_f32_e64 v28, |v246|, s1
	v_mul_f32_e64 v29, |v247|, s1
	v_mul_f32_e64 v30, |v248|, s1
	v_mul_f32_e64 v31, |v249|, s1
	v_mul_f32_e64 v32, |v250|, s1
	v_mul_f32_e64 v33, |v251|, s1
	v_exp_f32_e32 v18, v18
	v_exp_f32_e32 v19, v19
	v_exp_f32_e32 v20, v20
	v_exp_f32_e32 v21, v21
	v_exp_f32_e32 v22, v22
	v_exp_f32_e32 v23, v23
	v_exp_f32_e32 v24, v24
	v_exp_f32_e32 v25, v25
	v_exp_f32_e32 v26, v26
	v_exp_f32_e32 v27, v27
	v_exp_f32_e32 v28, v28
	v_exp_f32_e32 v29, v29
	v_exp_f32_e32 v30, v30
	v_exp_f32_e32 v31, v31
	v_exp_f32_e32 v32, v32
; __device__ __forceinline__ void gl1_item(PREF p, int l, int item, bool valid, LAS unsigned char* pl, int sw, int lane) {
;     ...
;                 gv[ss] = -(fmaxf(-z, 0.f) + __logf(1.f + __expf(-fabsf(z)))) * (1.f / 16.f);
;     ...
;                 bc += gv[ss];
	v_exp_f32_e32 v33, v33
	v_max_f32_e64 v236, -v236, -v236
	v_max_f32_e64 v237, -v237, -v237
	v_max_f32_e64 v238, -v238, -v238
	v_max_f32_e64 v239, -v239, -v239
	v_max_f32_e64 v240, -v240, -v240
	v_max_f32_e64 v241, -v241, -v241
	v_max_f32_e64 v242, -v242, -v242
	v_max_f32_e64 v243, -v243, -v243
	v_max_f32_e64 v244, -v244, -v244
	v_max_f32_e64 v245, -v245, -v245
	v_max_f32_e64 v246, -v246, -v246
	v_max_f32_e64 v247, -v247, -v247
	v_max_f32_e64 v248, -v248, -v248
	v_max_f32_e64 v249, -v249, -v249
	v_max_f32_e64 v250, -v250, -v250
	v_max_f32_e64 v251, -v251, -v251
	v_max_f32_e32 v236, 0, v236
	v_max_f32_e32 v237, 0, v237
	v_max_f32_e32 v238, 0, v238
	v_max_f32_e32 v239, 0, v239
	v_max_f32_e32 v240, 0, v240
	v_max_f32_e32 v241, 0, v241
	v_max_f32_e32 v242, 0, v242
	v_max_f32_e32 v243, 0, v243
	v_max_f32_e32 v244, 0, v244
	v_max_f32_e32 v245, 0, v245
	v_max_f32_e32 v246, 0, v246
	v_max_f32_e32 v247, 0, v247
	v_max_f32_e32 v248, 0, v248
	v_max_f32_e32 v249, 0, v249
	v_max_f32_e32 v250, 0, v250
	v_max_f32_e32 v251, 0, v251
	v_add_f32_e32 v18, 1.0, v18
	v_add_f32_e32 v19, 1.0, v19
	v_add_f32_e32 v20, 1.0, v20
	v_add_f32_e32 v21, 1.0, v21
	v_add_f32_e32 v22, 1.0, v22
	v_add_f32_e32 v23, 1.0, v23
	v_add_f32_e32 v24, 1.0, v24
	v_add_f32_e32 v25, 1.0, v25
	v_add_f32_e32 v26, 1.0, v26
	v_add_f32_e32 v27, 1.0, v27
	v_add_f32_e32 v28, 1.0, v28
	v_add_f32_e32 v29, 1.0, v29
	v_add_f32_e32 v30, 1.0, v30
	v_add_f32_e32 v31, 1.0, v31
	v_add_f32_e32 v32, 1.0, v32
	v_add_f32_e32 v33, 1.0, v33
	v_log_f32_e32 v18, v18
	v_log_f32_e32 v19, v19
	v_log_f32_e32 v20, v20
	v_log_f32_e32 v21, v21
	v_log_f32_e32 v22, v22
	v_log_f32_e32 v23, v23
	v_log_f32_e32 v24, v24
	v_log_f32_e32 v25, v25
	v_log_f32_e32 v26, v26
	v_log_f32_e32 v27, v27
	v_log_f32_e32 v28, v28
	v_log_f32_e32 v29, v29
	v_log_f32_e32 v30, v30
	v_log_f32_e32 v31, v31
	v_log_f32_e32 v32, v32
	v_log_f32_e32 v33, v33
	s_mov_b32 s45, 0x3f317217
	v_mul_f32_e32 v70, 0x3f317217, v18
	v_mul_f32_e32 v71, 0x3f317217, v19
	v_mul_f32_e32 v72, 0x3f317217, v20
	v_mul_f32_e32 v73, 0x3f317217, v21
	v_mul_f32_e32 v74, 0x3f317217, v22
	v_mul_f32_e32 v75, 0x3f317217, v23
	v_mul_f32_e32 v76, 0x3f317217, v24
	v_mul_f32_e32 v77, 0x3f317217, v25
	v_mul_f32_e32 v78, 0x3f317217, v26
	v_mul_f32_e32 v79, 0x3f317217, v27
	v_mul_f32_e32 v80, 0x3f317217, v28
	v_mul_f32_e32 v81, 0x3f317217, v29
	v_mul_f32_e32 v82, 0x3f317217, v30
	v_mul_f32_e32 v83, 0x3f317217, v31
	v_mul_f32_e32 v84, 0x3f317217, v32
	v_mul_f32_e32 v85, 0x3f317217, v33
	v_fma_f32 v70, v18, s45, -v70
	v_fma_f32 v71, v19, s45, -v71
	v_fma_f32 v72, v20, s45, -v72
	v_fma_f32 v73, v21, s45, -v73
	v_fma_f32 v74, v22, s45, -v74
	v_fma_f32 v75, v23, s45, -v75
	v_fma_f32 v76, v24, s45, -v76
	v_fma_f32 v77, v25, s45, -v77
	v_fma_f32 v78, v26, s45, -v78
	v_fma_f32 v79, v27, s45, -v79
	v_fma_f32 v80, v28, s45, -v80
	v_fma_f32 v81, v29, s45, -v81
	v_fma_f32 v82, v30, s45, -v82
	v_fma_f32 v83, v31, s45, -v83
	v_fma_f32 v84, v32, s45, -v84
	v_fma_f32 v85, v33, s45, -v85
	v_fmac_f32_e32 v70, 0x3377d1cf, v18
	v_fmac_f32_e32 v71, 0x3377d1cf, v19
	v_fmac_f32_e32 v72, 0x3377d1cf, v20
	v_fmac_f32_e32 v73, 0x3377d1cf, v21
	v_fmac_f32_e32 v74, 0x3377d1cf, v22
	v_fmac_f32_e32 v75, 0x3377d1cf, v23
	v_fmac_f32_e32 v76, 0x3377d1cf, v24
	v_fmac_f32_e32 v77, 0x3377d1cf, v25
	v_fmac_f32_e32 v78, 0x3377d1cf, v26
	v_fmac_f32_e32 v79, 0x3377d1cf, v27
	v_fmac_f32_e32 v80, 0x3377d1cf, v28
	v_fmac_f32_e32 v81, 0x3377d1cf, v29
	v_fmac_f32_e32 v82, 0x3377d1cf, v30
	v_fmac_f32_e32 v83, 0x3377d1cf, v31
	v_fmac_f32_e32 v84, 0x3377d1cf, v32
	v_fmac_f32_e32 v85, 0x3377d1cf, v33
	v_fmac_f32_e32 v70, 0x3f317217, v18
	v_fmac_f32_e32 v71, 0x3f317217, v19
	v_fmac_f32_e32 v72, 0x3f317217, v20
	v_fmac_f32_e32 v73, 0x3f317217, v21
	v_fmac_f32_e32 v74, 0x3f317217, v22
	v_fmac_f32_e32 v75, 0x3f317217, v23
	v_fmac_f32_e32 v76, 0x3f317217, v24
	v_fmac_f32_e32 v77, 0x3f317217, v25
	v_fmac_f32_e32 v78, 0x3f317217, v26
	v_fmac_f32_e32 v79, 0x3f317217, v27
	v_fmac_f32_e32 v80, 0x3f317217, v28
	v_fmac_f32_e32 v81, 0x3f317217, v29
	v_fmac_f32_e32 v82, 0x3f317217, v30
	v_fmac_f32_e32 v83, 0x3f317217, v31
	v_fmac_f32_e32 v84, 0x3f317217, v32
	v_fmac_f32_e32 v85, 0x3f317217, v33
	v_add_f32_e32 v236, v236, v70
	v_add_f32_e32 v237, v237, v71
	v_add_f32_e32 v238, v238, v72
	v_add_f32_e32 v239, v239, v73
	v_add_f32_e32 v240, v240, v74
	v_add_f32_e32 v241, v241, v75
	v_add_f32_e32 v242, v242, v76
	v_add_f32_e32 v243, v243, v77
	v_add_f32_e32 v244, v244, v78
	v_add_f32_e32 v245, v245, v79
	v_add_f32_e32 v246, v246, v80
	v_add_f32_e32 v247, v247, v81
	v_add_f32_e32 v248, v248, v82
	v_add_f32_e32 v249, v249, v83
	v_add_f32_e32 v250, v250, v84
	v_add_f32_e32 v251, v251, v85
	v_mov_b32_e32 v70, v17
	v_fmac_f32_e32 v70, 0xbd800000, v236
	v_mov_b32_e32 v71, v70
	v_fmac_f32_e32 v71, 0xbd800000, v237
	v_mov_b32_e32 v72, v71
	v_fmac_f32_e32 v72, 0xbd800000, v238
	v_mov_b32_e32 v73, v72
	v_fmac_f32_e32 v73, 0xbd800000, v239
	v_mov_b32_e32 v74, v73
	v_fmac_f32_e32 v74, 0xbd800000, v240
	v_mov_b32_e32 v75, v74
	v_fmac_f32_e32 v75, 0xbd800000, v241
	v_mov_b32_e32 v76, v75
	v_fmac_f32_e32 v76, 0xbd800000, v242
	v_mov_b32_e32 v77, v76
	v_fmac_f32_e32 v77, 0xbd800000, v243
	v_mov_b32_e32 v78, v77
	v_fmac_f32_e32 v78, 0xbd800000, v244
	v_mov_b32_e32 v79, v78
	v_fmac_f32_e32 v79, 0xbd800000, v245
	v_mov_b32_e32 v80, v79
	v_fmac_f32_e32 v80, 0xbd800000, v246
	v_mov_b32_e32 v81, v80
	v_fmac_f32_e32 v81, 0xbd800000, v247
	v_mov_b32_e32 v82, v81
	v_fmac_f32_e32 v82, 0xbd800000, v248
	v_mov_b32_e32 v83, v82
	v_fmac_f32_e32 v83, 0xbd800000, v249
	v_mov_b32_e32 v84, v83
	v_fmac_f32_e32 v84, 0xbd800000, v250
	v_mov_b32_e32 v85, v84
	v_fmac_f32_e32 v85, 0xbd800000, v251
	v_mov_b32_e32 v17, v85
	s_waitcnt vmcnt(32)
; __device__ __forceinline__ void gl1_item(PREF p, int l, int item, bool valid, LAS unsigned char* pl, int sw, int lane) {
;     ...
;                 const float en = __expf(-bc), ep = __expf(bc);
;                 const float kt = kc[ss] * en, qt = qc[ss] * 0.125f * ep;
	v_mul_f32_e32 v18, 0xbfb8aa3b, v70
	v_mul_f32_e32 v19, 0xbfb8aa3b, v71
	v_mul_f32_e32 v20, 0xbfb8aa3b, v72
	v_mul_f32_e32 v21, 0xbfb8aa3b, v73
	v_mul_f32_e32 v22, 0xbfb8aa3b, v74
	v_mul_f32_e32 v23, 0xbfb8aa3b, v75
	v_mul_f32_e32 v24, 0xbfb8aa3b, v76
	v_mul_f32_e32 v25, 0xbfb8aa3b, v77
	v_mul_f32_e32 v26, 0xbfb8aa3b, v78
	v_mul_f32_e32 v27, 0xbfb8aa3b, v79
	v_mul_f32_e32 v28, 0xbfb8aa3b, v80
	v_mul_f32_e32 v29, 0xbfb8aa3b, v81
	v_mul_f32_e32 v30, 0xbfb8aa3b, v82
	v_mul_f32_e32 v31, 0xbfb8aa3b, v83
	v_mul_f32_e32 v32, 0xbfb8aa3b, v84
	v_mul_f32_e32 v33, 0xbfb8aa3b, v85
	v_mul_f32_e32 v236, 0x3fb8aa3b, v70
	v_mul_f32_e32 v237, 0x3fb8aa3b, v71
	v_mul_f32_e32 v238, 0x3fb8aa3b, v72
	v_mul_f32_e32 v239, 0x3fb8aa3b, v73
	v_mul_f32_e32 v240, 0x3fb8aa3b, v74
	v_mul_f32_e32 v241, 0x3fb8aa3b, v75
	v_mul_f32_e32 v242, 0x3fb8aa3b, v76
	v_mul_f32_e32 v243, 0x3fb8aa3b, v77
	v_mul_f32_e32 v244, 0x3fb8aa3b, v78
	v_mul_f32_e32 v245, 0x3fb8aa3b, v79
	v_mul_f32_e32 v246, 0x3fb8aa3b, v80
	v_mul_f32_e32 v247, 0x3fb8aa3b, v81
	v_mul_f32_e32 v248, 0x3fb8aa3b, v82
	v_mul_f32_e32 v249, 0x3fb8aa3b, v83
	v_mul_f32_e32 v250, 0x3fb8aa3b, v84
	v_mul_f32_e32 v251, 0x3fb8aa3b, v85
	v_exp_f32_e32 v18, v18
	v_exp_f32_e32 v19, v19
	v_exp_f32_e32 v20, v20
	v_exp_f32_e32 v21, v21
	v_exp_f32_e32 v22, v22
	v_exp_f32_e32 v23, v23
	v_exp_f32_e32 v24, v24
	v_exp_f32_e32 v25, v25
	v_exp_f32_e32 v26, v26
	v_exp_f32_e32 v27, v27
	v_exp_f32_e32 v28, v28
	v_exp_f32_e32 v29, v29
	v_exp_f32_e32 v30, v30
	v_exp_f32_e32 v31, v31
	v_exp_f32_e32 v32, v32
	v_exp_f32_e32 v33, v33
	v_exp_f32_e32 v236, v236
	v_exp_f32_e32 v237, v237
	v_exp_f32_e32 v238, v238
	v_exp_f32_e32 v239, v239
	v_exp_f32_e32 v240, v240
	v_exp_f32_e32 v241, v241
	v_exp_f32_e32 v242, v242
	v_exp_f32_e32 v243, v243
	v_exp_f32_e32 v244, v244
	v_exp_f32_e32 v245, v245
	v_exp_f32_e32 v246, v246
	v_exp_f32_e32 v247, v247
	v_exp_f32_e32 v248, v248
	v_exp_f32_e32 v249, v249
	v_exp_f32_e32 v250, v250
	v_exp_f32_e32 v251, v251
	v_lshlrev_b32_e32 v196, 16, v196
	v_lshlrev_b32_e32 v197, 16, v197
	v_lshlrev_b32_e32 v198, 16, v198
	v_lshlrev_b32_e32 v199, 16, v199
	v_lshlrev_b32_e32 v200, 16, v200
	v_lshlrev_b32_e32 v201, 16, v201
	v_lshlrev_b32_e32 v202, 16, v202
	v_lshlrev_b32_e32 v203, 16, v203
	v_lshlrev_b32_e32 v204, 16, v204
	v_lshlrev_b32_e32 v205, 16, v205
	v_lshlrev_b32_e32 v206, 16, v206
	v_lshlrev_b32_e32 v207, 16, v207
	v_lshlrev_b32_e32 v208, 16, v208
	v_lshlrev_b32_e32 v209, 16, v209
	v_lshlrev_b32_e32 v210, 16, v210
	v_lshlrev_b32_e32 v211, 16, v211
	v_lshlrev_b32_e32 v180, 16, v180
	v_lshlrev_b32_e32 v181, 16, v181
	v_lshlrev_b32_e32 v182, 16, v182
	v_lshlrev_b32_e32 v183, 16, v183
	v_lshlrev_b32_e32 v184, 16, v184
	v_lshlrev_b32_e32 v185, 16, v185
	v_lshlrev_b32_e32 v186, 16, v186
	v_lshlrev_b32_e32 v187, 16, v187
	v_lshlrev_b32_e32 v188, 16, v188
	v_lshlrev_b32_e32 v189, 16, v189
	v_lshlrev_b32_e32 v190, 16, v190
	v_lshlrev_b32_e32 v191, 16, v191
	v_lshlrev_b32_e32 v192, 16, v192
	v_lshlrev_b32_e32 v193, 16, v193
	v_lshlrev_b32_e32 v194, 16, v194
	v_lshlrev_b32_e32 v195, 16, v195
	v_mul_f32_e32 v196, v18, v196
	v_mul_f32_e32 v197, v19, v197
	v_mul_f32_e32 v198, v20, v198
	v_mul_f32_e32 v199, v21, v199
	v_mul_f32_e32 v200, v22, v200
	v_mul_f32_e32 v201, v23, v201
	v_mul_f32_e32 v202, v24, v202
	v_mul_f32_e32 v203, v25, v203
	v_mul_f32_e32 v204, v26, v204
	v_mul_f32_e32 v205, v27, v205
	v_mul_f32_e32 v206, v28, v206
	v_mul_f32_e32 v207, v29, v207
	v_mul_f32_e32 v208, v30, v208
	v_mul_f32_e32 v209, v31, v209
	v_mul_f32_e32 v210, v32, v210
	v_mul_f32_e32 v211, v33, v211
	v_mul_f32_e32 v180, 0x3e000000, v180
	v_mul_f32_e32 v181, 0x3e000000, v181
	v_mul_f32_e32 v182, 0x3e000000, v182
	v_mul_f32_e32 v183, 0x3e000000, v183
	v_mul_f32_e32 v184, 0x3e000000, v184
	v_mul_f32_e32 v185, 0x3e000000, v185
	v_mul_f32_e32 v186, 0x3e000000, v186
	v_mul_f32_e32 v187, 0x3e000000, v187
	v_mul_f32_e32 v188, 0x3e000000, v188
	v_mul_f32_e32 v189, 0x3e000000, v189
	v_mul_f32_e32 v190, 0x3e000000, v190
	v_mul_f32_e32 v191, 0x3e000000, v191
	v_mul_f32_e32 v192, 0x3e000000, v192
	v_mul_f32_e32 v193, 0x3e000000, v193
	v_mul_f32_e32 v194, 0x3e000000, v194
	v_mul_f32_e32 v195, 0x3e000000, v195
	v_mul_f32_e32 v180, v180, v236
	v_mul_f32_e32 v181, v181, v237
	v_mul_f32_e32 v182, v182, v238
	v_mul_f32_e32 v183, v183, v239
	v_mul_f32_e32 v184, v184, v240
	v_mul_f32_e32 v185, v185, v241
	v_mul_f32_e32 v186, v186, v242
	v_mul_f32_e32 v187, v187, v243
	v_mul_f32_e32 v188, v188, v244
	v_mul_f32_e32 v189, v189, v245
	v_mul_f32_e32 v190, v190, v246
	v_mul_f32_e32 v191, v191, v247
	v_mul_f32_e32 v192, v192, v248
	v_mul_f32_e32 v193, v193, v249
	v_mul_f32_e32 v194, v194, v250
	v_mul_f32_e32 v195, v195, v251
	v_cvt_pk_bf16_f32 v196, v196, v196
	v_cvt_pk_bf16_f32 v197, v197, v197
; __device__ __forceinline__ unsigned f2bf(float f) { unsigned r; asm("v_cvt_pk_bf16_f32 %0, %1, %1" : "=v"(r) : "v"(f)); return r & 0xffffu; }
; __device__ __forceinline__ void gl1_item(PREF p, int l, int item, bool valid, LAS unsigned char* pl, int sw, int lane) {
;     ...
;                 const float kt = kc[ss] * en, qt = qc[ss] * 0.125f * ep;
;                 const unsigned ktb = f2bf(kt);
;                 sKt[lane * 72 + i] = (bf16_t)ktb;
;                 QK[rowi * 1024 + d * 512 + h * 64 + lane] = (bf16_t)f2bf(qt);
;                 QK[rowi * 1024 + d * 512 + 256 + h * 64 + lane] = (bf16_t)ktb;
;             }
; #pragma unroll
;             for (int ss = 0; ss < 16; ++ss) { qc[ss] = bf2f(__builtin_bit_cast(unsigned, qn[ss])); kc[ss] = bf2f(__builtin_bit_cast(unsigned, kn[ss])); }
;         }
;         const float Dv = __expf(bc);
;         sD[lane] = Dv; GLD[(size_t)(seq * NCH + cj) * 64 + lane] = Dv;
	v_cvt_pk_bf16_f32 v198, v198, v198
	v_cvt_pk_bf16_f32 v199, v199, v199
	v_cvt_pk_bf16_f32 v200, v200, v200
	v_cvt_pk_bf16_f32 v201, v201, v201
	v_cvt_pk_bf16_f32 v202, v202, v202
	v_cvt_pk_bf16_f32 v203, v203, v203
	v_cvt_pk_bf16_f32 v204, v204, v204
	v_cvt_pk_bf16_f32 v205, v205, v205
	v_cvt_pk_bf16_f32 v206, v206, v206
	v_cvt_pk_bf16_f32 v207, v207, v207
	v_cvt_pk_bf16_f32 v208, v208, v208
	v_cvt_pk_bf16_f32 v209, v209, v209
	v_cvt_pk_bf16_f32 v210, v210, v210
	v_cvt_pk_bf16_f32 v211, v211, v211
	v_cvt_pk_bf16_f32 v180, v180, v180
	v_cvt_pk_bf16_f32 v181, v181, v181
	v_cvt_pk_bf16_f32 v182, v182, v182
	v_cvt_pk_bf16_f32 v183, v183, v183
	v_cvt_pk_bf16_f32 v184, v184, v184
	v_cvt_pk_bf16_f32 v185, v185, v185
	v_cvt_pk_bf16_f32 v186, v186, v186
	v_cvt_pk_bf16_f32 v187, v187, v187
	v_cvt_pk_bf16_f32 v188, v188, v188
	v_cvt_pk_bf16_f32 v189, v189, v189
	v_cvt_pk_bf16_f32 v190, v190, v190
	v_cvt_pk_bf16_f32 v191, v191, v191
	v_cvt_pk_bf16_f32 v192, v192, v192
	v_cvt_pk_bf16_f32 v193, v193, v193
	v_cvt_pk_bf16_f32 v194, v194, v194
	v_cvt_pk_bf16_f32 v195, v195, v195
	ds_write_b16 v60, v196
	v_add_u32_e32 v60, v61, v60
	global_store_short v134, v180, s[4:5]
	global_store_short v134, v196, s[4:5] offset:512
	s_add_u32 s4, s4, s56
	s_addc_u32 s5, s5, s3
	ds_write_b16 v60, v197
	v_add_u32_e32 v60, v61, v60
	global_store_short v134, v181, s[4:5]
	global_store_short v134, v197, s[4:5] offset:512
	s_add_u32 s4, s4, s56
	s_addc_u32 s5, s5, s3
	ds_write_b16 v60, v198
	v_add_u32_e32 v60, v61, v60
	global_store_short v134, v182, s[4:5]
	global_store_short v134, v198, s[4:5] offset:512
	s_add_u32 s4, s4, s56
	s_addc_u32 s5, s5, s3
	ds_write_b16 v60, v199
	v_add_u32_e32 v60, v61, v60
	global_store_short v134, v183, s[4:5]
	global_store_short v134, v199, s[4:5] offset:512
	s_add_u32 s4, s4, s56
	s_addc_u32 s5, s5, s3
	ds_write_b16 v60, v200
	v_add_u32_e32 v60, v61, v60
	global_store_short v134, v184, s[4:5]
	global_store_short v134, v200, s[4:5] offset:512
	s_add_u32 s4, s4, s56
	s_addc_u32 s5, s5, s3
	ds_write_b16 v60, v201
	v_add_u32_e32 v60, v61, v60
	global_store_short v134, v185, s[4:5]
	global_store_short v134, v201, s[4:5] offset:512
	s_add_u32 s4, s4, s56
	s_addc_u32 s5, s5, s3
	ds_write_b16 v60, v202
	v_add_u32_e32 v60, v61, v60
	global_store_short v134, v186, s[4:5]
	global_store_short v134, v202, s[4:5] offset:512
	s_add_u32 s4, s4, s56
	s_addc_u32 s5, s5, s3
	ds_write_b16 v60, v203
	v_add_u32_e32 v60, v61, v60
	global_store_short v134, v187, s[4:5]
	global_store_short v134, v203, s[4:5] offset:512
	s_add_u32 s4, s4, s56
	s_addc_u32 s5, s5, s3
	ds_write_b16 v60, v204
	v_add_u32_e32 v60, v61, v60
	global_store_short v134, v188, s[4:5]
	global_store_short v134, v204, s[4:5] offset:512
	s_add_u32 s4, s4, s56
	s_addc_u32 s5, s5, s3
	ds_write_b16 v60, v205
	v_add_u32_e32 v60, v61, v60
	global_store_short v134, v189, s[4:5]
	global_store_short v134, v205, s[4:5] offset:512
	s_add_u32 s4, s4, s56
	s_addc_u32 s5, s5, s3
	ds_write_b16 v60, v206
	v_add_u32_e32 v60, v61, v60
	global_store_short v134, v190, s[4:5]
	global_store_short v134, v206, s[4:5] offset:512
	s_add_u32 s4, s4, s56
	s_addc_u32 s5, s5, s3
	ds_write_b16 v60, v207
	v_add_u32_e32 v60, v61, v60
	global_store_short v134, v191, s[4:5]
	global_store_short v134, v207, s[4:5] offset:512
	s_add_u32 s4, s4, s56
	s_addc_u32 s5, s5, s3
	ds_write_b16 v60, v208
	v_add_u32_e32 v60, v61, v60
	global_store_short v134, v192, s[4:5]
	global_store_short v134, v208, s[4:5] offset:512
	s_add_u32 s4, s4, s56
	s_addc_u32 s5, s5, s3
	ds_write_b16 v60, v209
	v_add_u32_e32 v60, v61, v60
	global_store_short v134, v193, s[4:5]
	global_store_short v134, v209, s[4:5] offset:512
	s_add_u32 s4, s4, s56
	s_addc_u32 s5, s5, s3
	ds_write_b16 v60, v210
	v_add_u32_e32 v60, v61, v60
	global_store_short v134, v194, s[4:5]
	global_store_short v134, v210, s[4:5] offset:512
	s_add_u32 s4, s4, s56
	s_addc_u32 s5, s5, s3
	ds_write_b16 v60, v211
	v_add_u32_e32 v60, v61, v60
	global_store_short v134, v195, s[4:5]
	global_store_short v134, v211, s[4:5] offset:512
	s_add_u32 s4, s4, s56
	s_addc_u32 s5, s5, s3
	v_mul_f32_e32 v18, 0x3fb8aa3b, v17
	v_exp_f32_e32 v18, v18
	v_readlane_b32 s50, v253, 55
	v_readlane_b32 s51, v253, 56
	v_readlane_b32 s45, v254, 11
	s_nop 3
	s_load_dwordx2 s[46:47], s[50:51], 0xc0
	s_and_b32 s48, s38, 1
	s_lshr_b32 s45, s45, 7
	s_mul_i32 s45, s45, 0x9200
	s_lshl_b32 s48, s48, 8
	s_add_i32 s45, s45, s48
	v_lshl_add_u32 v86, v64, 2, s45
	ds_write_b32 v86, v18 offset:36864
	s_or_b32 s45, s42, s38
	s_mulk_i32 s45, 0x104
	s_add_i32 s45, s45, s41
	s_lshl_b32 s45, s45, 8
	s_waitcnt lgkmcnt(0)
	s_add_u32 s46, s46, 0xd00000
	s_addc_u32 s47, s47, 0
	s_add_u32 s46, s46, s45
	s_addc_u32 s47, s47, 0
	global_store_dword v135, v18, s[46:47]
